# dil lean path: fully unrolled 33-group loop with immediates, 3 rotating register sets (prefetch distance 2), unit->CU permutation so boundary units spread
# speedup vs baseline: 1.0049x; 1.0049x over previous
; #define LAS __attribute__((address_space(3)))
; #define GAS __attribute__((address_space(1)))
; __device__ __forceinline__ void dil_unit(LAS unsigned char* lds, bf16_t* proj, int seq, int hd, int T0, int rho) {
;     int tid_ = threadIdx.x; asm volatile("" : "+v"(tid_));
;     const int tid = tid_, lane = tid & 63, r32 = lane & 31, hi = lane >> 5, wid = __builtin_amdgcn_readfirstlane(tid >> 6);
;     bf16_t* base = proj + (size_t)seq * SEQ * NIN;
;     LAS unsigned char* wbuf = lds + wid * 4096;
;     const LAS unsigned char* vp = wbuf + ((lane >> 4) & 1) * 32 + (lane & 3) * 8 + (4 * hi + ((lane & 15) >> 2)) * 64;
;     const int P0 = T0 + rho;
;     bf16x8 qr[4];
; #pragma unroll
;     for (int ks = 0; ks < 4; ++ks) qr[ks] = *(const GAS bf16x8*)(base + (size_t)(P0 + 16 * r32) * NIN + PC_LQ + hd * 64 + 16 * ks + 8 * hi);
;     f32x16 o0 = {}, o1 = {}; float l = 0.f;
;     const bool bound = (T0 < 1024) || (T0 >= 15360);
; __device__ __forceinline__ void attn_phase(unsigned char* ws, int l, LAS unsigned char* lds, int G) {
;     ...
;     for (int bu = vb; bu < 1152; bu += G) {
;         const int sh = bu >> 6, rem = bu & 63, T0 = (rem >> 1) * 512, rho = (rem & 1) * 8 + wid;
;         dil_unit(lds, proj, sh / 6, sh % 6, T0, rho);
.LBB0_554:
	s_lshr_b32 s82, s33, 8
	s_mul_i32 s82, s82, 13
	s_add_i32 s82, s82, s33
	s_ashr_i32 s2, s33, 6
	s_mul_hi_i32 s7, s2, 0x2aaaaaab
	s_lshl_b32 s3, s82, 8
	s_lshr_b32 s8, s7, 31
	s_and_b32 s6, s3, 0x3e00
	s_lshl_b32 s3, s82, 3
	s_add_i32 s7, s7, s8
	s_and_b32 s3, s3, 8
	s_mul_i32 s8, s7, 6
	s_add_i32 s3, s3, s64
	s_sub_i32 s8, s2, s8
	s_mul_hi_i32 s2, s7, 0x6000000
	s_mul_i32 s7, s7, 0x6000000
	v_mov_b32_e32 v2, v154
	s_add_u32 s56, s48, s7
	s_addc_u32 s57, s49, s2
	v_and_b32_e32 v105, 31, v2
	s_add_i32 s76, s3, s6
	v_lshl_add_u32 v3, v105, 4, s76
	v_mov_b64_e32 v[0:1], s[56:57]
	s_lshl_b32 s58, s8, 6
	v_bfe_u32 v106, v2, 5, 1
	v_mad_u64_u32 v[0:1], s[2:3], v3, s65, v[0:1]
	s_ashr_i32 s59, s58, 31
	v_lshl_add_u64 v[0:1], s[58:59], 1, v[0:1]
	v_lshlrev_b32_e32 v80, 4, v106
	v_lshl_add_u64 v[0:1], v[0:1], 0, v[80:81]
	global_load_dwordx4 v[48:51], v[0:1], off offset:1280
	global_load_dwordx4 v[52:55], v[0:1], off offset:1312
	global_load_dwordx4 v[56:59], v[0:1], off offset:1344
	global_load_dwordx4 v[60:63], v[0:1], off offset:1376
	v_readfirstlane_b32 s2, v2
	s_lshl_b32 s2, s2, 6
	s_and_b32 s2, s2, 0xfffff000
	v_lshlrev_b32_e32 v0, 1, v2
	v_lshlrev_b32_e32 v104, 3, v2
	v_lshlrev_b32_e32 v107, 2, v106
	v_lshrrev_b32_e32 v1, 2, v2
	v_and_b32_e32 v103, 63, v2
	v_and_b32_e32 v0, 32, v0
	v_and_b32_e32 v98, 24, v104
	v_and_or_b32 v1, v1, 3, v107
	s_add_i32 s77, s2, 0
	v_lshlrev_b32_e32 v108, 6, v1
	v_lshlrev_b32_e32 v1, 3, v106
	v_add3_u32 v109, s77, v0, v98
	s_addk_i32 s6, 0xc400
	v_lshrrev_b32_e32 v110, 2, v103
	v_lshlrev_b32_e32 v0, 4, v103
	s_mov_b64 s[2:3], -1
	s_cmp_gt_u32 s6, 0xffffc7ff
	v_lshlrev_b32_e32 v100, 1, v98
	s_mul_i32 s6, s8, 0x1c00
	v_lshlrev_b32_e32 v82, 1, v1
	v_or_b32_e32 v111, 16, v110
	v_add_u32_e32 v112, s77, v0
	s_cbranch_scc0 .LBB0_558
	s_movk_i32 s100, 0x1800
	s_add_i32 s101, s6, 0x15c00
	s_lshl_b32 s90, s58, 1
	s_add_u32 s82, s56, s90
	s_addc_u32 s83, s57, 0
	s_add_u32 s82, s82, 0x1200
	s_addc_u32 s83, s83, 0
	s_sub_i32 s90, s76, 64
	s_mul_i32 s90, s90, 0x1800
	s_add_u32 s84, s82, s90
	s_addc_u32 s85, s83, 0
	s_sub_i32 s90, s76, 256
	s_mul_i32 s90, s90, 0x1800
	s_add_u32 s86, s82, s90
	s_addc_u32 s87, s83, 0
	s_sub_i32 s90, s76, 1024
	s_mul_i32 s90, s90, 0x1800
	s_add_u32 s88, s82, s90
	s_addc_u32 s89, s83, 0
	v_lshlrev_b32_e32 v153, 1, v98
	v_mad_u32_u24 v80, v105, s100, v82
	v_mad_u32_u24 v100, v110, s100, v153
	v_add_u32_e32 v149, 0x18000, v100
	v_lshlrev_b32_e32 v83, 2, v105
	v_mad_u32_u24 v83, v83, s100, v82
	v_lshlrev_b32_e32 v101, 2, v110
	v_mad_u32_u24 v101, v101, s100, v153
	v_add_u32_e32 v150, 0x60000, v101
	v_lshlrev_b32_e32 v99, 4, v105
	v_mad_u32_u24 v99, v99, s100, v82
	v_lshlrev_b32_e32 v148, 4, v110
	v_mad_u32_u24 v148, v148, s100, v153
	v_add_u32_e32 v151, 0x180000, v148
	v_lshlrev_b32_e32 v228, 4, v105
	v_sub_u32_e32 v228, v107, v228
	s_add_i32 s90, s101, 1984
	v_lshl_add_u32 v228, v228, 2, s90
	v_lshlrev_b32_e32 v229, 2, v105
	v_sub_u32_e32 v229, v107, v229
	s_add_i32 s90, s101, 5104
	v_lshl_add_u32 v229, v229, 2, s90
	v_sub_u32_e32 v230, v107, v105
	s_add_i32 s90, s101, 6364
	v_lshl_add_u32 v230, v230, 2, s90
	v_add_u32_e32 v231, v109, v108
	v_mov_b64_e32 v[232:233], 0
	v_mov_b64_e32 v[0:1], 0
	v_mov_b64_e32 v[2:3], 0
	v_mov_b64_e32 v[4:5], 0
	v_mov_b64_e32 v[6:7], 0
	v_mov_b64_e32 v[8:9], 0
	v_mov_b64_e32 v[10:11], 0
	v_mov_b64_e32 v[12:13], 0
	v_mov_b64_e32 v[14:15], 0
	v_mov_b64_e32 v[16:17], 0
	v_mov_b64_e32 v[18:19], 0
	v_mov_b64_e32 v[20:21], 0
	v_mov_b64_e32 v[22:23], 0
	v_mov_b64_e32 v[24:25], 0
	v_mov_b64_e32 v[26:27], 0
	v_mov_b64_e32 v[28:29], 0
	v_mov_b64_e32 v[30:31], 0
	global_load_dwordx4 v[116:119], v80, s[84:85]
	global_load_dwordx4 v[120:123], v80, s[84:85] offset:32
	global_load_dwordx4 v[124:127], v80, s[84:85] offset:64
	global_load_dwordx4 v[128:131], v80, s[84:85] offset:96
	global_load_dwordx4 v[132:135], v100, s[84:85] offset:768
	global_load_dwordx4 v[136:139], v149, s[84:85] offset:768
	global_load_dwordx4 v[140:143], v100, s[84:85] offset:832
	global_load_dwordx4 v[144:147], v149, s[84:85] offset:832
	s_add_u32 s84, s84, 0x30000
	s_addc_u32 s85, s85, 0
	global_load_dwordx4 v[156:159], v80, s[84:85]
	global_load_dwordx4 v[160:163], v80, s[84:85] offset:32
	global_load_dwordx4 v[164:167], v80, s[84:85] offset:64
	global_load_dwordx4 v[168:171], v80, s[84:85] offset:96
	global_load_dwordx4 v[172:175], v100, s[84:85] offset:768
	global_load_dwordx4 v[176:179], v149, s[84:85] offset:768
	global_load_dwordx4 v[180:183], v100, s[84:85] offset:832
	global_load_dwordx4 v[184:187], v149, s[84:85] offset:832
	s_add_u32 s84, s84, 0x30000
	s_addc_u32 s85, s85, 0
	global_load_dwordx4 v[188:191], v80, s[84:85]
	global_load_dwordx4 v[192:195], v80, s[84:85] offset:32
	global_load_dwordx4 v[196:199], v80, s[84:85] offset:64
	global_load_dwordx4 v[200:203], v80, s[84:85] offset:96
	global_load_dwordx4 v[204:207], v100, s[84:85] offset:768
	global_load_dwordx4 v[208:211], v149, s[84:85] offset:768
	global_load_dwordx4 v[212:215], v100, s[84:85] offset:832
	global_load_dwordx4 v[216:219], v149, s[84:85] offset:832
	s_add_u32 s84, s84, 0x30000
	s_addc_u32 s85, s85, 0
	s_waitcnt vmcnt(16)
	ds_write_b128 v112, v[132:135]
	ds_write_b128 v112, v[136:139] offset:1024
	ds_write_b128 v112, v[140:143] offset:2048
	ds_write_b128 v112, v[144:147] offset:3072
	v_mov_b32_e32 v115, v228
	ds_read2_b32 v[32:33], v115 offset0:0 offset1:1
	ds_read2_b32 v[34:35], v115 offset0:2 offset1:3
	ds_read2_b32 v[36:37], v115 offset0:8 offset1:9
	ds_read2_b32 v[38:39], v115 offset0:10 offset1:11
	ds_read2_b32 v[40:41], v115 offset0:16 offset1:17
	ds_read2_b32 v[42:43], v115 offset0:18 offset1:19
	ds_read2_b32 v[44:45], v115 offset0:24 offset1:25
	ds_read2_b32 v[46:47], v115 offset0:26 offset1:27
	s_waitcnt lgkmcnt(0)
	v_mfma_f32_32x32x16_bf16 v[32:47], v[116:119], v[48:51], v[32:47]
	ds_read_b64_tr_b16 v[72:73], v231
	ds_read_b64_tr_b16 v[74:75], v231 offset:512
	ds_read_b64_tr_b16 v[76:77], v231 offset:2048
	ds_read_b64_tr_b16 v[78:79], v231 offset:2560
	ds_read_b64_tr_b16 v[220:221], v231 offset:1024
	ds_read_b64_tr_b16 v[222:223], v231 offset:1536
	ds_read_b64_tr_b16 v[224:225], v231 offset:3072
	ds_read_b64_tr_b16 v[226:227], v231 offset:3584
	v_mfma_f32_32x32x16_bf16 v[32:47], v[120:123], v[52:55], v[32:47]
	v_mfma_f32_32x32x16_bf16 v[32:47], v[124:127], v[56:59], v[32:47]
	v_mfma_f32_32x32x16_bf16 v[32:47], v[128:131], v[60:63], v[32:47]
	s_nop 11
	v_exp_f32_e32 v32, v32
	v_exp_f32_e32 v33, v33
	v_exp_f32_e32 v34, v34
	v_exp_f32_e32 v35, v35
	v_exp_f32_e32 v36, v36
	v_exp_f32_e32 v37, v37
	v_exp_f32_e32 v38, v38
	v_exp_f32_e32 v39, v39
	v_exp_f32_e32 v40, v40
	v_exp_f32_e32 v41, v41
	v_exp_f32_e32 v42, v42
	v_exp_f32_e32 v43, v43
	v_exp_f32_e32 v44, v44
	v_exp_f32_e32 v45, v45
	v_exp_f32_e32 v46, v46
	v_exp_f32_e32 v47, v47
	v_cvt_pk_bf16_f32 v64, v32, v33
	v_cvt_pk_bf16_f32 v65, v34, v35
	v_cvt_pk_bf16_f32 v66, v36, v37
	v_cvt_pk_bf16_f32 v67, v38, v39
	v_cvt_pk_bf16_f32 v68, v40, v41
	v_cvt_pk_bf16_f32 v69, v42, v43
	v_cvt_pk_bf16_f32 v70, v44, v45
	v_cvt_pk_bf16_f32 v71, v46, v47
	v_pk_add_f32 v[232:233], v[232:233], v[32:33]
	v_pk_add_f32 v[232:233], v[232:233], v[34:35]
	v_pk_add_f32 v[232:233], v[232:233], v[36:37]
	v_pk_add_f32 v[232:233], v[232:233], v[38:39]
	v_pk_add_f32 v[232:233], v[232:233], v[40:41]
	v_pk_add_f32 v[232:233], v[232:233], v[42:43]
	v_pk_add_f32 v[232:233], v[232:233], v[44:45]
	v_pk_add_f32 v[232:233], v[232:233], v[46:47]
	s_waitcnt lgkmcnt(0)
	v_mfma_f32_32x32x16_bf16 v[0:15], v[64:67], v[72:75], v[0:15]
	v_mfma_f32_32x32x16_bf16 v[16:31], v[64:67], v[76:79], v[16:31]
	v_mfma_f32_32x32x16_bf16 v[0:15], v[68:71], v[220:223], v[0:15]
	v_mfma_f32_32x32x16_bf16 v[16:31], v[68:71], v[224:227], v[16:31]
	global_load_dwordx4 v[116:119], v80, s[84:85]
	global_load_dwordx4 v[120:123], v80, s[84:85] offset:32
	global_load_dwordx4 v[124:127], v80, s[84:85] offset:64
	global_load_dwordx4 v[128:131], v80, s[84:85] offset:96
	global_load_dwordx4 v[132:135], v100, s[84:85] offset:768
	global_load_dwordx4 v[136:139], v149, s[84:85] offset:768
	global_load_dwordx4 v[140:143], v100, s[84:85] offset:832
	global_load_dwordx4 v[144:147], v149, s[84:85] offset:832
	s_add_u32 s84, s84, 0x30000
	s_addc_u32 s85, s85, 0
	s_waitcnt vmcnt(16)
	ds_write_b128 v112, v[172:175]
	ds_write_b128 v112, v[176:179] offset:1024
	ds_write_b128 v112, v[180:183] offset:2048
	ds_write_b128 v112, v[184:187] offset:3072
	ds_read2_b32 v[32:33], v115 offset0:32 offset1:33
	ds_read2_b32 v[34:35], v115 offset0:34 offset1:35
	ds_read2_b32 v[36:37], v115 offset0:40 offset1:41
	ds_read2_b32 v[38:39], v115 offset0:42 offset1:43
	ds_read2_b32 v[40:41], v115 offset0:48 offset1:49
	ds_read2_b32 v[42:43], v115 offset0:50 offset1:51
	ds_read2_b32 v[44:45], v115 offset0:56 offset1:57
	ds_read2_b32 v[46:47], v115 offset0:58 offset1:59
	s_waitcnt lgkmcnt(0)
	v_mfma_f32_32x32x16_bf16 v[32:47], v[156:159], v[48:51], v[32:47]
	ds_read_b64_tr_b16 v[72:73], v231
	ds_read_b64_tr_b16 v[74:75], v231 offset:512
	ds_read_b64_tr_b16 v[76:77], v231 offset:2048
	ds_read_b64_tr_b16 v[78:79], v231 offset:2560
	ds_read_b64_tr_b16 v[220:221], v231 offset:1024
	ds_read_b64_tr_b16 v[222:223], v231 offset:1536
	ds_read_b64_tr_b16 v[224:225], v231 offset:3072
	ds_read_b64_tr_b16 v[226:227], v231 offset:3584
	v_mfma_f32_32x32x16_bf16 v[32:47], v[160:163], v[52:55], v[32:47]
	v_mfma_f32_32x32x16_bf16 v[32:47], v[164:167], v[56:59], v[32:47]
	v_mfma_f32_32x32x16_bf16 v[32:47], v[168:171], v[60:63], v[32:47]
	s_nop 11
	v_exp_f32_e32 v32, v32
	v_exp_f32_e32 v33, v33
	v_exp_f32_e32 v34, v34
	v_exp_f32_e32 v35, v35
	v_exp_f32_e32 v36, v36
	v_exp_f32_e32 v37, v37
	v_exp_f32_e32 v38, v38
	v_exp_f32_e32 v39, v39
	v_exp_f32_e32 v40, v40
	v_exp_f32_e32 v41, v41
	v_exp_f32_e32 v42, v42
	v_exp_f32_e32 v43, v43
	v_exp_f32_e32 v44, v44
	v_exp_f32_e32 v45, v45
	v_exp_f32_e32 v46, v46
	v_exp_f32_e32 v47, v47
	v_cvt_pk_bf16_f32 v64, v32, v33
	v_cvt_pk_bf16_f32 v65, v34, v35
	v_cvt_pk_bf16_f32 v66, v36, v37
	v_cvt_pk_bf16_f32 v67, v38, v39
	v_cvt_pk_bf16_f32 v68, v40, v41
	v_cvt_pk_bf16_f32 v69, v42, v43
	v_cvt_pk_bf16_f32 v70, v44, v45
	v_cvt_pk_bf16_f32 v71, v46, v47
	v_pk_add_f32 v[232:233], v[232:233], v[32:33]
	v_pk_add_f32 v[232:233], v[232:233], v[34:35]
	v_pk_add_f32 v[232:233], v[232:233], v[36:37]
	v_pk_add_f32 v[232:233], v[232:233], v[38:39]
	v_pk_add_f32 v[232:233], v[232:233], v[40:41]
	v_pk_add_f32 v[232:233], v[232:233], v[42:43]
	v_pk_add_f32 v[232:233], v[232:233], v[44:45]
	v_pk_add_f32 v[232:233], v[232:233], v[46:47]
	s_waitcnt lgkmcnt(0)
	v_mfma_f32_32x32x16_bf16 v[0:15], v[64:67], v[72:75], v[0:15]
	v_mfma_f32_32x32x16_bf16 v[16:31], v[64:67], v[76:79], v[16:31]
	v_mfma_f32_32x32x16_bf16 v[0:15], v[68:71], v[220:223], v[0:15]
	v_mfma_f32_32x32x16_bf16 v[16:31], v[68:71], v[224:227], v[16:31]
	global_load_dwordx4 v[156:159], v80, s[84:85]
	global_load_dwordx4 v[160:163], v80, s[84:85] offset:32
	global_load_dwordx4 v[164:167], v80, s[84:85] offset:64
	global_load_dwordx4 v[168:171], v80, s[84:85] offset:96
	global_load_dwordx4 v[172:175], v100, s[84:85] offset:768
	global_load_dwordx4 v[176:179], v149, s[84:85] offset:768
	global_load_dwordx4 v[180:183], v100, s[84:85] offset:832
	global_load_dwordx4 v[184:187], v149, s[84:85] offset:832
	s_add_u32 s84, s84, 0x30000
	s_addc_u32 s85, s85, 0
	s_waitcnt vmcnt(16)
	ds_write_b128 v112, v[204:207]
	ds_write_b128 v112, v[208:211] offset:1024
	ds_write_b128 v112, v[212:215] offset:2048
	ds_write_b128 v112, v[216:219] offset:3072
	ds_read2_b32 v[32:33], v115 offset0:64 offset1:65
	ds_read2_b32 v[34:35], v115 offset0:66 offset1:67
	ds_read2_b32 v[36:37], v115 offset0:72 offset1:73
	ds_read2_b32 v[38:39], v115 offset0:74 offset1:75
	ds_read2_b32 v[40:41], v115 offset0:80 offset1:81
	ds_read2_b32 v[42:43], v115 offset0:82 offset1:83
	ds_read2_b32 v[44:45], v115 offset0:88 offset1:89
	ds_read2_b32 v[46:47], v115 offset0:90 offset1:91
	s_waitcnt lgkmcnt(0)
	v_mfma_f32_32x32x16_bf16 v[32:47], v[188:191], v[48:51], v[32:47]
	ds_read_b64_tr_b16 v[72:73], v231
	ds_read_b64_tr_b16 v[74:75], v231 offset:512
	ds_read_b64_tr_b16 v[76:77], v231 offset:2048
	ds_read_b64_tr_b16 v[78:79], v231 offset:2560
	ds_read_b64_tr_b16 v[220:221], v231 offset:1024
	ds_read_b64_tr_b16 v[222:223], v231 offset:1536
	ds_read_b64_tr_b16 v[224:225], v231 offset:3072
	ds_read_b64_tr_b16 v[226:227], v231 offset:3584
	v_mfma_f32_32x32x16_bf16 v[32:47], v[192:195], v[52:55], v[32:47]
	v_mfma_f32_32x32x16_bf16 v[32:47], v[196:199], v[56:59], v[32:47]
	v_mfma_f32_32x32x16_bf16 v[32:47], v[200:203], v[60:63], v[32:47]
	s_nop 11
	v_exp_f32_e32 v32, v32
	v_exp_f32_e32 v33, v33
	v_exp_f32_e32 v34, v34
	v_exp_f32_e32 v35, v35
	v_exp_f32_e32 v36, v36
	v_exp_f32_e32 v37, v37
	v_exp_f32_e32 v38, v38
	v_exp_f32_e32 v39, v39
	v_exp_f32_e32 v40, v40
	v_exp_f32_e32 v41, v41
	v_exp_f32_e32 v42, v42
	v_exp_f32_e32 v43, v43
	v_exp_f32_e32 v44, v44
	v_exp_f32_e32 v45, v45
	v_exp_f32_e32 v46, v46
	v_exp_f32_e32 v47, v47
	v_cvt_pk_bf16_f32 v64, v32, v33
	v_cvt_pk_bf16_f32 v65, v34, v35
	v_cvt_pk_bf16_f32 v66, v36, v37
	v_cvt_pk_bf16_f32 v67, v38, v39
	v_cvt_pk_bf16_f32 v68, v40, v41
	v_cvt_pk_bf16_f32 v69, v42, v43
	v_cvt_pk_bf16_f32 v70, v44, v45
	v_cvt_pk_bf16_f32 v71, v46, v47
	v_pk_add_f32 v[232:233], v[232:233], v[32:33]
	v_pk_add_f32 v[232:233], v[232:233], v[34:35]
	v_pk_add_f32 v[232:233], v[232:233], v[36:37]
	v_pk_add_f32 v[232:233], v[232:233], v[38:39]
	v_pk_add_f32 v[232:233], v[232:233], v[40:41]
	v_pk_add_f32 v[232:233], v[232:233], v[42:43]
	v_pk_add_f32 v[232:233], v[232:233], v[44:45]
	v_pk_add_f32 v[232:233], v[232:233], v[46:47]
	s_waitcnt lgkmcnt(0)
	v_mfma_f32_32x32x16_bf16 v[0:15], v[64:67], v[72:75], v[0:15]
	v_mfma_f32_32x32x16_bf16 v[16:31], v[64:67], v[76:79], v[16:31]
	v_mfma_f32_32x32x16_bf16 v[0:15], v[68:71], v[220:223], v[0:15]
	v_mfma_f32_32x32x16_bf16 v[16:31], v[68:71], v[224:227], v[16:31]
	global_load_dwordx4 v[188:191], v80, s[84:85]
	global_load_dwordx4 v[192:195], v80, s[84:85] offset:32
	global_load_dwordx4 v[196:199], v80, s[84:85] offset:64
	global_load_dwordx4 v[200:203], v80, s[84:85] offset:96
	global_load_dwordx4 v[204:207], v100, s[84:85] offset:768
	global_load_dwordx4 v[208:211], v149, s[84:85] offset:768
	global_load_dwordx4 v[212:215], v100, s[84:85] offset:832
	global_load_dwordx4 v[216:219], v149, s[84:85] offset:832
	s_add_u32 s84, s84, 0x30000
	s_addc_u32 s85, s85, 0
	s_waitcnt vmcnt(16)
	ds_write_b128 v112, v[132:135]
	ds_write_b128 v112, v[136:139] offset:1024
	ds_write_b128 v112, v[140:143] offset:2048
	ds_write_b128 v112, v[144:147] offset:3072
	ds_read2_b32 v[32:33], v115 offset0:96 offset1:97
	ds_read2_b32 v[34:35], v115 offset0:98 offset1:99
	ds_read2_b32 v[36:37], v115 offset0:104 offset1:105
	ds_read2_b32 v[38:39], v115 offset0:106 offset1:107
	ds_read2_b32 v[40:41], v115 offset0:112 offset1:113
	ds_read2_b32 v[42:43], v115 offset0:114 offset1:115
	ds_read2_b32 v[44:45], v115 offset0:120 offset1:121
	ds_read2_b32 v[46:47], v115 offset0:122 offset1:123
	s_waitcnt lgkmcnt(0)
	v_mfma_f32_32x32x16_bf16 v[32:47], v[116:119], v[48:51], v[32:47]
	ds_read_b64_tr_b16 v[72:73], v231
	ds_read_b64_tr_b16 v[74:75], v231 offset:512
	ds_read_b64_tr_b16 v[76:77], v231 offset:2048
	ds_read_b64_tr_b16 v[78:79], v231 offset:2560
	ds_read_b64_tr_b16 v[220:221], v231 offset:1024
	ds_read_b64_tr_b16 v[222:223], v231 offset:1536
	ds_read_b64_tr_b16 v[224:225], v231 offset:3072
	ds_read_b64_tr_b16 v[226:227], v231 offset:3584
	v_mfma_f32_32x32x16_bf16 v[32:47], v[120:123], v[52:55], v[32:47]
	v_mfma_f32_32x32x16_bf16 v[32:47], v[124:127], v[56:59], v[32:47]
	v_mfma_f32_32x32x16_bf16 v[32:47], v[128:131], v[60:63], v[32:47]
	s_nop 11
	v_exp_f32_e32 v32, v32
	v_exp_f32_e32 v33, v33
	v_exp_f32_e32 v34, v34
	v_exp_f32_e32 v35, v35
	v_exp_f32_e32 v36, v36
	v_exp_f32_e32 v37, v37
	v_exp_f32_e32 v38, v38
	v_exp_f32_e32 v39, v39
	v_exp_f32_e32 v40, v40
	v_exp_f32_e32 v41, v41
	v_exp_f32_e32 v42, v42
	v_exp_f32_e32 v43, v43
	v_exp_f32_e32 v44, v44
	v_exp_f32_e32 v45, v45
	v_exp_f32_e32 v46, v46
	v_exp_f32_e32 v47, v47
	v_cvt_pk_bf16_f32 v64, v32, v33
	v_cvt_pk_bf16_f32 v65, v34, v35
	v_cvt_pk_bf16_f32 v66, v36, v37
	v_cvt_pk_bf16_f32 v67, v38, v39
	v_cvt_pk_bf16_f32 v68, v40, v41
	v_cvt_pk_bf16_f32 v69, v42, v43
	v_cvt_pk_bf16_f32 v70, v44, v45
	v_cvt_pk_bf16_f32 v71, v46, v47
	v_pk_add_f32 v[232:233], v[232:233], v[32:33]
	v_pk_add_f32 v[232:233], v[232:233], v[34:35]
	v_pk_add_f32 v[232:233], v[232:233], v[36:37]
	v_pk_add_f32 v[232:233], v[232:233], v[38:39]
	v_pk_add_f32 v[232:233], v[232:233], v[40:41]
	v_pk_add_f32 v[232:233], v[232:233], v[42:43]
	v_pk_add_f32 v[232:233], v[232:233], v[44:45]
	v_pk_add_f32 v[232:233], v[232:233], v[46:47]
	s_waitcnt lgkmcnt(0)
	v_mfma_f32_32x32x16_bf16 v[0:15], v[64:67], v[72:75], v[0:15]
	v_mfma_f32_32x32x16_bf16 v[16:31], v[64:67], v[76:79], v[16:31]
	v_mfma_f32_32x32x16_bf16 v[0:15], v[68:71], v[220:223], v[0:15]
	v_mfma_f32_32x32x16_bf16 v[16:31], v[68:71], v[224:227], v[16:31]
	global_load_dwordx4 v[116:119], v80, s[84:85]
	global_load_dwordx4 v[120:123], v80, s[84:85] offset:32
	global_load_dwordx4 v[124:127], v80, s[84:85] offset:64
	global_load_dwordx4 v[128:131], v80, s[84:85] offset:96
	global_load_dwordx4 v[132:135], v100, s[84:85] offset:768
	global_load_dwordx4 v[136:139], v149, s[84:85] offset:768
	global_load_dwordx4 v[140:143], v100, s[84:85] offset:832
	global_load_dwordx4 v[144:147], v149, s[84:85] offset:832
	s_add_u32 s84, s84, 0x30000
	s_addc_u32 s85, s85, 0
	s_waitcnt vmcnt(16)
	ds_write_b128 v112, v[172:175]
	ds_write_b128 v112, v[176:179] offset:1024
	ds_write_b128 v112, v[180:183] offset:2048
	ds_write_b128 v112, v[184:187] offset:3072
	ds_read2_b32 v[32:33], v115 offset0:128 offset1:129
	ds_read2_b32 v[34:35], v115 offset0:130 offset1:131
	ds_read2_b32 v[36:37], v115 offset0:136 offset1:137
	ds_read2_b32 v[38:39], v115 offset0:138 offset1:139
	ds_read2_b32 v[40:41], v115 offset0:144 offset1:145
	ds_read2_b32 v[42:43], v115 offset0:146 offset1:147
	ds_read2_b32 v[44:45], v115 offset0:152 offset1:153
	ds_read2_b32 v[46:47], v115 offset0:154 offset1:155
	s_waitcnt lgkmcnt(0)
	v_mfma_f32_32x32x16_bf16 v[32:47], v[156:159], v[48:51], v[32:47]
	ds_read_b64_tr_b16 v[72:73], v231
	ds_read_b64_tr_b16 v[74:75], v231 offset:512
	ds_read_b64_tr_b16 v[76:77], v231 offset:2048
	ds_read_b64_tr_b16 v[78:79], v231 offset:2560
	ds_read_b64_tr_b16 v[220:221], v231 offset:1024
	ds_read_b64_tr_b16 v[222:223], v231 offset:1536
	ds_read_b64_tr_b16 v[224:225], v231 offset:3072
	ds_read_b64_tr_b16 v[226:227], v231 offset:3584
	v_mfma_f32_32x32x16_bf16 v[32:47], v[160:163], v[52:55], v[32:47]
	v_mfma_f32_32x32x16_bf16 v[32:47], v[164:167], v[56:59], v[32:47]
	v_mfma_f32_32x32x16_bf16 v[32:47], v[168:171], v[60:63], v[32:47]
	s_nop 11
	v_exp_f32_e32 v32, v32
	v_exp_f32_e32 v33, v33
	v_exp_f32_e32 v34, v34
	v_exp_f32_e32 v35, v35
	v_exp_f32_e32 v36, v36
	v_exp_f32_e32 v37, v37
	v_exp_f32_e32 v38, v38
	v_exp_f32_e32 v39, v39
	v_exp_f32_e32 v40, v40
	v_exp_f32_e32 v41, v41
	v_exp_f32_e32 v42, v42
	v_exp_f32_e32 v43, v43
	v_exp_f32_e32 v44, v44
	v_exp_f32_e32 v45, v45
	v_exp_f32_e32 v46, v46
	v_exp_f32_e32 v47, v47
	v_cvt_pk_bf16_f32 v64, v32, v33
	v_cvt_pk_bf16_f32 v65, v34, v35
	v_cvt_pk_bf16_f32 v66, v36, v37
	v_cvt_pk_bf16_f32 v67, v38, v39
	v_cvt_pk_bf16_f32 v68, v40, v41
	v_cvt_pk_bf16_f32 v69, v42, v43
	v_cvt_pk_bf16_f32 v70, v44, v45
	v_cvt_pk_bf16_f32 v71, v46, v47
	v_pk_add_f32 v[232:233], v[232:233], v[32:33]
	v_pk_add_f32 v[232:233], v[232:233], v[34:35]
	v_pk_add_f32 v[232:233], v[232:233], v[36:37]
	v_pk_add_f32 v[232:233], v[232:233], v[38:39]
	v_pk_add_f32 v[232:233], v[232:233], v[40:41]
	v_pk_add_f32 v[232:233], v[232:233], v[42:43]
	v_pk_add_f32 v[232:233], v[232:233], v[44:45]
	v_pk_add_f32 v[232:233], v[232:233], v[46:47]
	s_waitcnt lgkmcnt(0)
	v_mfma_f32_32x32x16_bf16 v[0:15], v[64:67], v[72:75], v[0:15]
	v_mfma_f32_32x32x16_bf16 v[16:31], v[64:67], v[76:79], v[16:31]
	v_mfma_f32_32x32x16_bf16 v[0:15], v[68:71], v[220:223], v[0:15]
	v_mfma_f32_32x32x16_bf16 v[16:31], v[68:71], v[224:227], v[16:31]
	global_load_dwordx4 v[156:159], v80, s[84:85]
	global_load_dwordx4 v[160:163], v80, s[84:85] offset:32
	global_load_dwordx4 v[164:167], v80, s[84:85] offset:64
	global_load_dwordx4 v[168:171], v80, s[84:85] offset:96
	global_load_dwordx4 v[172:175], v100, s[84:85] offset:768
	global_load_dwordx4 v[176:179], v149, s[84:85] offset:768
	global_load_dwordx4 v[180:183], v100, s[84:85] offset:832
	global_load_dwordx4 v[184:187], v149, s[84:85] offset:832
	s_add_u32 s84, s84, 0x30000
	s_addc_u32 s85, s85, 0
	s_waitcnt vmcnt(16)
	ds_write_b128 v112, v[204:207]
	ds_write_b128 v112, v[208:211] offset:1024
	ds_write_b128 v112, v[212:215] offset:2048
	ds_write_b128 v112, v[216:219] offset:3072
	ds_read2_b32 v[32:33], v115 offset0:160 offset1:161
	ds_read2_b32 v[34:35], v115 offset0:162 offset1:163
	ds_read2_b32 v[36:37], v115 offset0:168 offset1:169
	ds_read2_b32 v[38:39], v115 offset0:170 offset1:171
	ds_read2_b32 v[40:41], v115 offset0:176 offset1:177
	ds_read2_b32 v[42:43], v115 offset0:178 offset1:179
	ds_read2_b32 v[44:45], v115 offset0:184 offset1:185
	ds_read2_b32 v[46:47], v115 offset0:186 offset1:187
	s_waitcnt lgkmcnt(0)
	v_mfma_f32_32x32x16_bf16 v[32:47], v[188:191], v[48:51], v[32:47]
	ds_read_b64_tr_b16 v[72:73], v231
	ds_read_b64_tr_b16 v[74:75], v231 offset:512
	ds_read_b64_tr_b16 v[76:77], v231 offset:2048
	ds_read_b64_tr_b16 v[78:79], v231 offset:2560
	ds_read_b64_tr_b16 v[220:221], v231 offset:1024
	ds_read_b64_tr_b16 v[222:223], v231 offset:1536
	ds_read_b64_tr_b16 v[224:225], v231 offset:3072
	ds_read_b64_tr_b16 v[226:227], v231 offset:3584
	v_mfma_f32_32x32x16_bf16 v[32:47], v[192:195], v[52:55], v[32:47]
	v_mfma_f32_32x32x16_bf16 v[32:47], v[196:199], v[56:59], v[32:47]
	v_mfma_f32_32x32x16_bf16 v[32:47], v[200:203], v[60:63], v[32:47]
	s_nop 11
	v_exp_f32_e32 v32, v32
	v_exp_f32_e32 v33, v33
	v_exp_f32_e32 v34, v34
	v_exp_f32_e32 v35, v35
	v_exp_f32_e32 v36, v36
	v_exp_f32_e32 v37, v37
	v_exp_f32_e32 v38, v38
	v_exp_f32_e32 v39, v39
	v_exp_f32_e32 v40, v40
	v_exp_f32_e32 v41, v41
	v_exp_f32_e32 v42, v42
	v_exp_f32_e32 v43, v43
	v_exp_f32_e32 v44, v44
	v_exp_f32_e32 v45, v45
	v_exp_f32_e32 v46, v46
	v_exp_f32_e32 v47, v47
	v_cvt_pk_bf16_f32 v64, v32, v33
	v_cvt_pk_bf16_f32 v65, v34, v35
	v_cvt_pk_bf16_f32 v66, v36, v37
	v_cvt_pk_bf16_f32 v67, v38, v39
	v_cvt_pk_bf16_f32 v68, v40, v41
	v_cvt_pk_bf16_f32 v69, v42, v43
	v_cvt_pk_bf16_f32 v70, v44, v45
	v_cvt_pk_bf16_f32 v71, v46, v47
	v_pk_add_f32 v[232:233], v[232:233], v[32:33]
	v_pk_add_f32 v[232:233], v[232:233], v[34:35]
	v_pk_add_f32 v[232:233], v[232:233], v[36:37]
	v_pk_add_f32 v[232:233], v[232:233], v[38:39]
	v_pk_add_f32 v[232:233], v[232:233], v[40:41]
	v_pk_add_f32 v[232:233], v[232:233], v[42:43]
	v_pk_add_f32 v[232:233], v[232:233], v[44:45]
	v_pk_add_f32 v[232:233], v[232:233], v[46:47]
	s_waitcnt lgkmcnt(0)
	v_mfma_f32_32x32x16_bf16 v[0:15], v[64:67], v[72:75], v[0:15]
	v_mfma_f32_32x32x16_bf16 v[16:31], v[64:67], v[76:79], v[16:31]
	v_mfma_f32_32x32x16_bf16 v[0:15], v[68:71], v[220:223], v[0:15]
	v_mfma_f32_32x32x16_bf16 v[16:31], v[68:71], v[224:227], v[16:31]
	global_load_dwordx4 v[188:191], v80, s[84:85]
	global_load_dwordx4 v[192:195], v80, s[84:85] offset:32
	global_load_dwordx4 v[196:199], v80, s[84:85] offset:64
	global_load_dwordx4 v[200:203], v80, s[84:85] offset:96
	global_load_dwordx4 v[204:207], v100, s[84:85] offset:768
	global_load_dwordx4 v[208:211], v149, s[84:85] offset:768
	global_load_dwordx4 v[212:215], v100, s[84:85] offset:832
	global_load_dwordx4 v[216:219], v149, s[84:85] offset:832
	s_add_u32 s84, s84, 0x30000
	s_addc_u32 s85, s85, 0
	s_waitcnt vmcnt(16)
	ds_write_b128 v112, v[132:135]
	ds_write_b128 v112, v[136:139] offset:1024
	ds_write_b128 v112, v[140:143] offset:2048
	ds_write_b128 v112, v[144:147] offset:3072
	ds_read2_b32 v[32:33], v115 offset0:192 offset1:193
	ds_read2_b32 v[34:35], v115 offset0:194 offset1:195
	ds_read2_b32 v[36:37], v115 offset0:200 offset1:201
	ds_read2_b32 v[38:39], v115 offset0:202 offset1:203
	ds_read2_b32 v[40:41], v115 offset0:208 offset1:209
	ds_read2_b32 v[42:43], v115 offset0:210 offset1:211
	ds_read2_b32 v[44:45], v115 offset0:216 offset1:217
	ds_read2_b32 v[46:47], v115 offset0:218 offset1:219
	s_waitcnt lgkmcnt(0)
	v_mfma_f32_32x32x16_bf16 v[32:47], v[116:119], v[48:51], v[32:47]
	ds_read_b64_tr_b16 v[72:73], v231
	ds_read_b64_tr_b16 v[74:75], v231 offset:512
	ds_read_b64_tr_b16 v[76:77], v231 offset:2048
	ds_read_b64_tr_b16 v[78:79], v231 offset:2560
	ds_read_b64_tr_b16 v[220:221], v231 offset:1024
	ds_read_b64_tr_b16 v[222:223], v231 offset:1536
	ds_read_b64_tr_b16 v[224:225], v231 offset:3072
	ds_read_b64_tr_b16 v[226:227], v231 offset:3584
	v_mfma_f32_32x32x16_bf16 v[32:47], v[120:123], v[52:55], v[32:47]
	v_mfma_f32_32x32x16_bf16 v[32:47], v[124:127], v[56:59], v[32:47]
	v_mfma_f32_32x32x16_bf16 v[32:47], v[128:131], v[60:63], v[32:47]
	s_nop 11
	v_exp_f32_e32 v32, v32
	v_exp_f32_e32 v33, v33
	v_exp_f32_e32 v34, v34
	v_exp_f32_e32 v35, v35
	v_exp_f32_e32 v36, v36
	v_exp_f32_e32 v37, v37
	v_exp_f32_e32 v38, v38
	v_exp_f32_e32 v39, v39
	v_exp_f32_e32 v40, v40
	v_exp_f32_e32 v41, v41
	v_exp_f32_e32 v42, v42
	v_exp_f32_e32 v43, v43
	v_exp_f32_e32 v44, v44
	v_exp_f32_e32 v45, v45
	v_exp_f32_e32 v46, v46
	v_exp_f32_e32 v47, v47
	v_cvt_pk_bf16_f32 v64, v32, v33
	v_cvt_pk_bf16_f32 v65, v34, v35
	v_cvt_pk_bf16_f32 v66, v36, v37
	v_cvt_pk_bf16_f32 v67, v38, v39
	v_cvt_pk_bf16_f32 v68, v40, v41
	v_cvt_pk_bf16_f32 v69, v42, v43
	v_cvt_pk_bf16_f32 v70, v44, v45
	v_cvt_pk_bf16_f32 v71, v46, v47
	v_pk_add_f32 v[232:233], v[232:233], v[32:33]
	v_pk_add_f32 v[232:233], v[232:233], v[34:35]
	v_pk_add_f32 v[232:233], v[232:233], v[36:37]
	v_pk_add_f32 v[232:233], v[232:233], v[38:39]
	v_pk_add_f32 v[232:233], v[232:233], v[40:41]
	v_pk_add_f32 v[232:233], v[232:233], v[42:43]
	v_pk_add_f32 v[232:233], v[232:233], v[44:45]
	v_pk_add_f32 v[232:233], v[232:233], v[46:47]
	s_waitcnt lgkmcnt(0)
	v_mfma_f32_32x32x16_bf16 v[0:15], v[64:67], v[72:75], v[0:15]
	v_mfma_f32_32x32x16_bf16 v[16:31], v[64:67], v[76:79], v[16:31]
	v_mfma_f32_32x32x16_bf16 v[0:15], v[68:71], v[220:223], v[0:15]
	v_mfma_f32_32x32x16_bf16 v[16:31], v[68:71], v[224:227], v[16:31]
	global_load_dwordx4 v[116:119], v80, s[84:85]
	global_load_dwordx4 v[120:123], v80, s[84:85] offset:32
	global_load_dwordx4 v[124:127], v80, s[84:85] offset:64
	global_load_dwordx4 v[128:131], v80, s[84:85] offset:96
	global_load_dwordx4 v[132:135], v100, s[84:85] offset:768
	global_load_dwordx4 v[136:139], v149, s[84:85] offset:768
	global_load_dwordx4 v[140:143], v100, s[84:85] offset:832
	global_load_dwordx4 v[144:147], v149, s[84:85] offset:832
	s_add_u32 s84, s84, 0x30000
	s_addc_u32 s85, s85, 0
	s_waitcnt vmcnt(16)
	ds_write_b128 v112, v[172:175]
	ds_write_b128 v112, v[176:179] offset:1024
	ds_write_b128 v112, v[180:183] offset:2048
	ds_write_b128 v112, v[184:187] offset:3072
	ds_read2_b32 v[32:33], v115 offset0:224 offset1:225
	ds_read2_b32 v[34:35], v115 offset0:226 offset1:227
	ds_read2_b32 v[36:37], v115 offset0:232 offset1:233
	ds_read2_b32 v[38:39], v115 offset0:234 offset1:235
	ds_read2_b32 v[40:41], v115 offset0:240 offset1:241
	ds_read2_b32 v[42:43], v115 offset0:242 offset1:243
	ds_read2_b32 v[44:45], v115 offset0:248 offset1:249
	ds_read2_b32 v[46:47], v115 offset0:250 offset1:251
	s_waitcnt lgkmcnt(0)
	v_mfma_f32_32x32x16_bf16 v[32:47], v[156:159], v[48:51], v[32:47]
	ds_read_b64_tr_b16 v[72:73], v231
	ds_read_b64_tr_b16 v[74:75], v231 offset:512
	ds_read_b64_tr_b16 v[76:77], v231 offset:2048
	ds_read_b64_tr_b16 v[78:79], v231 offset:2560
	ds_read_b64_tr_b16 v[220:221], v231 offset:1024
	ds_read_b64_tr_b16 v[222:223], v231 offset:1536
	ds_read_b64_tr_b16 v[224:225], v231 offset:3072
	ds_read_b64_tr_b16 v[226:227], v231 offset:3584
	v_mfma_f32_32x32x16_bf16 v[32:47], v[160:163], v[52:55], v[32:47]
	v_mfma_f32_32x32x16_bf16 v[32:47], v[164:167], v[56:59], v[32:47]
	v_mfma_f32_32x32x16_bf16 v[32:47], v[168:171], v[60:63], v[32:47]
	s_nop 11
	v_exp_f32_e32 v32, v32
	v_exp_f32_e32 v33, v33
	v_exp_f32_e32 v34, v34
	v_exp_f32_e32 v35, v35
	v_exp_f32_e32 v36, v36
	v_exp_f32_e32 v37, v37
	v_exp_f32_e32 v38, v38
	v_exp_f32_e32 v39, v39
	v_exp_f32_e32 v40, v40
	v_exp_f32_e32 v41, v41
	v_exp_f32_e32 v42, v42
	v_exp_f32_e32 v43, v43
	v_exp_f32_e32 v44, v44
	v_exp_f32_e32 v45, v45
	v_exp_f32_e32 v46, v46
	v_exp_f32_e32 v47, v47
	v_cvt_pk_bf16_f32 v64, v32, v33
	v_cvt_pk_bf16_f32 v65, v34, v35
	v_cvt_pk_bf16_f32 v66, v36, v37
	v_cvt_pk_bf16_f32 v67, v38, v39
	v_cvt_pk_bf16_f32 v68, v40, v41
	v_cvt_pk_bf16_f32 v69, v42, v43
	v_cvt_pk_bf16_f32 v70, v44, v45
	v_cvt_pk_bf16_f32 v71, v46, v47
	v_pk_add_f32 v[232:233], v[232:233], v[32:33]
	v_pk_add_f32 v[232:233], v[232:233], v[34:35]
	v_pk_add_f32 v[232:233], v[232:233], v[36:37]
	v_pk_add_f32 v[232:233], v[232:233], v[38:39]
	v_pk_add_f32 v[232:233], v[232:233], v[40:41]
	v_pk_add_f32 v[232:233], v[232:233], v[42:43]
	v_pk_add_f32 v[232:233], v[232:233], v[44:45]
	v_pk_add_f32 v[232:233], v[232:233], v[46:47]
	s_waitcnt lgkmcnt(0)
	v_mfma_f32_32x32x16_bf16 v[0:15], v[64:67], v[72:75], v[0:15]
	v_mfma_f32_32x32x16_bf16 v[16:31], v[64:67], v[76:79], v[16:31]
	v_mfma_f32_32x32x16_bf16 v[0:15], v[68:71], v[220:223], v[0:15]
	v_mfma_f32_32x32x16_bf16 v[16:31], v[68:71], v[224:227], v[16:31]
	global_load_dwordx4 v[156:159], v80, s[84:85]
	global_load_dwordx4 v[160:163], v80, s[84:85] offset:32
	global_load_dwordx4 v[164:167], v80, s[84:85] offset:64
	global_load_dwordx4 v[168:171], v80, s[84:85] offset:96
	global_load_dwordx4 v[172:175], v100, s[84:85] offset:768
	global_load_dwordx4 v[176:179], v149, s[84:85] offset:768
	global_load_dwordx4 v[180:183], v100, s[84:85] offset:832
	global_load_dwordx4 v[184:187], v149, s[84:85] offset:832
	s_add_u32 s84, s84, 0x30000
	s_addc_u32 s85, s85, 0
	s_waitcnt vmcnt(16)
	ds_write_b128 v112, v[204:207]
	ds_write_b128 v112, v[208:211] offset:1024
	ds_write_b128 v112, v[212:215] offset:2048
	ds_write_b128 v112, v[216:219] offset:3072
	v_add_u32_e32 v115, 0x400, v115
	ds_read2_b32 v[32:33], v115 offset0:0 offset1:1
	ds_read2_b32 v[34:35], v115 offset0:2 offset1:3
	ds_read2_b32 v[36:37], v115 offset0:8 offset1:9
	ds_read2_b32 v[38:39], v115 offset0:10 offset1:11
	ds_read2_b32 v[40:41], v115 offset0:16 offset1:17
	ds_read2_b32 v[42:43], v115 offset0:18 offset1:19
	ds_read2_b32 v[44:45], v115 offset0:24 offset1:25
	ds_read2_b32 v[46:47], v115 offset0:26 offset1:27
	s_waitcnt lgkmcnt(0)
	v_mfma_f32_32x32x16_bf16 v[32:47], v[188:191], v[48:51], v[32:47]
	ds_read_b64_tr_b16 v[72:73], v231
	ds_read_b64_tr_b16 v[74:75], v231 offset:512
	ds_read_b64_tr_b16 v[76:77], v231 offset:2048
	ds_read_b64_tr_b16 v[78:79], v231 offset:2560
	ds_read_b64_tr_b16 v[220:221], v231 offset:1024
	ds_read_b64_tr_b16 v[222:223], v231 offset:1536
	ds_read_b64_tr_b16 v[224:225], v231 offset:3072
	ds_read_b64_tr_b16 v[226:227], v231 offset:3584
	v_mfma_f32_32x32x16_bf16 v[32:47], v[192:195], v[52:55], v[32:47]
	v_mfma_f32_32x32x16_bf16 v[32:47], v[196:199], v[56:59], v[32:47]
	v_mfma_f32_32x32x16_bf16 v[32:47], v[200:203], v[60:63], v[32:47]
	s_nop 11
	v_exp_f32_e32 v32, v32
	v_exp_f32_e32 v33, v33
	v_exp_f32_e32 v34, v34
	v_exp_f32_e32 v35, v35
	v_exp_f32_e32 v36, v36
	v_exp_f32_e32 v37, v37
	v_exp_f32_e32 v38, v38
	v_exp_f32_e32 v39, v39
	v_exp_f32_e32 v40, v40
	v_exp_f32_e32 v41, v41
	v_exp_f32_e32 v42, v42
	v_exp_f32_e32 v43, v43
	v_exp_f32_e32 v44, v44
	v_exp_f32_e32 v45, v45
	v_exp_f32_e32 v46, v46
	v_exp_f32_e32 v47, v47
	v_cvt_pk_bf16_f32 v64, v32, v33
	v_cvt_pk_bf16_f32 v65, v34, v35
	v_cvt_pk_bf16_f32 v66, v36, v37
	v_cvt_pk_bf16_f32 v67, v38, v39
	v_cvt_pk_bf16_f32 v68, v40, v41
	v_cvt_pk_bf16_f32 v69, v42, v43
	v_cvt_pk_bf16_f32 v70, v44, v45
	v_cvt_pk_bf16_f32 v71, v46, v47
	v_pk_add_f32 v[232:233], v[232:233], v[32:33]
	v_pk_add_f32 v[232:233], v[232:233], v[34:35]
	v_pk_add_f32 v[232:233], v[232:233], v[36:37]
	v_pk_add_f32 v[232:233], v[232:233], v[38:39]
	v_pk_add_f32 v[232:233], v[232:233], v[40:41]
	v_pk_add_f32 v[232:233], v[232:233], v[42:43]
	v_pk_add_f32 v[232:233], v[232:233], v[44:45]
	v_pk_add_f32 v[232:233], v[232:233], v[46:47]
	s_waitcnt lgkmcnt(0)
	v_mfma_f32_32x32x16_bf16 v[0:15], v[64:67], v[72:75], v[0:15]
	v_mfma_f32_32x32x16_bf16 v[16:31], v[64:67], v[76:79], v[16:31]
	v_mfma_f32_32x32x16_bf16 v[0:15], v[68:71], v[220:223], v[0:15]
	v_mfma_f32_32x32x16_bf16 v[16:31], v[68:71], v[224:227], v[16:31]
	global_load_dwordx4 v[188:191], v80, s[84:85]
	global_load_dwordx4 v[192:195], v80, s[84:85] offset:32
	global_load_dwordx4 v[196:199], v80, s[84:85] offset:64
	global_load_dwordx4 v[200:203], v80, s[84:85] offset:96
	global_load_dwordx4 v[204:207], v100, s[84:85] offset:768
	global_load_dwordx4 v[208:211], v149, s[84:85] offset:768
	global_load_dwordx4 v[212:215], v100, s[84:85] offset:832
	global_load_dwordx4 v[216:219], v149, s[84:85] offset:832
	s_add_u32 s84, s84, 0x30000
	s_addc_u32 s85, s85, 0
	s_waitcnt vmcnt(16)
	ds_write_b128 v112, v[132:135]
	ds_write_b128 v112, v[136:139] offset:1024
	ds_write_b128 v112, v[140:143] offset:2048
	ds_write_b128 v112, v[144:147] offset:3072
	ds_read2_b32 v[32:33], v115 offset0:32 offset1:33
	ds_read2_b32 v[34:35], v115 offset0:34 offset1:35
	ds_read2_b32 v[36:37], v115 offset0:40 offset1:41
	ds_read2_b32 v[38:39], v115 offset0:42 offset1:43
	ds_read2_b32 v[40:41], v115 offset0:48 offset1:49
	ds_read2_b32 v[42:43], v115 offset0:50 offset1:51
	ds_read2_b32 v[44:45], v115 offset0:56 offset1:57
	ds_read2_b32 v[46:47], v115 offset0:58 offset1:59
	s_waitcnt lgkmcnt(0)
	v_mfma_f32_32x32x16_bf16 v[32:47], v[116:119], v[48:51], v[32:47]
	ds_read_b64_tr_b16 v[72:73], v231
	ds_read_b64_tr_b16 v[74:75], v231 offset:512
	ds_read_b64_tr_b16 v[76:77], v231 offset:2048
	ds_read_b64_tr_b16 v[78:79], v231 offset:2560
	ds_read_b64_tr_b16 v[220:221], v231 offset:1024
	ds_read_b64_tr_b16 v[222:223], v231 offset:1536
	ds_read_b64_tr_b16 v[224:225], v231 offset:3072
	ds_read_b64_tr_b16 v[226:227], v231 offset:3584
	v_mfma_f32_32x32x16_bf16 v[32:47], v[120:123], v[52:55], v[32:47]
	v_mfma_f32_32x32x16_bf16 v[32:47], v[124:127], v[56:59], v[32:47]
	v_mfma_f32_32x32x16_bf16 v[32:47], v[128:131], v[60:63], v[32:47]
	s_nop 11
	v_exp_f32_e32 v32, v32
	v_exp_f32_e32 v33, v33
	v_exp_f32_e32 v34, v34
	v_exp_f32_e32 v35, v35
	v_exp_f32_e32 v36, v36
	v_exp_f32_e32 v37, v37
	v_exp_f32_e32 v38, v38
	v_exp_f32_e32 v39, v39
	v_exp_f32_e32 v40, v40
	v_exp_f32_e32 v41, v41
	v_exp_f32_e32 v42, v42
	v_exp_f32_e32 v43, v43
	v_exp_f32_e32 v44, v44
	v_exp_f32_e32 v45, v45
	v_exp_f32_e32 v46, v46
	v_exp_f32_e32 v47, v47
	v_cvt_pk_bf16_f32 v64, v32, v33
	v_cvt_pk_bf16_f32 v65, v34, v35
	v_cvt_pk_bf16_f32 v66, v36, v37
	v_cvt_pk_bf16_f32 v67, v38, v39
	v_cvt_pk_bf16_f32 v68, v40, v41
	v_cvt_pk_bf16_f32 v69, v42, v43
	v_cvt_pk_bf16_f32 v70, v44, v45
	v_cvt_pk_bf16_f32 v71, v46, v47
	v_pk_add_f32 v[232:233], v[232:233], v[32:33]
	v_pk_add_f32 v[232:233], v[232:233], v[34:35]
	v_pk_add_f32 v[232:233], v[232:233], v[36:37]
	v_pk_add_f32 v[232:233], v[232:233], v[38:39]
	v_pk_add_f32 v[232:233], v[232:233], v[40:41]
	v_pk_add_f32 v[232:233], v[232:233], v[42:43]
	v_pk_add_f32 v[232:233], v[232:233], v[44:45]
	v_pk_add_f32 v[232:233], v[232:233], v[46:47]
	s_waitcnt lgkmcnt(0)
	v_mfma_f32_32x32x16_bf16 v[0:15], v[64:67], v[72:75], v[0:15]
	v_mfma_f32_32x32x16_bf16 v[16:31], v[64:67], v[76:79], v[16:31]
	v_mfma_f32_32x32x16_bf16 v[0:15], v[68:71], v[220:223], v[0:15]
	v_mfma_f32_32x32x16_bf16 v[16:31], v[68:71], v[224:227], v[16:31]
	global_load_dwordx4 v[116:119], v80, s[84:85]
	global_load_dwordx4 v[120:123], v80, s[84:85] offset:32
	global_load_dwordx4 v[124:127], v80, s[84:85] offset:64
	global_load_dwordx4 v[128:131], v80, s[84:85] offset:96
	global_load_dwordx4 v[132:135], v100, s[84:85] offset:768
	global_load_dwordx4 v[136:139], v149, s[84:85] offset:768
	global_load_dwordx4 v[140:143], v100, s[84:85] offset:832
	global_load_dwordx4 v[144:147], v149, s[84:85] offset:832
	s_add_u32 s84, s84, 0x30000
	s_addc_u32 s85, s85, 0
	s_waitcnt vmcnt(16)
	ds_write_b128 v112, v[172:175]
	ds_write_b128 v112, v[176:179] offset:1024
	ds_write_b128 v112, v[180:183] offset:2048
	ds_write_b128 v112, v[184:187] offset:3072
	ds_read2_b32 v[32:33], v115 offset0:64 offset1:65
	ds_read2_b32 v[34:35], v115 offset0:66 offset1:67
	ds_read2_b32 v[36:37], v115 offset0:72 offset1:73
	ds_read2_b32 v[38:39], v115 offset0:74 offset1:75
	ds_read2_b32 v[40:41], v115 offset0:80 offset1:81
	ds_read2_b32 v[42:43], v115 offset0:82 offset1:83
	ds_read2_b32 v[44:45], v115 offset0:88 offset1:89
	ds_read2_b32 v[46:47], v115 offset0:90 offset1:91
	s_waitcnt lgkmcnt(0)
	v_mfma_f32_32x32x16_bf16 v[32:47], v[156:159], v[48:51], v[32:47]
	ds_read_b64_tr_b16 v[72:73], v231
	ds_read_b64_tr_b16 v[74:75], v231 offset:512
	ds_read_b64_tr_b16 v[76:77], v231 offset:2048
	ds_read_b64_tr_b16 v[78:79], v231 offset:2560
	ds_read_b64_tr_b16 v[220:221], v231 offset:1024
	ds_read_b64_tr_b16 v[222:223], v231 offset:1536
	ds_read_b64_tr_b16 v[224:225], v231 offset:3072
	ds_read_b64_tr_b16 v[226:227], v231 offset:3584
	v_mfma_f32_32x32x16_bf16 v[32:47], v[160:163], v[52:55], v[32:47]
	v_mfma_f32_32x32x16_bf16 v[32:47], v[164:167], v[56:59], v[32:47]
	v_mfma_f32_32x32x16_bf16 v[32:47], v[168:171], v[60:63], v[32:47]
	s_nop 11
	v_exp_f32_e32 v32, v32
	v_exp_f32_e32 v33, v33
	v_exp_f32_e32 v34, v34
	v_exp_f32_e32 v35, v35
	v_exp_f32_e32 v36, v36
	v_exp_f32_e32 v37, v37
	v_exp_f32_e32 v38, v38
	v_exp_f32_e32 v39, v39
	v_exp_f32_e32 v40, v40
	v_exp_f32_e32 v41, v41
	v_exp_f32_e32 v42, v42
	v_exp_f32_e32 v43, v43
	v_exp_f32_e32 v44, v44
	v_exp_f32_e32 v45, v45
	v_exp_f32_e32 v46, v46
	v_exp_f32_e32 v47, v47
	v_cvt_pk_bf16_f32 v64, v32, v33
	v_cvt_pk_bf16_f32 v65, v34, v35
	v_cvt_pk_bf16_f32 v66, v36, v37
	v_cvt_pk_bf16_f32 v67, v38, v39
	v_cvt_pk_bf16_f32 v68, v40, v41
	v_cvt_pk_bf16_f32 v69, v42, v43
	v_cvt_pk_bf16_f32 v70, v44, v45
	v_cvt_pk_bf16_f32 v71, v46, v47
	v_pk_add_f32 v[232:233], v[232:233], v[32:33]
	v_pk_add_f32 v[232:233], v[232:233], v[34:35]
	v_pk_add_f32 v[232:233], v[232:233], v[36:37]
	v_pk_add_f32 v[232:233], v[232:233], v[38:39]
	v_pk_add_f32 v[232:233], v[232:233], v[40:41]
	v_pk_add_f32 v[232:233], v[232:233], v[42:43]
	v_pk_add_f32 v[232:233], v[232:233], v[44:45]
	v_pk_add_f32 v[232:233], v[232:233], v[46:47]
	s_waitcnt lgkmcnt(0)
	v_mfma_f32_32x32x16_bf16 v[0:15], v[64:67], v[72:75], v[0:15]
	v_mfma_f32_32x32x16_bf16 v[16:31], v[64:67], v[76:79], v[16:31]
	v_mfma_f32_32x32x16_bf16 v[0:15], v[68:71], v[220:223], v[0:15]
	v_mfma_f32_32x32x16_bf16 v[16:31], v[68:71], v[224:227], v[16:31]
	global_load_dwordx4 v[156:159], v80, s[84:85]
	global_load_dwordx4 v[160:163], v80, s[84:85] offset:32
	global_load_dwordx4 v[164:167], v80, s[84:85] offset:64
	global_load_dwordx4 v[168:171], v80, s[84:85] offset:96
	global_load_dwordx4 v[172:175], v100, s[84:85] offset:768
	global_load_dwordx4 v[176:179], v149, s[84:85] offset:768
	global_load_dwordx4 v[180:183], v100, s[84:85] offset:832
	global_load_dwordx4 v[184:187], v149, s[84:85] offset:832
	s_add_u32 s84, s84, 0x30000
	s_addc_u32 s85, s85, 0
	s_waitcnt vmcnt(16)
	ds_write_b128 v112, v[204:207]
	ds_write_b128 v112, v[208:211] offset:1024
	ds_write_b128 v112, v[212:215] offset:2048
	ds_write_b128 v112, v[216:219] offset:3072
	ds_read2_b32 v[32:33], v115 offset0:96 offset1:97
	ds_read2_b32 v[34:35], v115 offset0:98 offset1:99
	ds_read2_b32 v[36:37], v115 offset0:104 offset1:105
	ds_read2_b32 v[38:39], v115 offset0:106 offset1:107
	ds_read2_b32 v[40:41], v115 offset0:112 offset1:113
	ds_read2_b32 v[42:43], v115 offset0:114 offset1:115
	ds_read2_b32 v[44:45], v115 offset0:120 offset1:121
	ds_read2_b32 v[46:47], v115 offset0:122 offset1:123
	s_waitcnt lgkmcnt(0)
	v_mfma_f32_32x32x16_bf16 v[32:47], v[188:191], v[48:51], v[32:47]
	ds_read_b64_tr_b16 v[72:73], v231
	ds_read_b64_tr_b16 v[74:75], v231 offset:512
	ds_read_b64_tr_b16 v[76:77], v231 offset:2048
	ds_read_b64_tr_b16 v[78:79], v231 offset:2560
	ds_read_b64_tr_b16 v[220:221], v231 offset:1024
	ds_read_b64_tr_b16 v[222:223], v231 offset:1536
	ds_read_b64_tr_b16 v[224:225], v231 offset:3072
	ds_read_b64_tr_b16 v[226:227], v231 offset:3584
	v_mfma_f32_32x32x16_bf16 v[32:47], v[192:195], v[52:55], v[32:47]
	v_mfma_f32_32x32x16_bf16 v[32:47], v[196:199], v[56:59], v[32:47]
	v_mfma_f32_32x32x16_bf16 v[32:47], v[200:203], v[60:63], v[32:47]
	s_nop 11
	v_exp_f32_e32 v32, v32
	v_exp_f32_e32 v33, v33
	v_exp_f32_e32 v34, v34
	v_exp_f32_e32 v35, v35
	v_exp_f32_e32 v36, v36
	v_exp_f32_e32 v37, v37
	v_exp_f32_e32 v38, v38
	v_exp_f32_e32 v39, v39
	v_exp_f32_e32 v40, v40
	v_exp_f32_e32 v41, v41
	v_exp_f32_e32 v42, v42
	v_exp_f32_e32 v43, v43
	v_exp_f32_e32 v44, v44
	v_exp_f32_e32 v45, v45
	v_exp_f32_e32 v46, v46
	v_exp_f32_e32 v47, v47
	v_cvt_pk_bf16_f32 v64, v32, v33
	v_cvt_pk_bf16_f32 v65, v34, v35
	v_cvt_pk_bf16_f32 v66, v36, v37
	v_cvt_pk_bf16_f32 v67, v38, v39
	v_cvt_pk_bf16_f32 v68, v40, v41
	v_cvt_pk_bf16_f32 v69, v42, v43
	v_cvt_pk_bf16_f32 v70, v44, v45
	v_cvt_pk_bf16_f32 v71, v46, v47
	v_pk_add_f32 v[232:233], v[232:233], v[32:33]
	v_pk_add_f32 v[232:233], v[232:233], v[34:35]
	v_pk_add_f32 v[232:233], v[232:233], v[36:37]
	v_pk_add_f32 v[232:233], v[232:233], v[38:39]
	v_pk_add_f32 v[232:233], v[232:233], v[40:41]
	v_pk_add_f32 v[232:233], v[232:233], v[42:43]
	v_pk_add_f32 v[232:233], v[232:233], v[44:45]
	v_pk_add_f32 v[232:233], v[232:233], v[46:47]
	s_waitcnt lgkmcnt(0)
	v_mfma_f32_32x32x16_bf16 v[0:15], v[64:67], v[72:75], v[0:15]
	v_mfma_f32_32x32x16_bf16 v[16:31], v[64:67], v[76:79], v[16:31]
	v_mfma_f32_32x32x16_bf16 v[0:15], v[68:71], v[220:223], v[0:15]
	v_mfma_f32_32x32x16_bf16 v[16:31], v[68:71], v[224:227], v[16:31]
	global_load_dwordx4 v[188:191], v80, s[84:85]
	global_load_dwordx4 v[192:195], v80, s[84:85] offset:32
	global_load_dwordx4 v[196:199], v80, s[84:85] offset:64
	global_load_dwordx4 v[200:203], v80, s[84:85] offset:96
	global_load_dwordx4 v[204:207], v100, s[84:85] offset:768
	global_load_dwordx4 v[208:211], v149, s[84:85] offset:768
	global_load_dwordx4 v[212:215], v100, s[84:85] offset:832
	global_load_dwordx4 v[216:219], v149, s[84:85] offset:832
	s_add_u32 s84, s84, 0x30000
	s_addc_u32 s85, s85, 0
	s_waitcnt vmcnt(16)
	ds_write_b128 v112, v[132:135]
	ds_write_b128 v112, v[136:139] offset:1024
	ds_write_b128 v112, v[140:143] offset:2048
	ds_write_b128 v112, v[144:147] offset:3072
	ds_read2_b32 v[32:33], v115 offset0:128 offset1:129
	ds_read2_b32 v[34:35], v115 offset0:130 offset1:131
	ds_read2_b32 v[36:37], v115 offset0:136 offset1:137
	ds_read2_b32 v[38:39], v115 offset0:138 offset1:139
	ds_read2_b32 v[40:41], v115 offset0:144 offset1:145
	ds_read2_b32 v[42:43], v115 offset0:146 offset1:147
	ds_read2_b32 v[44:45], v115 offset0:152 offset1:153
	ds_read2_b32 v[46:47], v115 offset0:154 offset1:155
	s_waitcnt lgkmcnt(0)
	v_mfma_f32_32x32x16_bf16 v[32:47], v[116:119], v[48:51], v[32:47]
	ds_read_b64_tr_b16 v[72:73], v231
	ds_read_b64_tr_b16 v[74:75], v231 offset:512
	ds_read_b64_tr_b16 v[76:77], v231 offset:2048
	ds_read_b64_tr_b16 v[78:79], v231 offset:2560
	ds_read_b64_tr_b16 v[220:221], v231 offset:1024
	ds_read_b64_tr_b16 v[222:223], v231 offset:1536
	ds_read_b64_tr_b16 v[224:225], v231 offset:3072
	ds_read_b64_tr_b16 v[226:227], v231 offset:3584
	v_mfma_f32_32x32x16_bf16 v[32:47], v[120:123], v[52:55], v[32:47]
	v_mfma_f32_32x32x16_bf16 v[32:47], v[124:127], v[56:59], v[32:47]
	v_mfma_f32_32x32x16_bf16 v[32:47], v[128:131], v[60:63], v[32:47]
	s_nop 11
	v_exp_f32_e32 v32, v32
	v_exp_f32_e32 v33, v33
	v_exp_f32_e32 v34, v34
	v_exp_f32_e32 v35, v35
	v_exp_f32_e32 v36, v36
	v_exp_f32_e32 v37, v37
	v_exp_f32_e32 v38, v38
	v_exp_f32_e32 v39, v39
	v_exp_f32_e32 v40, v40
	v_exp_f32_e32 v41, v41
	v_exp_f32_e32 v42, v42
	v_exp_f32_e32 v43, v43
	v_exp_f32_e32 v44, v44
	v_exp_f32_e32 v45, v45
	v_exp_f32_e32 v46, v46
	v_exp_f32_e32 v47, v47
	v_cvt_pk_bf16_f32 v64, v32, v33
	v_cvt_pk_bf16_f32 v65, v34, v35
	v_cvt_pk_bf16_f32 v66, v36, v37
	v_cvt_pk_bf16_f32 v67, v38, v39
	v_cvt_pk_bf16_f32 v68, v40, v41
	v_cvt_pk_bf16_f32 v69, v42, v43
	v_cvt_pk_bf16_f32 v70, v44, v45
	v_cvt_pk_bf16_f32 v71, v46, v47
	v_pk_add_f32 v[232:233], v[232:233], v[32:33]
	v_pk_add_f32 v[232:233], v[232:233], v[34:35]
	v_pk_add_f32 v[232:233], v[232:233], v[36:37]
	v_pk_add_f32 v[232:233], v[232:233], v[38:39]
	v_pk_add_f32 v[232:233], v[232:233], v[40:41]
	v_pk_add_f32 v[232:233], v[232:233], v[42:43]
	v_pk_add_f32 v[232:233], v[232:233], v[44:45]
	v_pk_add_f32 v[232:233], v[232:233], v[46:47]
	s_waitcnt lgkmcnt(0)
	v_mfma_f32_32x32x16_bf16 v[0:15], v[64:67], v[72:75], v[0:15]
	v_mfma_f32_32x32x16_bf16 v[16:31], v[64:67], v[76:79], v[16:31]
	v_mfma_f32_32x32x16_bf16 v[0:15], v[68:71], v[220:223], v[0:15]
	v_mfma_f32_32x32x16_bf16 v[16:31], v[68:71], v[224:227], v[16:31]
	global_load_dwordx4 v[116:119], v80, s[84:85]
	global_load_dwordx4 v[120:123], v80, s[84:85] offset:32
	global_load_dwordx4 v[124:127], v80, s[84:85] offset:64
	global_load_dwordx4 v[128:131], v80, s[84:85] offset:96
	global_load_dwordx4 v[132:135], v100, s[84:85] offset:768
	global_load_dwordx4 v[136:139], v149, s[84:85] offset:768
	global_load_dwordx4 v[140:143], v100, s[84:85] offset:832
	global_load_dwordx4 v[144:147], v149, s[84:85] offset:832
	s_add_u32 s84, s84, 0x30000
	s_addc_u32 s85, s85, 0
	s_waitcnt vmcnt(16)
	ds_write_b128 v112, v[172:175]
	ds_write_b128 v112, v[176:179] offset:1024
	ds_write_b128 v112, v[180:183] offset:2048
	ds_write_b128 v112, v[184:187] offset:3072
	ds_read2_b32 v[32:33], v115 offset0:160 offset1:161
	ds_read2_b32 v[34:35], v115 offset0:162 offset1:163
	ds_read2_b32 v[36:37], v115 offset0:168 offset1:169
	ds_read2_b32 v[38:39], v115 offset0:170 offset1:171
	ds_read2_b32 v[40:41], v115 offset0:176 offset1:177
	ds_read2_b32 v[42:43], v115 offset0:178 offset1:179
	ds_read2_b32 v[44:45], v115 offset0:184 offset1:185
	ds_read2_b32 v[46:47], v115 offset0:186 offset1:187
	s_waitcnt lgkmcnt(0)
	v_mfma_f32_32x32x16_bf16 v[32:47], v[156:159], v[48:51], v[32:47]
	ds_read_b64_tr_b16 v[72:73], v231
	ds_read_b64_tr_b16 v[74:75], v231 offset:512
	ds_read_b64_tr_b16 v[76:77], v231 offset:2048
	ds_read_b64_tr_b16 v[78:79], v231 offset:2560
	ds_read_b64_tr_b16 v[220:221], v231 offset:1024
	ds_read_b64_tr_b16 v[222:223], v231 offset:1536
	ds_read_b64_tr_b16 v[224:225], v231 offset:3072
	ds_read_b64_tr_b16 v[226:227], v231 offset:3584
	v_mfma_f32_32x32x16_bf16 v[32:47], v[160:163], v[52:55], v[32:47]
	v_mfma_f32_32x32x16_bf16 v[32:47], v[164:167], v[56:59], v[32:47]
	v_mfma_f32_32x32x16_bf16 v[32:47], v[168:171], v[60:63], v[32:47]
	s_nop 11
	v_exp_f32_e32 v32, v32
	v_exp_f32_e32 v33, v33
	v_exp_f32_e32 v34, v34
	v_exp_f32_e32 v35, v35
	v_exp_f32_e32 v36, v36
	v_exp_f32_e32 v37, v37
	v_exp_f32_e32 v38, v38
	v_exp_f32_e32 v39, v39
	v_exp_f32_e32 v40, v40
	v_exp_f32_e32 v41, v41
	v_exp_f32_e32 v42, v42
	v_exp_f32_e32 v43, v43
	v_exp_f32_e32 v44, v44
	v_exp_f32_e32 v45, v45
	v_exp_f32_e32 v46, v46
	v_exp_f32_e32 v47, v47
	v_cvt_pk_bf16_f32 v64, v32, v33
	v_cvt_pk_bf16_f32 v65, v34, v35
	v_cvt_pk_bf16_f32 v66, v36, v37
	v_cvt_pk_bf16_f32 v67, v38, v39
	v_cvt_pk_bf16_f32 v68, v40, v41
	v_cvt_pk_bf16_f32 v69, v42, v43
	v_cvt_pk_bf16_f32 v70, v44, v45
	v_cvt_pk_bf16_f32 v71, v46, v47
	v_pk_add_f32 v[232:233], v[232:233], v[32:33]
	v_pk_add_f32 v[232:233], v[232:233], v[34:35]
	v_pk_add_f32 v[232:233], v[232:233], v[36:37]
	v_pk_add_f32 v[232:233], v[232:233], v[38:39]
	v_pk_add_f32 v[232:233], v[232:233], v[40:41]
	v_pk_add_f32 v[232:233], v[232:233], v[42:43]
	v_pk_add_f32 v[232:233], v[232:233], v[44:45]
	v_pk_add_f32 v[232:233], v[232:233], v[46:47]
	s_waitcnt lgkmcnt(0)
	v_mfma_f32_32x32x16_bf16 v[0:15], v[64:67], v[72:75], v[0:15]
	v_mfma_f32_32x32x16_bf16 v[16:31], v[64:67], v[76:79], v[16:31]
	v_mfma_f32_32x32x16_bf16 v[0:15], v[68:71], v[220:223], v[0:15]
	v_mfma_f32_32x32x16_bf16 v[16:31], v[68:71], v[224:227], v[16:31]
	global_load_dwordx4 v[156:159], v80, s[84:85]
	global_load_dwordx4 v[160:163], v80, s[84:85] offset:32
	global_load_dwordx4 v[164:167], v80, s[84:85] offset:64
	global_load_dwordx4 v[168:171], v80, s[84:85] offset:96
	global_load_dwordx4 v[172:175], v100, s[84:85] offset:768
	global_load_dwordx4 v[176:179], v149, s[84:85] offset:768
	global_load_dwordx4 v[180:183], v100, s[84:85] offset:832
	global_load_dwordx4 v[184:187], v149, s[84:85] offset:832
	s_add_u32 s84, s84, 0x30000
	s_addc_u32 s85, s85, 0
	s_waitcnt vmcnt(16)
	ds_write_b128 v112, v[204:207]
	ds_write_b128 v112, v[208:211] offset:1024
	ds_write_b128 v112, v[212:215] offset:2048
	ds_write_b128 v112, v[216:219] offset:3072
	ds_read2_b32 v[32:33], v115 offset0:192 offset1:193
	ds_read2_b32 v[34:35], v115 offset0:194 offset1:195
	ds_read2_b32 v[36:37], v115 offset0:200 offset1:201
	ds_read2_b32 v[38:39], v115 offset0:202 offset1:203
	ds_read2_b32 v[40:41], v115 offset0:208 offset1:209
	ds_read2_b32 v[42:43], v115 offset0:210 offset1:211
	ds_read2_b32 v[44:45], v115 offset0:216 offset1:217
	ds_read2_b32 v[46:47], v115 offset0:218 offset1:219
	s_waitcnt lgkmcnt(0)
	v_mfma_f32_32x32x16_bf16 v[32:47], v[188:191], v[48:51], v[32:47]
	ds_read_b64_tr_b16 v[72:73], v231
	ds_read_b64_tr_b16 v[74:75], v231 offset:512
	ds_read_b64_tr_b16 v[76:77], v231 offset:2048
	ds_read_b64_tr_b16 v[78:79], v231 offset:2560
	ds_read_b64_tr_b16 v[220:221], v231 offset:1024
	ds_read_b64_tr_b16 v[222:223], v231 offset:1536
	ds_read_b64_tr_b16 v[224:225], v231 offset:3072
	ds_read_b64_tr_b16 v[226:227], v231 offset:3584
	v_mfma_f32_32x32x16_bf16 v[32:47], v[192:195], v[52:55], v[32:47]
	v_mfma_f32_32x32x16_bf16 v[32:47], v[196:199], v[56:59], v[32:47]
	v_mfma_f32_32x32x16_bf16 v[32:47], v[200:203], v[60:63], v[32:47]
	s_nop 11
	v_exp_f32_e32 v32, v32
	v_exp_f32_e32 v33, v33
	v_exp_f32_e32 v34, v34
	v_exp_f32_e32 v35, v35
	v_exp_f32_e32 v36, v36
	v_exp_f32_e32 v37, v37
	v_exp_f32_e32 v38, v38
	v_exp_f32_e32 v39, v39
	v_exp_f32_e32 v40, v40
	v_exp_f32_e32 v41, v41
	v_exp_f32_e32 v42, v42
	v_exp_f32_e32 v43, v43
	v_exp_f32_e32 v44, v44
	v_exp_f32_e32 v45, v45
	v_exp_f32_e32 v46, v46
	v_exp_f32_e32 v47, v47
	v_cvt_pk_bf16_f32 v64, v32, v33
	v_cvt_pk_bf16_f32 v65, v34, v35
	v_cvt_pk_bf16_f32 v66, v36, v37
	v_cvt_pk_bf16_f32 v67, v38, v39
	v_cvt_pk_bf16_f32 v68, v40, v41
	v_cvt_pk_bf16_f32 v69, v42, v43
	v_cvt_pk_bf16_f32 v70, v44, v45
	v_cvt_pk_bf16_f32 v71, v46, v47
	v_pk_add_f32 v[232:233], v[232:233], v[32:33]
	v_pk_add_f32 v[232:233], v[232:233], v[34:35]
	v_pk_add_f32 v[232:233], v[232:233], v[36:37]
	v_pk_add_f32 v[232:233], v[232:233], v[38:39]
	v_pk_add_f32 v[232:233], v[232:233], v[40:41]
	v_pk_add_f32 v[232:233], v[232:233], v[42:43]
	v_pk_add_f32 v[232:233], v[232:233], v[44:45]
	v_pk_add_f32 v[232:233], v[232:233], v[46:47]
	s_waitcnt lgkmcnt(0)
	v_mfma_f32_32x32x16_bf16 v[0:15], v[64:67], v[72:75], v[0:15]
	v_mfma_f32_32x32x16_bf16 v[16:31], v[64:67], v[76:79], v[16:31]
	v_mfma_f32_32x32x16_bf16 v[0:15], v[68:71], v[220:223], v[0:15]
	v_mfma_f32_32x32x16_bf16 v[16:31], v[68:71], v[224:227], v[16:31]
	global_load_dwordx4 v[188:191], v80, s[84:85]
	global_load_dwordx4 v[192:195], v80, s[84:85] offset:32
	global_load_dwordx4 v[196:199], v80, s[84:85] offset:64
	global_load_dwordx4 v[200:203], v80, s[84:85] offset:96
	global_load_dwordx4 v[204:207], v100, s[84:85] offset:768
	global_load_dwordx4 v[208:211], v149, s[84:85] offset:768
	global_load_dwordx4 v[212:215], v100, s[84:85] offset:832
	global_load_dwordx4 v[216:219], v149, s[84:85] offset:832
	s_add_u32 s84, s84, 0x30000
	s_addc_u32 s85, s85, 0
	s_waitcnt vmcnt(16)
	ds_write_b128 v112, v[132:135]
	ds_write_b128 v112, v[136:139] offset:1024
	ds_write_b128 v112, v[140:143] offset:2048
	ds_write_b128 v112, v[144:147] offset:3072
	ds_read2_b32 v[32:33], v115 offset0:224 offset1:225
	ds_read2_b32 v[34:35], v115 offset0:226 offset1:227
	ds_read2_b32 v[36:37], v115 offset0:232 offset1:233
	ds_read2_b32 v[38:39], v115 offset0:234 offset1:235
	ds_read2_b32 v[40:41], v115 offset0:240 offset1:241
	ds_read2_b32 v[42:43], v115 offset0:242 offset1:243
	ds_read2_b32 v[44:45], v115 offset0:248 offset1:249
	ds_read2_b32 v[46:47], v115 offset0:250 offset1:251
	s_waitcnt lgkmcnt(0)
	v_mfma_f32_32x32x16_bf16 v[32:47], v[116:119], v[48:51], v[32:47]
	ds_read_b64_tr_b16 v[72:73], v231
	ds_read_b64_tr_b16 v[74:75], v231 offset:512
	ds_read_b64_tr_b16 v[76:77], v231 offset:2048
	ds_read_b64_tr_b16 v[78:79], v231 offset:2560
	ds_read_b64_tr_b16 v[220:221], v231 offset:1024
	ds_read_b64_tr_b16 v[222:223], v231 offset:1536
	ds_read_b64_tr_b16 v[224:225], v231 offset:3072
	ds_read_b64_tr_b16 v[226:227], v231 offset:3584
	v_mfma_f32_32x32x16_bf16 v[32:47], v[120:123], v[52:55], v[32:47]
	v_mfma_f32_32x32x16_bf16 v[32:47], v[124:127], v[56:59], v[32:47]
	v_mfma_f32_32x32x16_bf16 v[32:47], v[128:131], v[60:63], v[32:47]
	s_nop 11
	v_exp_f32_e32 v32, v32
	v_exp_f32_e32 v33, v33
	v_exp_f32_e32 v34, v34
	v_exp_f32_e32 v35, v35
	v_exp_f32_e32 v36, v36
	v_exp_f32_e32 v37, v37
	v_exp_f32_e32 v38, v38
	v_exp_f32_e32 v39, v39
	v_exp_f32_e32 v40, v40
	v_exp_f32_e32 v41, v41
	v_exp_f32_e32 v42, v42
	v_exp_f32_e32 v43, v43
	v_exp_f32_e32 v44, v44
	v_exp_f32_e32 v45, v45
	v_exp_f32_e32 v46, v46
	v_exp_f32_e32 v47, v47
	v_cvt_pk_bf16_f32 v64, v32, v33
	v_cvt_pk_bf16_f32 v65, v34, v35
	v_cvt_pk_bf16_f32 v66, v36, v37
	v_cvt_pk_bf16_f32 v67, v38, v39
	v_cvt_pk_bf16_f32 v68, v40, v41
	v_cvt_pk_bf16_f32 v69, v42, v43
	v_cvt_pk_bf16_f32 v70, v44, v45
	v_cvt_pk_bf16_f32 v71, v46, v47
	v_pk_add_f32 v[232:233], v[232:233], v[32:33]
	v_pk_add_f32 v[232:233], v[232:233], v[34:35]
	v_pk_add_f32 v[232:233], v[232:233], v[36:37]
	v_pk_add_f32 v[232:233], v[232:233], v[38:39]
	v_pk_add_f32 v[232:233], v[232:233], v[40:41]
	v_pk_add_f32 v[232:233], v[232:233], v[42:43]
	v_pk_add_f32 v[232:233], v[232:233], v[44:45]
	v_pk_add_f32 v[232:233], v[232:233], v[46:47]
	s_waitcnt lgkmcnt(0)
	v_mfma_f32_32x32x16_bf16 v[0:15], v[64:67], v[72:75], v[0:15]
	v_mfma_f32_32x32x16_bf16 v[16:31], v[64:67], v[76:79], v[16:31]
	v_mfma_f32_32x32x16_bf16 v[0:15], v[68:71], v[220:223], v[0:15]
	v_mfma_f32_32x32x16_bf16 v[16:31], v[68:71], v[224:227], v[16:31]
	global_load_dwordx4 v[116:119], v80, s[84:85]
	global_load_dwordx4 v[120:123], v80, s[84:85] offset:32
	global_load_dwordx4 v[124:127], v80, s[84:85] offset:64
	global_load_dwordx4 v[128:131], v80, s[84:85] offset:96
	global_load_dwordx4 v[132:135], v100, s[84:85] offset:768
	global_load_dwordx4 v[136:139], v149, s[84:85] offset:768
	global_load_dwordx4 v[140:143], v100, s[84:85] offset:832
	global_load_dwordx4 v[144:147], v149, s[84:85] offset:832
	s_add_u32 s84, s84, 0x30000
	s_addc_u32 s85, s85, 0
	s_waitcnt vmcnt(16)
	ds_write_b128 v112, v[172:175]
	ds_write_b128 v112, v[176:179] offset:1024
	ds_write_b128 v112, v[180:183] offset:2048
	ds_write_b128 v112, v[184:187] offset:3072
	v_add_u32_e32 v115, 0x400, v115
	ds_read2_b32 v[32:33], v115 offset0:0 offset1:1
	ds_read2_b32 v[34:35], v115 offset0:2 offset1:3
	ds_read2_b32 v[36:37], v115 offset0:8 offset1:9
	ds_read2_b32 v[38:39], v115 offset0:10 offset1:11
	ds_read2_b32 v[40:41], v115 offset0:16 offset1:17
	ds_read2_b32 v[42:43], v115 offset0:18 offset1:19
	ds_read2_b32 v[44:45], v115 offset0:24 offset1:25
	ds_read2_b32 v[46:47], v115 offset0:26 offset1:27
	s_waitcnt lgkmcnt(0)
	v_mfma_f32_32x32x16_bf16 v[32:47], v[156:159], v[48:51], v[32:47]
	ds_read_b64_tr_b16 v[72:73], v231
	ds_read_b64_tr_b16 v[74:75], v231 offset:512
	ds_read_b64_tr_b16 v[76:77], v231 offset:2048
	ds_read_b64_tr_b16 v[78:79], v231 offset:2560
	ds_read_b64_tr_b16 v[220:221], v231 offset:1024
	ds_read_b64_tr_b16 v[222:223], v231 offset:1536
	ds_read_b64_tr_b16 v[224:225], v231 offset:3072
	ds_read_b64_tr_b16 v[226:227], v231 offset:3584
	v_mfma_f32_32x32x16_bf16 v[32:47], v[160:163], v[52:55], v[32:47]
	v_mfma_f32_32x32x16_bf16 v[32:47], v[164:167], v[56:59], v[32:47]
	v_mfma_f32_32x32x16_bf16 v[32:47], v[168:171], v[60:63], v[32:47]
	s_nop 11
	v_exp_f32_e32 v32, v32
	v_exp_f32_e32 v33, v33
	v_exp_f32_e32 v34, v34
	v_exp_f32_e32 v35, v35
	v_exp_f32_e32 v36, v36
	v_exp_f32_e32 v37, v37
	v_exp_f32_e32 v38, v38
	v_exp_f32_e32 v39, v39
	v_exp_f32_e32 v40, v40
	v_exp_f32_e32 v41, v41
	v_exp_f32_e32 v42, v42
	v_exp_f32_e32 v43, v43
	v_exp_f32_e32 v44, v44
	v_exp_f32_e32 v45, v45
	v_exp_f32_e32 v46, v46
	v_exp_f32_e32 v47, v47
	v_cvt_pk_bf16_f32 v64, v32, v33
	v_cvt_pk_bf16_f32 v65, v34, v35
	v_cvt_pk_bf16_f32 v66, v36, v37
	v_cvt_pk_bf16_f32 v67, v38, v39
	v_cvt_pk_bf16_f32 v68, v40, v41
	v_cvt_pk_bf16_f32 v69, v42, v43
	v_cvt_pk_bf16_f32 v70, v44, v45
	v_cvt_pk_bf16_f32 v71, v46, v47
	v_pk_add_f32 v[232:233], v[232:233], v[32:33]
	v_pk_add_f32 v[232:233], v[232:233], v[34:35]
	v_pk_add_f32 v[232:233], v[232:233], v[36:37]
	v_pk_add_f32 v[232:233], v[232:233], v[38:39]
	v_pk_add_f32 v[232:233], v[232:233], v[40:41]
	v_pk_add_f32 v[232:233], v[232:233], v[42:43]
	v_pk_add_f32 v[232:233], v[232:233], v[44:45]
	v_pk_add_f32 v[232:233], v[232:233], v[46:47]
	s_waitcnt lgkmcnt(0)
	v_mfma_f32_32x32x16_bf16 v[0:15], v[64:67], v[72:75], v[0:15]
	v_mfma_f32_32x32x16_bf16 v[16:31], v[64:67], v[76:79], v[16:31]
	v_mfma_f32_32x32x16_bf16 v[0:15], v[68:71], v[220:223], v[0:15]
	v_mfma_f32_32x32x16_bf16 v[16:31], v[68:71], v[224:227], v[16:31]
	global_load_dwordx4 v[156:159], v80, s[84:85]
	global_load_dwordx4 v[160:163], v80, s[84:85] offset:32
	global_load_dwordx4 v[164:167], v80, s[84:85] offset:64
	global_load_dwordx4 v[168:171], v80, s[84:85] offset:96
	global_load_dwordx4 v[172:175], v100, s[84:85] offset:768
	global_load_dwordx4 v[176:179], v149, s[84:85] offset:768
	global_load_dwordx4 v[180:183], v100, s[84:85] offset:832
	global_load_dwordx4 v[184:187], v149, s[84:85] offset:832
	s_waitcnt vmcnt(16)
	ds_write_b128 v112, v[204:207]
	ds_write_b128 v112, v[208:211] offset:1024
	ds_write_b128 v112, v[212:215] offset:2048
	ds_write_b128 v112, v[216:219] offset:3072
	ds_read2_b32 v[32:33], v115 offset0:32 offset1:33
	ds_read2_b32 v[34:35], v115 offset0:34 offset1:35
	ds_read2_b32 v[36:37], v115 offset0:40 offset1:41
	ds_read2_b32 v[38:39], v115 offset0:42 offset1:43
	ds_read2_b32 v[40:41], v115 offset0:48 offset1:49
	ds_read2_b32 v[42:43], v115 offset0:50 offset1:51
	ds_read2_b32 v[44:45], v115 offset0:56 offset1:57
	ds_read2_b32 v[46:47], v115 offset0:58 offset1:59
	s_waitcnt lgkmcnt(0)
	v_mfma_f32_32x32x16_bf16 v[32:47], v[188:191], v[48:51], v[32:47]
	ds_read_b64_tr_b16 v[72:73], v231
	ds_read_b64_tr_b16 v[74:75], v231 offset:512
	ds_read_b64_tr_b16 v[76:77], v231 offset:2048
	ds_read_b64_tr_b16 v[78:79], v231 offset:2560
	ds_read_b64_tr_b16 v[220:221], v231 offset:1024
	ds_read_b64_tr_b16 v[222:223], v231 offset:1536
	ds_read_b64_tr_b16 v[224:225], v231 offset:3072
	ds_read_b64_tr_b16 v[226:227], v231 offset:3584
	v_mfma_f32_32x32x16_bf16 v[32:47], v[192:195], v[52:55], v[32:47]
	v_mfma_f32_32x32x16_bf16 v[32:47], v[196:199], v[56:59], v[32:47]
	v_mfma_f32_32x32x16_bf16 v[32:47], v[200:203], v[60:63], v[32:47]
	s_nop 11
	v_exp_f32_e32 v32, v32
	v_exp_f32_e32 v33, v33
	v_exp_f32_e32 v34, v34
	v_exp_f32_e32 v35, v35
	v_exp_f32_e32 v36, v36
	v_exp_f32_e32 v37, v37
	v_exp_f32_e32 v38, v38
	v_exp_f32_e32 v39, v39
	v_exp_f32_e32 v40, v40
	v_exp_f32_e32 v41, v41
	v_exp_f32_e32 v42, v42
	v_exp_f32_e32 v43, v43
	v_exp_f32_e32 v44, v44
	v_exp_f32_e32 v45, v45
	v_exp_f32_e32 v46, v46
	v_exp_f32_e32 v47, v47
	v_cvt_pk_bf16_f32 v64, v32, v33
	v_cvt_pk_bf16_f32 v65, v34, v35
	v_cvt_pk_bf16_f32 v66, v36, v37
	v_cvt_pk_bf16_f32 v67, v38, v39
	v_cvt_pk_bf16_f32 v68, v40, v41
	v_cvt_pk_bf16_f32 v69, v42, v43
	v_cvt_pk_bf16_f32 v70, v44, v45
	v_cvt_pk_bf16_f32 v71, v46, v47
	v_pk_add_f32 v[232:233], v[232:233], v[32:33]
	v_pk_add_f32 v[232:233], v[232:233], v[34:35]
	v_pk_add_f32 v[232:233], v[232:233], v[36:37]
	v_pk_add_f32 v[232:233], v[232:233], v[38:39]
	v_pk_add_f32 v[232:233], v[232:233], v[40:41]
	v_pk_add_f32 v[232:233], v[232:233], v[42:43]
	v_pk_add_f32 v[232:233], v[232:233], v[44:45]
	v_pk_add_f32 v[232:233], v[232:233], v[46:47]
	s_waitcnt lgkmcnt(0)
	v_mfma_f32_32x32x16_bf16 v[0:15], v[64:67], v[72:75], v[0:15]
	v_mfma_f32_32x32x16_bf16 v[16:31], v[64:67], v[76:79], v[16:31]
	v_mfma_f32_32x32x16_bf16 v[0:15], v[68:71], v[220:223], v[0:15]
	v_mfma_f32_32x32x16_bf16 v[16:31], v[68:71], v[224:227], v[16:31]
	global_load_dwordx4 v[188:191], v83, s[86:87]
	global_load_dwordx4 v[192:195], v83, s[86:87] offset:32
	global_load_dwordx4 v[196:199], v83, s[86:87] offset:64
	global_load_dwordx4 v[200:203], v83, s[86:87] offset:96
	global_load_dwordx4 v[204:207], v101, s[86:87] offset:768
	global_load_dwordx4 v[208:211], v150, s[86:87] offset:768
	global_load_dwordx4 v[212:215], v101, s[86:87] offset:832
	global_load_dwordx4 v[216:219], v150, s[86:87] offset:832
	s_add_u32 s86, s86, 0xc0000
	s_addc_u32 s87, s87, 0
	s_waitcnt vmcnt(16)
	ds_write_b128 v112, v[132:135]
	ds_write_b128 v112, v[136:139] offset:1024
	ds_write_b128 v112, v[140:143] offset:2048
	ds_write_b128 v112, v[144:147] offset:3072
	ds_read2_b32 v[32:33], v115 offset0:64 offset1:65
	ds_read2_b32 v[34:35], v115 offset0:66 offset1:67
	ds_read2_b32 v[36:37], v115 offset0:72 offset1:73
	ds_read2_b32 v[38:39], v115 offset0:74 offset1:75
	ds_read2_b32 v[40:41], v115 offset0:80 offset1:81
	ds_read2_b32 v[42:43], v115 offset0:82 offset1:83
	ds_read2_b32 v[44:45], v115 offset0:88 offset1:89
	ds_read2_b32 v[46:47], v115 offset0:90 offset1:91
	s_waitcnt lgkmcnt(0)
	v_mfma_f32_32x32x16_bf16 v[32:47], v[116:119], v[48:51], v[32:47]
	ds_read_b64_tr_b16 v[72:73], v231
	ds_read_b64_tr_b16 v[74:75], v231 offset:512
	ds_read_b64_tr_b16 v[76:77], v231 offset:2048
	ds_read_b64_tr_b16 v[78:79], v231 offset:2560
	ds_read_b64_tr_b16 v[220:221], v231 offset:1024
	ds_read_b64_tr_b16 v[222:223], v231 offset:1536
	ds_read_b64_tr_b16 v[224:225], v231 offset:3072
	ds_read_b64_tr_b16 v[226:227], v231 offset:3584
	v_mfma_f32_32x32x16_bf16 v[32:47], v[120:123], v[52:55], v[32:47]
	v_mfma_f32_32x32x16_bf16 v[32:47], v[124:127], v[56:59], v[32:47]
	v_mfma_f32_32x32x16_bf16 v[32:47], v[128:131], v[60:63], v[32:47]
	s_nop 11
	v_exp_f32_e32 v32, v32
	v_exp_f32_e32 v33, v33
	v_exp_f32_e32 v34, v34
	v_exp_f32_e32 v35, v35
	v_exp_f32_e32 v36, v36
	v_exp_f32_e32 v37, v37
	v_exp_f32_e32 v38, v38
	v_exp_f32_e32 v39, v39
	v_exp_f32_e32 v40, v40
	v_exp_f32_e32 v41, v41
	v_exp_f32_e32 v42, v42
	v_exp_f32_e32 v43, v43
	v_exp_f32_e32 v44, v44
	v_exp_f32_e32 v45, v45
	v_exp_f32_e32 v46, v46
	v_exp_f32_e32 v47, v47
	v_cvt_pk_bf16_f32 v64, v32, v33
	v_cvt_pk_bf16_f32 v65, v34, v35
	v_cvt_pk_bf16_f32 v66, v36, v37
	v_cvt_pk_bf16_f32 v67, v38, v39
	v_cvt_pk_bf16_f32 v68, v40, v41
	v_cvt_pk_bf16_f32 v69, v42, v43
	v_cvt_pk_bf16_f32 v70, v44, v45
	v_cvt_pk_bf16_f32 v71, v46, v47
	v_pk_add_f32 v[232:233], v[232:233], v[32:33]
	v_pk_add_f32 v[232:233], v[232:233], v[34:35]
	v_pk_add_f32 v[232:233], v[232:233], v[36:37]
	v_pk_add_f32 v[232:233], v[232:233], v[38:39]
	v_pk_add_f32 v[232:233], v[232:233], v[40:41]
	v_pk_add_f32 v[232:233], v[232:233], v[42:43]
	v_pk_add_f32 v[232:233], v[232:233], v[44:45]
	v_pk_add_f32 v[232:233], v[232:233], v[46:47]
	s_waitcnt lgkmcnt(0)
	v_mfma_f32_32x32x16_bf16 v[0:15], v[64:67], v[72:75], v[0:15]
	v_mfma_f32_32x32x16_bf16 v[16:31], v[64:67], v[76:79], v[16:31]
	v_mfma_f32_32x32x16_bf16 v[0:15], v[68:71], v[220:223], v[0:15]
	v_mfma_f32_32x32x16_bf16 v[16:31], v[68:71], v[224:227], v[16:31]
	global_load_dwordx4 v[116:119], v83, s[86:87]
	global_load_dwordx4 v[120:123], v83, s[86:87] offset:32
	global_load_dwordx4 v[124:127], v83, s[86:87] offset:64
	global_load_dwordx4 v[128:131], v83, s[86:87] offset:96
	global_load_dwordx4 v[132:135], v101, s[86:87] offset:768
	global_load_dwordx4 v[136:139], v150, s[86:87] offset:768
	global_load_dwordx4 v[140:143], v101, s[86:87] offset:832
	global_load_dwordx4 v[144:147], v150, s[86:87] offset:832
	s_add_u32 s86, s86, 0xc0000
	s_addc_u32 s87, s87, 0
	s_waitcnt vmcnt(16)
	ds_write_b128 v112, v[172:175]
	ds_write_b128 v112, v[176:179] offset:1024
	ds_write_b128 v112, v[180:183] offset:2048
	ds_write_b128 v112, v[184:187] offset:3072
	ds_read2_b32 v[32:33], v115 offset0:96 offset1:97
	ds_read2_b32 v[34:35], v115 offset0:98 offset1:99
	ds_read2_b32 v[36:37], v115 offset0:104 offset1:105
	ds_read2_b32 v[38:39], v115 offset0:106 offset1:107
	ds_read2_b32 v[40:41], v115 offset0:112 offset1:113
	ds_read2_b32 v[42:43], v115 offset0:114 offset1:115
	ds_read2_b32 v[44:45], v115 offset0:120 offset1:121
	ds_read2_b32 v[46:47], v115 offset0:122 offset1:123
	s_waitcnt lgkmcnt(0)
	v_mfma_f32_32x32x16_bf16 v[32:47], v[156:159], v[48:51], v[32:47]
	ds_read_b64_tr_b16 v[72:73], v231
	ds_read_b64_tr_b16 v[74:75], v231 offset:512
	ds_read_b64_tr_b16 v[76:77], v231 offset:2048
	ds_read_b64_tr_b16 v[78:79], v231 offset:2560
	ds_read_b64_tr_b16 v[220:221], v231 offset:1024
	ds_read_b64_tr_b16 v[222:223], v231 offset:1536
	ds_read_b64_tr_b16 v[224:225], v231 offset:3072
	ds_read_b64_tr_b16 v[226:227], v231 offset:3584
	v_mfma_f32_32x32x16_bf16 v[32:47], v[160:163], v[52:55], v[32:47]
	v_mfma_f32_32x32x16_bf16 v[32:47], v[164:167], v[56:59], v[32:47]
	v_mfma_f32_32x32x16_bf16 v[32:47], v[168:171], v[60:63], v[32:47]
	s_nop 11
	v_exp_f32_e32 v32, v32
	v_exp_f32_e32 v33, v33
	v_exp_f32_e32 v34, v34
	v_exp_f32_e32 v35, v35
	v_exp_f32_e32 v36, v36
	v_exp_f32_e32 v37, v37
	v_exp_f32_e32 v38, v38
	v_exp_f32_e32 v39, v39
	v_exp_f32_e32 v40, v40
	v_exp_f32_e32 v41, v41
	v_exp_f32_e32 v42, v42
	v_exp_f32_e32 v43, v43
	v_exp_f32_e32 v44, v44
	v_exp_f32_e32 v45, v45
	v_exp_f32_e32 v46, v46
	v_exp_f32_e32 v47, v47
	v_cvt_pk_bf16_f32 v64, v32, v33
	v_cvt_pk_bf16_f32 v65, v34, v35
	v_cvt_pk_bf16_f32 v66, v36, v37
	v_cvt_pk_bf16_f32 v67, v38, v39
	v_cvt_pk_bf16_f32 v68, v40, v41
	v_cvt_pk_bf16_f32 v69, v42, v43
	v_cvt_pk_bf16_f32 v70, v44, v45
	v_cvt_pk_bf16_f32 v71, v46, v47
	v_pk_add_f32 v[232:233], v[232:233], v[32:33]
	v_pk_add_f32 v[232:233], v[232:233], v[34:35]
	v_pk_add_f32 v[232:233], v[232:233], v[36:37]
	v_pk_add_f32 v[232:233], v[232:233], v[38:39]
	v_pk_add_f32 v[232:233], v[232:233], v[40:41]
	v_pk_add_f32 v[232:233], v[232:233], v[42:43]
	v_pk_add_f32 v[232:233], v[232:233], v[44:45]
	v_pk_add_f32 v[232:233], v[232:233], v[46:47]
	s_waitcnt lgkmcnt(0)
	v_mfma_f32_32x32x16_bf16 v[0:15], v[64:67], v[72:75], v[0:15]
	v_mfma_f32_32x32x16_bf16 v[16:31], v[64:67], v[76:79], v[16:31]
	v_mfma_f32_32x32x16_bf16 v[0:15], v[68:71], v[220:223], v[0:15]
	v_mfma_f32_32x32x16_bf16 v[16:31], v[68:71], v[224:227], v[16:31]
	global_load_dwordx4 v[156:159], v83, s[86:87]
	global_load_dwordx4 v[160:163], v83, s[86:87] offset:32
	global_load_dwordx4 v[164:167], v83, s[86:87] offset:64
	global_load_dwordx4 v[168:171], v83, s[86:87] offset:96
	global_load_dwordx4 v[172:175], v101, s[86:87] offset:768
	global_load_dwordx4 v[176:179], v150, s[86:87] offset:768
	global_load_dwordx4 v[180:183], v101, s[86:87] offset:832
	global_load_dwordx4 v[184:187], v150, s[86:87] offset:832
	s_add_u32 s86, s86, 0xc0000
	s_addc_u32 s87, s87, 0
	s_waitcnt vmcnt(16)
	ds_write_b128 v112, v[204:207]
	ds_write_b128 v112, v[208:211] offset:1024
	ds_write_b128 v112, v[212:215] offset:2048
	ds_write_b128 v112, v[216:219] offset:3072
	v_mov_b32_e32 v115, v229
	ds_read2_b32 v[32:33], v115 offset0:0 offset1:1
	ds_read2_b32 v[34:35], v115 offset0:2 offset1:3
	ds_read2_b32 v[36:37], v115 offset0:8 offset1:9
	ds_read2_b32 v[38:39], v115 offset0:10 offset1:11
	ds_read2_b32 v[40:41], v115 offset0:16 offset1:17
	ds_read2_b32 v[42:43], v115 offset0:18 offset1:19
	ds_read2_b32 v[44:45], v115 offset0:24 offset1:25
	ds_read2_b32 v[46:47], v115 offset0:26 offset1:27
	s_waitcnt lgkmcnt(0)
	v_mfma_f32_32x32x16_bf16 v[32:47], v[188:191], v[48:51], v[32:47]
	ds_read_b64_tr_b16 v[72:73], v231
	ds_read_b64_tr_b16 v[74:75], v231 offset:512
	ds_read_b64_tr_b16 v[76:77], v231 offset:2048
	ds_read_b64_tr_b16 v[78:79], v231 offset:2560
	ds_read_b64_tr_b16 v[220:221], v231 offset:1024
	ds_read_b64_tr_b16 v[222:223], v231 offset:1536
	ds_read_b64_tr_b16 v[224:225], v231 offset:3072
	ds_read_b64_tr_b16 v[226:227], v231 offset:3584
	v_mfma_f32_32x32x16_bf16 v[32:47], v[192:195], v[52:55], v[32:47]
	v_mfma_f32_32x32x16_bf16 v[32:47], v[196:199], v[56:59], v[32:47]
	v_mfma_f32_32x32x16_bf16 v[32:47], v[200:203], v[60:63], v[32:47]
	s_nop 11
	v_exp_f32_e32 v32, v32
	v_exp_f32_e32 v33, v33
	v_exp_f32_e32 v34, v34
	v_exp_f32_e32 v35, v35
	v_exp_f32_e32 v36, v36
	v_exp_f32_e32 v37, v37
	v_exp_f32_e32 v38, v38
	v_exp_f32_e32 v39, v39
	v_exp_f32_e32 v40, v40
	v_exp_f32_e32 v41, v41
	v_exp_f32_e32 v42, v42
	v_exp_f32_e32 v43, v43
	v_exp_f32_e32 v44, v44
	v_exp_f32_e32 v45, v45
	v_exp_f32_e32 v46, v46
	v_exp_f32_e32 v47, v47
	v_cvt_pk_bf16_f32 v64, v32, v33
	v_cvt_pk_bf16_f32 v65, v34, v35
	v_cvt_pk_bf16_f32 v66, v36, v37
	v_cvt_pk_bf16_f32 v67, v38, v39
	v_cvt_pk_bf16_f32 v68, v40, v41
	v_cvt_pk_bf16_f32 v69, v42, v43
	v_cvt_pk_bf16_f32 v70, v44, v45
	v_cvt_pk_bf16_f32 v71, v46, v47
	v_pk_add_f32 v[232:233], v[232:233], v[32:33]
	v_pk_add_f32 v[232:233], v[232:233], v[34:35]
	v_pk_add_f32 v[232:233], v[232:233], v[36:37]
	v_pk_add_f32 v[232:233], v[232:233], v[38:39]
	v_pk_add_f32 v[232:233], v[232:233], v[40:41]
	v_pk_add_f32 v[232:233], v[232:233], v[42:43]
	v_pk_add_f32 v[232:233], v[232:233], v[44:45]
	v_pk_add_f32 v[232:233], v[232:233], v[46:47]
	s_waitcnt lgkmcnt(0)
	v_mfma_f32_32x32x16_bf16 v[0:15], v[64:67], v[72:75], v[0:15]
	v_mfma_f32_32x32x16_bf16 v[16:31], v[64:67], v[76:79], v[16:31]
	v_mfma_f32_32x32x16_bf16 v[0:15], v[68:71], v[220:223], v[0:15]
	v_mfma_f32_32x32x16_bf16 v[16:31], v[68:71], v[224:227], v[16:31]
	global_load_dwordx4 v[188:191], v83, s[86:87]
	global_load_dwordx4 v[192:195], v83, s[86:87] offset:32
	global_load_dwordx4 v[196:199], v83, s[86:87] offset:64
	global_load_dwordx4 v[200:203], v83, s[86:87] offset:96
	global_load_dwordx4 v[204:207], v101, s[86:87] offset:768
	global_load_dwordx4 v[208:211], v150, s[86:87] offset:768
	global_load_dwordx4 v[212:215], v101, s[86:87] offset:832
	global_load_dwordx4 v[216:219], v150, s[86:87] offset:832
	s_add_u32 s86, s86, 0xc0000
	s_addc_u32 s87, s87, 0
	s_waitcnt vmcnt(16)
	ds_write_b128 v112, v[132:135]
	ds_write_b128 v112, v[136:139] offset:1024
	ds_write_b128 v112, v[140:143] offset:2048
	ds_write_b128 v112, v[144:147] offset:3072
	ds_read2_b32 v[32:33], v115 offset0:32 offset1:33
	ds_read2_b32 v[34:35], v115 offset0:34 offset1:35
	ds_read2_b32 v[36:37], v115 offset0:40 offset1:41
	ds_read2_b32 v[38:39], v115 offset0:42 offset1:43
	ds_read2_b32 v[40:41], v115 offset0:48 offset1:49
	ds_read2_b32 v[42:43], v115 offset0:50 offset1:51
	ds_read2_b32 v[44:45], v115 offset0:56 offset1:57
	ds_read2_b32 v[46:47], v115 offset0:58 offset1:59
	s_waitcnt lgkmcnt(0)
	v_mfma_f32_32x32x16_bf16 v[32:47], v[116:119], v[48:51], v[32:47]
	ds_read_b64_tr_b16 v[72:73], v231
	ds_read_b64_tr_b16 v[74:75], v231 offset:512
	ds_read_b64_tr_b16 v[76:77], v231 offset:2048
	ds_read_b64_tr_b16 v[78:79], v231 offset:2560
	ds_read_b64_tr_b16 v[220:221], v231 offset:1024
	ds_read_b64_tr_b16 v[222:223], v231 offset:1536
	ds_read_b64_tr_b16 v[224:225], v231 offset:3072
	ds_read_b64_tr_b16 v[226:227], v231 offset:3584
	v_mfma_f32_32x32x16_bf16 v[32:47], v[120:123], v[52:55], v[32:47]
	v_mfma_f32_32x32x16_bf16 v[32:47], v[124:127], v[56:59], v[32:47]
	v_mfma_f32_32x32x16_bf16 v[32:47], v[128:131], v[60:63], v[32:47]
	s_nop 11
	v_exp_f32_e32 v32, v32
	v_exp_f32_e32 v33, v33
	v_exp_f32_e32 v34, v34
	v_exp_f32_e32 v35, v35
	v_exp_f32_e32 v36, v36
	v_exp_f32_e32 v37, v37
	v_exp_f32_e32 v38, v38
	v_exp_f32_e32 v39, v39
	v_exp_f32_e32 v40, v40
	v_exp_f32_e32 v41, v41
	v_exp_f32_e32 v42, v42
	v_exp_f32_e32 v43, v43
	v_exp_f32_e32 v44, v44
	v_exp_f32_e32 v45, v45
	v_exp_f32_e32 v46, v46
	v_exp_f32_e32 v47, v47
	v_cvt_pk_bf16_f32 v64, v32, v33
	v_cvt_pk_bf16_f32 v65, v34, v35
	v_cvt_pk_bf16_f32 v66, v36, v37
	v_cvt_pk_bf16_f32 v67, v38, v39
	v_cvt_pk_bf16_f32 v68, v40, v41
	v_cvt_pk_bf16_f32 v69, v42, v43
	v_cvt_pk_bf16_f32 v70, v44, v45
	v_cvt_pk_bf16_f32 v71, v46, v47
	v_pk_add_f32 v[232:233], v[232:233], v[32:33]
	v_pk_add_f32 v[232:233], v[232:233], v[34:35]
	v_pk_add_f32 v[232:233], v[232:233], v[36:37]
	v_pk_add_f32 v[232:233], v[232:233], v[38:39]
	v_pk_add_f32 v[232:233], v[232:233], v[40:41]
	v_pk_add_f32 v[232:233], v[232:233], v[42:43]
	v_pk_add_f32 v[232:233], v[232:233], v[44:45]
	v_pk_add_f32 v[232:233], v[232:233], v[46:47]
	s_waitcnt lgkmcnt(0)
	v_mfma_f32_32x32x16_bf16 v[0:15], v[64:67], v[72:75], v[0:15]
	v_mfma_f32_32x32x16_bf16 v[16:31], v[64:67], v[76:79], v[16:31]
	v_mfma_f32_32x32x16_bf16 v[0:15], v[68:71], v[220:223], v[0:15]
	v_mfma_f32_32x32x16_bf16 v[16:31], v[68:71], v[224:227], v[16:31]
	global_load_dwordx4 v[116:119], v83, s[86:87]
	global_load_dwordx4 v[120:123], v83, s[86:87] offset:32
	global_load_dwordx4 v[124:127], v83, s[86:87] offset:64
	global_load_dwordx4 v[128:131], v83, s[86:87] offset:96
	global_load_dwordx4 v[132:135], v101, s[86:87] offset:768
	global_load_dwordx4 v[136:139], v150, s[86:87] offset:768
	global_load_dwordx4 v[140:143], v101, s[86:87] offset:832
	global_load_dwordx4 v[144:147], v150, s[86:87] offset:832
	s_add_u32 s86, s86, 0xc0000
	s_addc_u32 s87, s87, 0
	s_waitcnt vmcnt(16)
	ds_write_b128 v112, v[172:175]
	ds_write_b128 v112, v[176:179] offset:1024
	ds_write_b128 v112, v[180:183] offset:2048
	ds_write_b128 v112, v[184:187] offset:3072
	ds_read2_b32 v[32:33], v115 offset0:64 offset1:65
	ds_read2_b32 v[34:35], v115 offset0:66 offset1:67
	ds_read2_b32 v[36:37], v115 offset0:72 offset1:73
	ds_read2_b32 v[38:39], v115 offset0:74 offset1:75
	ds_read2_b32 v[40:41], v115 offset0:80 offset1:81
	ds_read2_b32 v[42:43], v115 offset0:82 offset1:83
	ds_read2_b32 v[44:45], v115 offset0:88 offset1:89
	ds_read2_b32 v[46:47], v115 offset0:90 offset1:91
	s_waitcnt lgkmcnt(0)
	v_mfma_f32_32x32x16_bf16 v[32:47], v[156:159], v[48:51], v[32:47]
	ds_read_b64_tr_b16 v[72:73], v231
	ds_read_b64_tr_b16 v[74:75], v231 offset:512
	ds_read_b64_tr_b16 v[76:77], v231 offset:2048
	ds_read_b64_tr_b16 v[78:79], v231 offset:2560
	ds_read_b64_tr_b16 v[220:221], v231 offset:1024
	ds_read_b64_tr_b16 v[222:223], v231 offset:1536
	ds_read_b64_tr_b16 v[224:225], v231 offset:3072
	ds_read_b64_tr_b16 v[226:227], v231 offset:3584
	v_mfma_f32_32x32x16_bf16 v[32:47], v[160:163], v[52:55], v[32:47]
	v_mfma_f32_32x32x16_bf16 v[32:47], v[164:167], v[56:59], v[32:47]
	v_mfma_f32_32x32x16_bf16 v[32:47], v[168:171], v[60:63], v[32:47]
	s_nop 11
	v_exp_f32_e32 v32, v32
	v_exp_f32_e32 v33, v33
	v_exp_f32_e32 v34, v34
	v_exp_f32_e32 v35, v35
	v_exp_f32_e32 v36, v36
	v_exp_f32_e32 v37, v37
	v_exp_f32_e32 v38, v38
	v_exp_f32_e32 v39, v39
	v_exp_f32_e32 v40, v40
	v_exp_f32_e32 v41, v41
	v_exp_f32_e32 v42, v42
	v_exp_f32_e32 v43, v43
	v_exp_f32_e32 v44, v44
	v_exp_f32_e32 v45, v45
	v_exp_f32_e32 v46, v46
	v_exp_f32_e32 v47, v47
	v_cvt_pk_bf16_f32 v64, v32, v33
	v_cvt_pk_bf16_f32 v65, v34, v35
	v_cvt_pk_bf16_f32 v66, v36, v37
	v_cvt_pk_bf16_f32 v67, v38, v39
	v_cvt_pk_bf16_f32 v68, v40, v41
	v_cvt_pk_bf16_f32 v69, v42, v43
	v_cvt_pk_bf16_f32 v70, v44, v45
	v_cvt_pk_bf16_f32 v71, v46, v47
	v_pk_add_f32 v[232:233], v[232:233], v[32:33]
	v_pk_add_f32 v[232:233], v[232:233], v[34:35]
	v_pk_add_f32 v[232:233], v[232:233], v[36:37]
	v_pk_add_f32 v[232:233], v[232:233], v[38:39]
	v_pk_add_f32 v[232:233], v[232:233], v[40:41]
	v_pk_add_f32 v[232:233], v[232:233], v[42:43]
	v_pk_add_f32 v[232:233], v[232:233], v[44:45]
	v_pk_add_f32 v[232:233], v[232:233], v[46:47]
	s_waitcnt lgkmcnt(0)
	v_mfma_f32_32x32x16_bf16 v[0:15], v[64:67], v[72:75], v[0:15]
	v_mfma_f32_32x32x16_bf16 v[16:31], v[64:67], v[76:79], v[16:31]
	v_mfma_f32_32x32x16_bf16 v[0:15], v[68:71], v[220:223], v[0:15]
	v_mfma_f32_32x32x16_bf16 v[16:31], v[68:71], v[224:227], v[16:31]
	global_load_dwordx4 v[156:159], v83, s[86:87]
	global_load_dwordx4 v[160:163], v83, s[86:87] offset:32
	global_load_dwordx4 v[164:167], v83, s[86:87] offset:64
	global_load_dwordx4 v[168:171], v83, s[86:87] offset:96
	global_load_dwordx4 v[172:175], v101, s[86:87] offset:768
	global_load_dwordx4 v[176:179], v150, s[86:87] offset:768
	global_load_dwordx4 v[180:183], v101, s[86:87] offset:832
	global_load_dwordx4 v[184:187], v150, s[86:87] offset:832
	s_add_u32 s86, s86, 0xc0000
	s_addc_u32 s87, s87, 0
	s_waitcnt vmcnt(16)
	ds_write_b128 v112, v[204:207]
	ds_write_b128 v112, v[208:211] offset:1024
	ds_write_b128 v112, v[212:215] offset:2048
	ds_write_b128 v112, v[216:219] offset:3072
	ds_read2_b32 v[32:33], v115 offset0:96 offset1:97
	ds_read2_b32 v[34:35], v115 offset0:98 offset1:99
	ds_read2_b32 v[36:37], v115 offset0:104 offset1:105
	ds_read2_b32 v[38:39], v115 offset0:106 offset1:107
	ds_read2_b32 v[40:41], v115 offset0:112 offset1:113
	ds_read2_b32 v[42:43], v115 offset0:114 offset1:115
	ds_read2_b32 v[44:45], v115 offset0:120 offset1:121
	ds_read2_b32 v[46:47], v115 offset0:122 offset1:123
	s_waitcnt lgkmcnt(0)
	v_mfma_f32_32x32x16_bf16 v[32:47], v[188:191], v[48:51], v[32:47]
	ds_read_b64_tr_b16 v[72:73], v231
	ds_read_b64_tr_b16 v[74:75], v231 offset:512
	ds_read_b64_tr_b16 v[76:77], v231 offset:2048
	ds_read_b64_tr_b16 v[78:79], v231 offset:2560
	ds_read_b64_tr_b16 v[220:221], v231 offset:1024
	ds_read_b64_tr_b16 v[222:223], v231 offset:1536
	ds_read_b64_tr_b16 v[224:225], v231 offset:3072
	ds_read_b64_tr_b16 v[226:227], v231 offset:3584
	v_mfma_f32_32x32x16_bf16 v[32:47], v[192:195], v[52:55], v[32:47]
	v_mfma_f32_32x32x16_bf16 v[32:47], v[196:199], v[56:59], v[32:47]
	v_mfma_f32_32x32x16_bf16 v[32:47], v[200:203], v[60:63], v[32:47]
	s_nop 11
	v_exp_f32_e32 v32, v32
	v_exp_f32_e32 v33, v33
	v_exp_f32_e32 v34, v34
	v_exp_f32_e32 v35, v35
	v_exp_f32_e32 v36, v36
	v_exp_f32_e32 v37, v37
	v_exp_f32_e32 v38, v38
	v_exp_f32_e32 v39, v39
	v_exp_f32_e32 v40, v40
	v_exp_f32_e32 v41, v41
	v_exp_f32_e32 v42, v42
	v_exp_f32_e32 v43, v43
	v_exp_f32_e32 v44, v44
	v_exp_f32_e32 v45, v45
	v_exp_f32_e32 v46, v46
	v_exp_f32_e32 v47, v47
	v_cvt_pk_bf16_f32 v64, v32, v33
	v_cvt_pk_bf16_f32 v65, v34, v35
	v_cvt_pk_bf16_f32 v66, v36, v37
	v_cvt_pk_bf16_f32 v67, v38, v39
	v_cvt_pk_bf16_f32 v68, v40, v41
	v_cvt_pk_bf16_f32 v69, v42, v43
	v_cvt_pk_bf16_f32 v70, v44, v45
	v_cvt_pk_bf16_f32 v71, v46, v47
	v_pk_add_f32 v[232:233], v[232:233], v[32:33]
	v_pk_add_f32 v[232:233], v[232:233], v[34:35]
	v_pk_add_f32 v[232:233], v[232:233], v[36:37]
	v_pk_add_f32 v[232:233], v[232:233], v[38:39]
	v_pk_add_f32 v[232:233], v[232:233], v[40:41]
	v_pk_add_f32 v[232:233], v[232:233], v[42:43]
	v_pk_add_f32 v[232:233], v[232:233], v[44:45]
	v_pk_add_f32 v[232:233], v[232:233], v[46:47]
	s_waitcnt lgkmcnt(0)
	v_mfma_f32_32x32x16_bf16 v[0:15], v[64:67], v[72:75], v[0:15]
	v_mfma_f32_32x32x16_bf16 v[16:31], v[64:67], v[76:79], v[16:31]
	v_mfma_f32_32x32x16_bf16 v[0:15], v[68:71], v[220:223], v[0:15]
	v_mfma_f32_32x32x16_bf16 v[16:31], v[68:71], v[224:227], v[16:31]
	global_load_dwordx4 v[188:191], v83, s[86:87]
	global_load_dwordx4 v[192:195], v83, s[86:87] offset:32
	global_load_dwordx4 v[196:199], v83, s[86:87] offset:64
	global_load_dwordx4 v[200:203], v83, s[86:87] offset:96
	global_load_dwordx4 v[204:207], v101, s[86:87] offset:768
	global_load_dwordx4 v[208:211], v150, s[86:87] offset:768
	global_load_dwordx4 v[212:215], v101, s[86:87] offset:832
	global_load_dwordx4 v[216:219], v150, s[86:87] offset:832
	s_add_u32 s86, s86, 0xc0000
	s_addc_u32 s87, s87, 0
	s_waitcnt vmcnt(16)
	ds_write_b128 v112, v[132:135]
	ds_write_b128 v112, v[136:139] offset:1024
	ds_write_b128 v112, v[140:143] offset:2048
	ds_write_b128 v112, v[144:147] offset:3072
	ds_read2_b32 v[32:33], v115 offset0:128 offset1:129
	ds_read2_b32 v[34:35], v115 offset0:130 offset1:131
	ds_read2_b32 v[36:37], v115 offset0:136 offset1:137
	ds_read2_b32 v[38:39], v115 offset0:138 offset1:139
	ds_read2_b32 v[40:41], v115 offset0:144 offset1:145
	ds_read2_b32 v[42:43], v115 offset0:146 offset1:147
	ds_read2_b32 v[44:45], v115 offset0:152 offset1:153
	ds_read2_b32 v[46:47], v115 offset0:154 offset1:155
	s_waitcnt lgkmcnt(0)
	v_mfma_f32_32x32x16_bf16 v[32:47], v[116:119], v[48:51], v[32:47]
	ds_read_b64_tr_b16 v[72:73], v231
	ds_read_b64_tr_b16 v[74:75], v231 offset:512
	ds_read_b64_tr_b16 v[76:77], v231 offset:2048
	ds_read_b64_tr_b16 v[78:79], v231 offset:2560
	ds_read_b64_tr_b16 v[220:221], v231 offset:1024
	ds_read_b64_tr_b16 v[222:223], v231 offset:1536
	ds_read_b64_tr_b16 v[224:225], v231 offset:3072
	ds_read_b64_tr_b16 v[226:227], v231 offset:3584
	v_mfma_f32_32x32x16_bf16 v[32:47], v[120:123], v[52:55], v[32:47]
	v_mfma_f32_32x32x16_bf16 v[32:47], v[124:127], v[56:59], v[32:47]
	v_mfma_f32_32x32x16_bf16 v[32:47], v[128:131], v[60:63], v[32:47]
	s_nop 11
	v_exp_f32_e32 v32, v32
	v_exp_f32_e32 v33, v33
	v_exp_f32_e32 v34, v34
	v_exp_f32_e32 v35, v35
	v_exp_f32_e32 v36, v36
	v_exp_f32_e32 v37, v37
	v_exp_f32_e32 v38, v38
	v_exp_f32_e32 v39, v39
	v_exp_f32_e32 v40, v40
	v_exp_f32_e32 v41, v41
	v_exp_f32_e32 v42, v42
	v_exp_f32_e32 v43, v43
	v_exp_f32_e32 v44, v44
	v_exp_f32_e32 v45, v45
	v_exp_f32_e32 v46, v46
	v_exp_f32_e32 v47, v47
	v_cvt_pk_bf16_f32 v64, v32, v33
	v_cvt_pk_bf16_f32 v65, v34, v35
	v_cvt_pk_bf16_f32 v66, v36, v37
	v_cvt_pk_bf16_f32 v67, v38, v39
	v_cvt_pk_bf16_f32 v68, v40, v41
	v_cvt_pk_bf16_f32 v69, v42, v43
	v_cvt_pk_bf16_f32 v70, v44, v45
	v_cvt_pk_bf16_f32 v71, v46, v47
	v_pk_add_f32 v[232:233], v[232:233], v[32:33]
	v_pk_add_f32 v[232:233], v[232:233], v[34:35]
	v_pk_add_f32 v[232:233], v[232:233], v[36:37]
	v_pk_add_f32 v[232:233], v[232:233], v[38:39]
	v_pk_add_f32 v[232:233], v[232:233], v[40:41]
	v_pk_add_f32 v[232:233], v[232:233], v[42:43]
	v_pk_add_f32 v[232:233], v[232:233], v[44:45]
	v_pk_add_f32 v[232:233], v[232:233], v[46:47]
	s_waitcnt lgkmcnt(0)
	v_mfma_f32_32x32x16_bf16 v[0:15], v[64:67], v[72:75], v[0:15]
	v_mfma_f32_32x32x16_bf16 v[16:31], v[64:67], v[76:79], v[16:31]
	v_mfma_f32_32x32x16_bf16 v[0:15], v[68:71], v[220:223], v[0:15]
	v_mfma_f32_32x32x16_bf16 v[16:31], v[68:71], v[224:227], v[16:31]
	global_load_dwordx4 v[116:119], v83, s[86:87]
	global_load_dwordx4 v[120:123], v83, s[86:87] offset:32
	global_load_dwordx4 v[124:127], v83, s[86:87] offset:64
	global_load_dwordx4 v[128:131], v83, s[86:87] offset:96
	global_load_dwordx4 v[132:135], v101, s[86:87] offset:768
	global_load_dwordx4 v[136:139], v150, s[86:87] offset:768
	global_load_dwordx4 v[140:143], v101, s[86:87] offset:832
	global_load_dwordx4 v[144:147], v150, s[86:87] offset:832
	s_waitcnt vmcnt(16)
	ds_write_b128 v112, v[172:175]
	ds_write_b128 v112, v[176:179] offset:1024
	ds_write_b128 v112, v[180:183] offset:2048
	ds_write_b128 v112, v[184:187] offset:3072
	ds_read2_b32 v[32:33], v115 offset0:160 offset1:161
	ds_read2_b32 v[34:35], v115 offset0:162 offset1:163
	ds_read2_b32 v[36:37], v115 offset0:168 offset1:169
	ds_read2_b32 v[38:39], v115 offset0:170 offset1:171
	ds_read2_b32 v[40:41], v115 offset0:176 offset1:177
	ds_read2_b32 v[42:43], v115 offset0:178 offset1:179
	ds_read2_b32 v[44:45], v115 offset0:184 offset1:185
	ds_read2_b32 v[46:47], v115 offset0:186 offset1:187
	s_waitcnt lgkmcnt(0)
	v_mfma_f32_32x32x16_bf16 v[32:47], v[156:159], v[48:51], v[32:47]
	ds_read_b64_tr_b16 v[72:73], v231
	ds_read_b64_tr_b16 v[74:75], v231 offset:512
	ds_read_b64_tr_b16 v[76:77], v231 offset:2048
	ds_read_b64_tr_b16 v[78:79], v231 offset:2560
	ds_read_b64_tr_b16 v[220:221], v231 offset:1024
	ds_read_b64_tr_b16 v[222:223], v231 offset:1536
	ds_read_b64_tr_b16 v[224:225], v231 offset:3072
	ds_read_b64_tr_b16 v[226:227], v231 offset:3584
	v_mfma_f32_32x32x16_bf16 v[32:47], v[160:163], v[52:55], v[32:47]
	v_mfma_f32_32x32x16_bf16 v[32:47], v[164:167], v[56:59], v[32:47]
	v_mfma_f32_32x32x16_bf16 v[32:47], v[168:171], v[60:63], v[32:47]
	s_nop 11
	v_exp_f32_e32 v32, v32
	v_exp_f32_e32 v33, v33
	v_exp_f32_e32 v34, v34
	v_exp_f32_e32 v35, v35
	v_exp_f32_e32 v36, v36
	v_exp_f32_e32 v37, v37
	v_exp_f32_e32 v38, v38
	v_exp_f32_e32 v39, v39
	v_exp_f32_e32 v40, v40
	v_exp_f32_e32 v41, v41
	v_exp_f32_e32 v42, v42
	v_exp_f32_e32 v43, v43
	v_exp_f32_e32 v44, v44
	v_exp_f32_e32 v45, v45
	v_exp_f32_e32 v46, v46
	v_exp_f32_e32 v47, v47
	v_cvt_pk_bf16_f32 v64, v32, v33
	v_cvt_pk_bf16_f32 v65, v34, v35
	v_cvt_pk_bf16_f32 v66, v36, v37
	v_cvt_pk_bf16_f32 v67, v38, v39
	v_cvt_pk_bf16_f32 v68, v40, v41
	v_cvt_pk_bf16_f32 v69, v42, v43
	v_cvt_pk_bf16_f32 v70, v44, v45
	v_cvt_pk_bf16_f32 v71, v46, v47
	v_pk_add_f32 v[232:233], v[232:233], v[32:33]
	v_pk_add_f32 v[232:233], v[232:233], v[34:35]
	v_pk_add_f32 v[232:233], v[232:233], v[36:37]
	v_pk_add_f32 v[232:233], v[232:233], v[38:39]
	v_pk_add_f32 v[232:233], v[232:233], v[40:41]
	v_pk_add_f32 v[232:233], v[232:233], v[42:43]
	v_pk_add_f32 v[232:233], v[232:233], v[44:45]
	v_pk_add_f32 v[232:233], v[232:233], v[46:47]
	s_waitcnt lgkmcnt(0)
	v_mfma_f32_32x32x16_bf16 v[0:15], v[64:67], v[72:75], v[0:15]
	v_mfma_f32_32x32x16_bf16 v[16:31], v[64:67], v[76:79], v[16:31]
	v_mfma_f32_32x32x16_bf16 v[0:15], v[68:71], v[220:223], v[0:15]
	v_mfma_f32_32x32x16_bf16 v[16:31], v[68:71], v[224:227], v[16:31]
	global_load_dwordx4 v[156:159], v99, s[88:89]
	global_load_dwordx4 v[160:163], v99, s[88:89] offset:32
	global_load_dwordx4 v[164:167], v99, s[88:89] offset:64
	global_load_dwordx4 v[168:171], v99, s[88:89] offset:96
	global_load_dwordx4 v[172:175], v148, s[88:89] offset:768
	global_load_dwordx4 v[176:179], v151, s[88:89] offset:768
	global_load_dwordx4 v[180:183], v148, s[88:89] offset:832
	global_load_dwordx4 v[184:187], v151, s[88:89] offset:832
	s_add_u32 s88, s88, 0x300000
	s_addc_u32 s89, s89, 0
	s_waitcnt vmcnt(16)
	ds_write_b128 v112, v[204:207]
	ds_write_b128 v112, v[208:211] offset:1024
	ds_write_b128 v112, v[212:215] offset:2048
	ds_write_b128 v112, v[216:219] offset:3072
	ds_read2_b32 v[32:33], v115 offset0:192 offset1:193
	ds_read2_b32 v[34:35], v115 offset0:194 offset1:195
	ds_read2_b32 v[36:37], v115 offset0:200 offset1:201
	ds_read2_b32 v[38:39], v115 offset0:202 offset1:203
	ds_read2_b32 v[40:41], v115 offset0:208 offset1:209
	ds_read2_b32 v[42:43], v115 offset0:210 offset1:211
	ds_read2_b32 v[44:45], v115 offset0:216 offset1:217
	ds_read2_b32 v[46:47], v115 offset0:218 offset1:219
	s_waitcnt lgkmcnt(0)
	v_mfma_f32_32x32x16_bf16 v[32:47], v[188:191], v[48:51], v[32:47]
	ds_read_b64_tr_b16 v[72:73], v231
	ds_read_b64_tr_b16 v[74:75], v231 offset:512
	ds_read_b64_tr_b16 v[76:77], v231 offset:2048
	ds_read_b64_tr_b16 v[78:79], v231 offset:2560
	ds_read_b64_tr_b16 v[220:221], v231 offset:1024
	ds_read_b64_tr_b16 v[222:223], v231 offset:1536
	ds_read_b64_tr_b16 v[224:225], v231 offset:3072
	ds_read_b64_tr_b16 v[226:227], v231 offset:3584
	v_mfma_f32_32x32x16_bf16 v[32:47], v[192:195], v[52:55], v[32:47]
	v_mfma_f32_32x32x16_bf16 v[32:47], v[196:199], v[56:59], v[32:47]
	v_mfma_f32_32x32x16_bf16 v[32:47], v[200:203], v[60:63], v[32:47]
	s_nop 11
	v_exp_f32_e32 v32, v32
	v_exp_f32_e32 v33, v33
	v_exp_f32_e32 v34, v34
	v_exp_f32_e32 v35, v35
	v_exp_f32_e32 v36, v36
	v_exp_f32_e32 v37, v37
	v_exp_f32_e32 v38, v38
	v_exp_f32_e32 v39, v39
	v_exp_f32_e32 v40, v40
	v_exp_f32_e32 v41, v41
	v_exp_f32_e32 v42, v42
	v_exp_f32_e32 v43, v43
	v_exp_f32_e32 v44, v44
	v_exp_f32_e32 v45, v45
	v_exp_f32_e32 v46, v46
	v_exp_f32_e32 v47, v47
	v_cvt_pk_bf16_f32 v64, v32, v33
	v_cvt_pk_bf16_f32 v65, v34, v35
	v_cvt_pk_bf16_f32 v66, v36, v37
	v_cvt_pk_bf16_f32 v67, v38, v39
	v_cvt_pk_bf16_f32 v68, v40, v41
	v_cvt_pk_bf16_f32 v69, v42, v43
	v_cvt_pk_bf16_f32 v70, v44, v45
	v_cvt_pk_bf16_f32 v71, v46, v47
	v_pk_add_f32 v[232:233], v[232:233], v[32:33]
	v_pk_add_f32 v[232:233], v[232:233], v[34:35]
	v_pk_add_f32 v[232:233], v[232:233], v[36:37]
	v_pk_add_f32 v[232:233], v[232:233], v[38:39]
	v_pk_add_f32 v[232:233], v[232:233], v[40:41]
	v_pk_add_f32 v[232:233], v[232:233], v[42:43]
	v_pk_add_f32 v[232:233], v[232:233], v[44:45]
	v_pk_add_f32 v[232:233], v[232:233], v[46:47]
	s_waitcnt lgkmcnt(0)
	v_mfma_f32_32x32x16_bf16 v[0:15], v[64:67], v[72:75], v[0:15]
	v_mfma_f32_32x32x16_bf16 v[16:31], v[64:67], v[76:79], v[16:31]
	v_mfma_f32_32x32x16_bf16 v[0:15], v[68:71], v[220:223], v[0:15]
	v_mfma_f32_32x32x16_bf16 v[16:31], v[68:71], v[224:227], v[16:31]
	global_load_dwordx4 v[188:191], v99, s[88:89]
	global_load_dwordx4 v[192:195], v99, s[88:89] offset:32
	global_load_dwordx4 v[196:199], v99, s[88:89] offset:64
	global_load_dwordx4 v[200:203], v99, s[88:89] offset:96
	global_load_dwordx4 v[204:207], v148, s[88:89] offset:768
	global_load_dwordx4 v[208:211], v151, s[88:89] offset:768
	global_load_dwordx4 v[212:215], v148, s[88:89] offset:832
	global_load_dwordx4 v[216:219], v151, s[88:89] offset:832
	s_add_u32 s88, s88, 0x300000
	s_addc_u32 s89, s89, 0
	s_waitcnt vmcnt(16)
	ds_write_b128 v112, v[132:135]
	ds_write_b128 v112, v[136:139] offset:1024
	ds_write_b128 v112, v[140:143] offset:2048
	ds_write_b128 v112, v[144:147] offset:3072
	ds_read2_b32 v[32:33], v115 offset0:224 offset1:225
	ds_read2_b32 v[34:35], v115 offset0:226 offset1:227
	ds_read2_b32 v[36:37], v115 offset0:232 offset1:233
	ds_read2_b32 v[38:39], v115 offset0:234 offset1:235
	ds_read2_b32 v[40:41], v115 offset0:240 offset1:241
	ds_read2_b32 v[42:43], v115 offset0:242 offset1:243
	ds_read2_b32 v[44:45], v115 offset0:248 offset1:249
	ds_read2_b32 v[46:47], v115 offset0:250 offset1:251
	s_waitcnt lgkmcnt(0)
	v_mfma_f32_32x32x16_bf16 v[32:47], v[116:119], v[48:51], v[32:47]
	ds_read_b64_tr_b16 v[72:73], v231
	ds_read_b64_tr_b16 v[74:75], v231 offset:512
	ds_read_b64_tr_b16 v[76:77], v231 offset:2048
	ds_read_b64_tr_b16 v[78:79], v231 offset:2560
	ds_read_b64_tr_b16 v[220:221], v231 offset:1024
	ds_read_b64_tr_b16 v[222:223], v231 offset:1536
	ds_read_b64_tr_b16 v[224:225], v231 offset:3072
	ds_read_b64_tr_b16 v[226:227], v231 offset:3584
	v_mfma_f32_32x32x16_bf16 v[32:47], v[120:123], v[52:55], v[32:47]
	v_mfma_f32_32x32x16_bf16 v[32:47], v[124:127], v[56:59], v[32:47]
	v_mfma_f32_32x32x16_bf16 v[32:47], v[128:131], v[60:63], v[32:47]
	s_nop 11
	v_exp_f32_e32 v32, v32
	v_exp_f32_e32 v33, v33
	v_exp_f32_e32 v34, v34
	v_exp_f32_e32 v35, v35
	v_exp_f32_e32 v36, v36
	v_exp_f32_e32 v37, v37
	v_exp_f32_e32 v38, v38
	v_exp_f32_e32 v39, v39
	v_exp_f32_e32 v40, v40
	v_exp_f32_e32 v41, v41
	v_exp_f32_e32 v42, v42
	v_exp_f32_e32 v43, v43
	v_exp_f32_e32 v44, v44
	v_exp_f32_e32 v45, v45
	v_exp_f32_e32 v46, v46
	v_exp_f32_e32 v47, v47
	v_cvt_pk_bf16_f32 v64, v32, v33
	v_cvt_pk_bf16_f32 v65, v34, v35
	v_cvt_pk_bf16_f32 v66, v36, v37
	v_cvt_pk_bf16_f32 v67, v38, v39
	v_cvt_pk_bf16_f32 v68, v40, v41
	v_cvt_pk_bf16_f32 v69, v42, v43
	v_cvt_pk_bf16_f32 v70, v44, v45
	v_cvt_pk_bf16_f32 v71, v46, v47
	v_pk_add_f32 v[232:233], v[232:233], v[32:33]
	v_pk_add_f32 v[232:233], v[232:233], v[34:35]
	v_pk_add_f32 v[232:233], v[232:233], v[36:37]
	v_pk_add_f32 v[232:233], v[232:233], v[38:39]
	v_pk_add_f32 v[232:233], v[232:233], v[40:41]
	v_pk_add_f32 v[232:233], v[232:233], v[42:43]
	v_pk_add_f32 v[232:233], v[232:233], v[44:45]
	v_pk_add_f32 v[232:233], v[232:233], v[46:47]
	s_waitcnt lgkmcnt(0)
	v_mfma_f32_32x32x16_bf16 v[0:15], v[64:67], v[72:75], v[0:15]
	v_mfma_f32_32x32x16_bf16 v[16:31], v[64:67], v[76:79], v[16:31]
	v_mfma_f32_32x32x16_bf16 v[0:15], v[68:71], v[220:223], v[0:15]
	v_mfma_f32_32x32x16_bf16 v[16:31], v[68:71], v[224:227], v[16:31]
	global_load_dwordx4 v[116:119], v99, s[88:89]
	global_load_dwordx4 v[120:123], v99, s[88:89] offset:32
	global_load_dwordx4 v[124:127], v99, s[88:89] offset:64
	global_load_dwordx4 v[128:131], v99, s[88:89] offset:96
	global_load_dwordx4 v[132:135], v148, s[88:89] offset:768
	global_load_dwordx4 v[136:139], v151, s[88:89] offset:768
	global_load_dwordx4 v[140:143], v148, s[88:89] offset:832
	global_load_dwordx4 v[144:147], v151, s[88:89] offset:832
	s_add_u32 s88, s88, 0x300000
	s_addc_u32 s89, s89, 0
	s_waitcnt vmcnt(16)
	ds_write_b128 v112, v[172:175]
	ds_write_b128 v112, v[176:179] offset:1024
	ds_write_b128 v112, v[180:183] offset:2048
	ds_write_b128 v112, v[184:187] offset:3072
	v_mov_b32_e32 v115, v230
	ds_read2_b32 v[32:33], v115 offset0:0 offset1:1
	ds_read2_b32 v[34:35], v115 offset0:2 offset1:3
	ds_read2_b32 v[36:37], v115 offset0:8 offset1:9
	ds_read2_b32 v[38:39], v115 offset0:10 offset1:11
	ds_read2_b32 v[40:41], v115 offset0:16 offset1:17
	ds_read2_b32 v[42:43], v115 offset0:18 offset1:19
	ds_read2_b32 v[44:45], v115 offset0:24 offset1:25
	ds_read2_b32 v[46:47], v115 offset0:26 offset1:27
	s_waitcnt lgkmcnt(0)
	v_mfma_f32_32x32x16_bf16 v[32:47], v[156:159], v[48:51], v[32:47]
	ds_read_b64_tr_b16 v[72:73], v231
	ds_read_b64_tr_b16 v[74:75], v231 offset:512
	ds_read_b64_tr_b16 v[76:77], v231 offset:2048
	ds_read_b64_tr_b16 v[78:79], v231 offset:2560
	ds_read_b64_tr_b16 v[220:221], v231 offset:1024
	ds_read_b64_tr_b16 v[222:223], v231 offset:1536
	ds_read_b64_tr_b16 v[224:225], v231 offset:3072
	ds_read_b64_tr_b16 v[226:227], v231 offset:3584
	v_mfma_f32_32x32x16_bf16 v[32:47], v[160:163], v[52:55], v[32:47]
	v_mfma_f32_32x32x16_bf16 v[32:47], v[164:167], v[56:59], v[32:47]
	v_mfma_f32_32x32x16_bf16 v[32:47], v[168:171], v[60:63], v[32:47]
	s_nop 11
	v_exp_f32_e32 v32, v32
	v_exp_f32_e32 v33, v33
	v_exp_f32_e32 v34, v34
	v_exp_f32_e32 v35, v35
	v_exp_f32_e32 v36, v36
	v_exp_f32_e32 v37, v37
	v_exp_f32_e32 v38, v38
	v_exp_f32_e32 v39, v39
	v_exp_f32_e32 v40, v40
	v_exp_f32_e32 v41, v41
	v_exp_f32_e32 v42, v42
	v_exp_f32_e32 v43, v43
	v_exp_f32_e32 v44, v44
	v_exp_f32_e32 v45, v45
	v_exp_f32_e32 v46, v46
	v_exp_f32_e32 v47, v47
	v_cvt_pk_bf16_f32 v64, v32, v33
	v_cvt_pk_bf16_f32 v65, v34, v35
	v_cvt_pk_bf16_f32 v66, v36, v37
	v_cvt_pk_bf16_f32 v67, v38, v39
	v_cvt_pk_bf16_f32 v68, v40, v41
	v_cvt_pk_bf16_f32 v69, v42, v43
	v_cvt_pk_bf16_f32 v70, v44, v45
	v_cvt_pk_bf16_f32 v71, v46, v47
	v_pk_add_f32 v[232:233], v[232:233], v[32:33]
	v_pk_add_f32 v[232:233], v[232:233], v[34:35]
	v_pk_add_f32 v[232:233], v[232:233], v[36:37]
	v_pk_add_f32 v[232:233], v[232:233], v[38:39]
	v_pk_add_f32 v[232:233], v[232:233], v[40:41]
	v_pk_add_f32 v[232:233], v[232:233], v[42:43]
	v_pk_add_f32 v[232:233], v[232:233], v[44:45]
	v_pk_add_f32 v[232:233], v[232:233], v[46:47]
	s_waitcnt lgkmcnt(0)
	v_mfma_f32_32x32x16_bf16 v[0:15], v[64:67], v[72:75], v[0:15]
	v_mfma_f32_32x32x16_bf16 v[16:31], v[64:67], v[76:79], v[16:31]
	v_mfma_f32_32x32x16_bf16 v[0:15], v[68:71], v[220:223], v[0:15]
	v_mfma_f32_32x32x16_bf16 v[16:31], v[68:71], v[224:227], v[16:31]
	global_load_dwordx4 v[156:159], v99, s[88:89]
	global_load_dwordx4 v[160:163], v99, s[88:89] offset:32
	global_load_dwordx4 v[164:167], v99, s[88:89] offset:64
	global_load_dwordx4 v[168:171], v99, s[88:89] offset:96
	global_load_dwordx4 v[172:175], v148, s[88:89] offset:768
	global_load_dwordx4 v[176:179], v151, s[88:89] offset:768
	global_load_dwordx4 v[180:183], v148, s[88:89] offset:832
	global_load_dwordx4 v[184:187], v151, s[88:89] offset:832
	s_add_u32 s88, s88, 0x300000
	s_addc_u32 s89, s89, 0
	s_waitcnt vmcnt(16)
	ds_write_b128 v112, v[204:207]
	ds_write_b128 v112, v[208:211] offset:1024
	ds_write_b128 v112, v[212:215] offset:2048
	ds_write_b128 v112, v[216:219] offset:3072
	ds_read2_b32 v[32:33], v115 offset0:32 offset1:33
	ds_read2_b32 v[34:35], v115 offset0:34 offset1:35
	ds_read2_b32 v[36:37], v115 offset0:40 offset1:41
	ds_read2_b32 v[38:39], v115 offset0:42 offset1:43
	ds_read2_b32 v[40:41], v115 offset0:48 offset1:49
	ds_read2_b32 v[42:43], v115 offset0:50 offset1:51
	ds_read2_b32 v[44:45], v115 offset0:56 offset1:57
	ds_read2_b32 v[46:47], v115 offset0:58 offset1:59
	s_waitcnt lgkmcnt(0)
	v_mfma_f32_32x32x16_bf16 v[32:47], v[188:191], v[48:51], v[32:47]
	ds_read_b64_tr_b16 v[72:73], v231
	ds_read_b64_tr_b16 v[74:75], v231 offset:512
	ds_read_b64_tr_b16 v[76:77], v231 offset:2048
	ds_read_b64_tr_b16 v[78:79], v231 offset:2560
	ds_read_b64_tr_b16 v[220:221], v231 offset:1024
	ds_read_b64_tr_b16 v[222:223], v231 offset:1536
	ds_read_b64_tr_b16 v[224:225], v231 offset:3072
	ds_read_b64_tr_b16 v[226:227], v231 offset:3584
	v_mfma_f32_32x32x16_bf16 v[32:47], v[192:195], v[52:55], v[32:47]
	v_mfma_f32_32x32x16_bf16 v[32:47], v[196:199], v[56:59], v[32:47]
	v_mfma_f32_32x32x16_bf16 v[32:47], v[200:203], v[60:63], v[32:47]
	s_nop 11
	v_exp_f32_e32 v32, v32
	v_exp_f32_e32 v33, v33
	v_exp_f32_e32 v34, v34
	v_exp_f32_e32 v35, v35
	v_exp_f32_e32 v36, v36
	v_exp_f32_e32 v37, v37
	v_exp_f32_e32 v38, v38
	v_exp_f32_e32 v39, v39
	v_exp_f32_e32 v40, v40
	v_exp_f32_e32 v41, v41
	v_exp_f32_e32 v42, v42
	v_exp_f32_e32 v43, v43
	v_exp_f32_e32 v44, v44
	v_exp_f32_e32 v45, v45
	v_exp_f32_e32 v46, v46
	v_exp_f32_e32 v47, v47
	v_cvt_pk_bf16_f32 v64, v32, v33
	v_cvt_pk_bf16_f32 v65, v34, v35
	v_cvt_pk_bf16_f32 v66, v36, v37
	v_cvt_pk_bf16_f32 v67, v38, v39
	v_cvt_pk_bf16_f32 v68, v40, v41
	v_cvt_pk_bf16_f32 v69, v42, v43
	v_cvt_pk_bf16_f32 v70, v44, v45
	v_cvt_pk_bf16_f32 v71, v46, v47
	v_pk_add_f32 v[232:233], v[232:233], v[32:33]
	v_pk_add_f32 v[232:233], v[232:233], v[34:35]
	v_pk_add_f32 v[232:233], v[232:233], v[36:37]
	v_pk_add_f32 v[232:233], v[232:233], v[38:39]
	v_pk_add_f32 v[232:233], v[232:233], v[40:41]
	v_pk_add_f32 v[232:233], v[232:233], v[42:43]
	v_pk_add_f32 v[232:233], v[232:233], v[44:45]
	v_pk_add_f32 v[232:233], v[232:233], v[46:47]
	s_waitcnt lgkmcnt(0)
	v_mfma_f32_32x32x16_bf16 v[0:15], v[64:67], v[72:75], v[0:15]
	v_mfma_f32_32x32x16_bf16 v[16:31], v[64:67], v[76:79], v[16:31]
	v_mfma_f32_32x32x16_bf16 v[0:15], v[68:71], v[220:223], v[0:15]
	v_mfma_f32_32x32x16_bf16 v[16:31], v[68:71], v[224:227], v[16:31]
	global_load_dwordx4 v[188:191], v99, s[88:89]
	global_load_dwordx4 v[192:195], v99, s[88:89] offset:32
	global_load_dwordx4 v[196:199], v99, s[88:89] offset:64
	global_load_dwordx4 v[200:203], v99, s[88:89] offset:96
	global_load_dwordx4 v[204:207], v148, s[88:89] offset:768
	global_load_dwordx4 v[208:211], v151, s[88:89] offset:768
	global_load_dwordx4 v[212:215], v148, s[88:89] offset:832
	global_load_dwordx4 v[216:219], v151, s[88:89] offset:832
	s_waitcnt vmcnt(16)
	ds_write_b128 v112, v[132:135]
	ds_write_b128 v112, v[136:139] offset:1024
	ds_write_b128 v112, v[140:143] offset:2048
	ds_write_b128 v112, v[144:147] offset:3072
	ds_read2_b32 v[32:33], v115 offset0:64 offset1:65
	ds_read2_b32 v[34:35], v115 offset0:66 offset1:67
	ds_read2_b32 v[36:37], v115 offset0:72 offset1:73
	ds_read2_b32 v[38:39], v115 offset0:74 offset1:75
	ds_read2_b32 v[40:41], v115 offset0:80 offset1:81
	ds_read2_b32 v[42:43], v115 offset0:82 offset1:83
	ds_read2_b32 v[44:45], v115 offset0:88 offset1:89
	ds_read2_b32 v[46:47], v115 offset0:90 offset1:91
	s_waitcnt lgkmcnt(0)
	v_mfma_f32_32x32x16_bf16 v[32:47], v[116:119], v[48:51], v[32:47]
	ds_read_b64_tr_b16 v[72:73], v231
	ds_read_b64_tr_b16 v[74:75], v231 offset:512
	ds_read_b64_tr_b16 v[76:77], v231 offset:2048
	ds_read_b64_tr_b16 v[78:79], v231 offset:2560
	ds_read_b64_tr_b16 v[220:221], v231 offset:1024
	ds_read_b64_tr_b16 v[222:223], v231 offset:1536
	ds_read_b64_tr_b16 v[224:225], v231 offset:3072
	ds_read_b64_tr_b16 v[226:227], v231 offset:3584
	v_mfma_f32_32x32x16_bf16 v[32:47], v[120:123], v[52:55], v[32:47]
	v_mfma_f32_32x32x16_bf16 v[32:47], v[124:127], v[56:59], v[32:47]
	v_mfma_f32_32x32x16_bf16 v[32:47], v[128:131], v[60:63], v[32:47]
	s_nop 11
	v_exp_f32_e32 v32, v32
	v_exp_f32_e32 v33, v33
	v_exp_f32_e32 v34, v34
	v_exp_f32_e32 v35, v35
	v_exp_f32_e32 v36, v36
	v_exp_f32_e32 v37, v37
	v_exp_f32_e32 v38, v38
	v_exp_f32_e32 v39, v39
	v_exp_f32_e32 v40, v40
	v_exp_f32_e32 v41, v41
	v_exp_f32_e32 v42, v42
	v_exp_f32_e32 v43, v43
	v_exp_f32_e32 v44, v44
	v_exp_f32_e32 v45, v45
	v_exp_f32_e32 v46, v46
	v_exp_f32_e32 v47, v47
	v_cvt_pk_bf16_f32 v64, v32, v33
	v_cvt_pk_bf16_f32 v65, v34, v35
	v_cvt_pk_bf16_f32 v66, v36, v37
	v_cvt_pk_bf16_f32 v67, v38, v39
	v_cvt_pk_bf16_f32 v68, v40, v41
	v_cvt_pk_bf16_f32 v69, v42, v43
	v_cvt_pk_bf16_f32 v70, v44, v45
	v_cvt_pk_bf16_f32 v71, v46, v47
	v_pk_add_f32 v[232:233], v[232:233], v[32:33]
	v_pk_add_f32 v[232:233], v[232:233], v[34:35]
	v_pk_add_f32 v[232:233], v[232:233], v[36:37]
	v_pk_add_f32 v[232:233], v[232:233], v[38:39]
	v_pk_add_f32 v[232:233], v[232:233], v[40:41]
	v_pk_add_f32 v[232:233], v[232:233], v[42:43]
	v_pk_add_f32 v[232:233], v[232:233], v[44:45]
	v_pk_add_f32 v[232:233], v[232:233], v[46:47]
	s_waitcnt lgkmcnt(0)
	v_mfma_f32_32x32x16_bf16 v[0:15], v[64:67], v[72:75], v[0:15]
	v_mfma_f32_32x32x16_bf16 v[16:31], v[64:67], v[76:79], v[16:31]
	v_mfma_f32_32x32x16_bf16 v[0:15], v[68:71], v[220:223], v[0:15]
	v_mfma_f32_32x32x16_bf16 v[16:31], v[68:71], v[224:227], v[16:31]
	s_waitcnt vmcnt(8)
	ds_write_b128 v112, v[172:175]
	ds_write_b128 v112, v[176:179] offset:1024
	ds_write_b128 v112, v[180:183] offset:2048
	ds_write_b128 v112, v[184:187] offset:3072
	ds_read2_b32 v[32:33], v115 offset0:96 offset1:97
	ds_read2_b32 v[34:35], v115 offset0:98 offset1:99
	ds_read2_b32 v[36:37], v115 offset0:104 offset1:105
	ds_read2_b32 v[38:39], v115 offset0:106 offset1:107
	ds_read2_b32 v[40:41], v115 offset0:112 offset1:113
	ds_read2_b32 v[42:43], v115 offset0:114 offset1:115
	ds_read2_b32 v[44:45], v115 offset0:120 offset1:121
	ds_read2_b32 v[46:47], v115 offset0:122 offset1:123
	s_waitcnt lgkmcnt(0)
	v_mfma_f32_32x32x16_bf16 v[32:47], v[156:159], v[48:51], v[32:47]
	ds_read_b64_tr_b16 v[72:73], v231
	ds_read_b64_tr_b16 v[74:75], v231 offset:512
	ds_read_b64_tr_b16 v[76:77], v231 offset:2048
	ds_read_b64_tr_b16 v[78:79], v231 offset:2560
	ds_read_b64_tr_b16 v[220:221], v231 offset:1024
	ds_read_b64_tr_b16 v[222:223], v231 offset:1536
	ds_read_b64_tr_b16 v[224:225], v231 offset:3072
	ds_read_b64_tr_b16 v[226:227], v231 offset:3584
	v_mfma_f32_32x32x16_bf16 v[32:47], v[160:163], v[52:55], v[32:47]
	v_mfma_f32_32x32x16_bf16 v[32:47], v[164:167], v[56:59], v[32:47]
	v_mfma_f32_32x32x16_bf16 v[32:47], v[168:171], v[60:63], v[32:47]
	s_nop 11
	v_exp_f32_e32 v32, v32
	v_exp_f32_e32 v33, v33
	v_exp_f32_e32 v34, v34
	v_exp_f32_e32 v35, v35
	v_exp_f32_e32 v36, v36
	v_exp_f32_e32 v37, v37
	v_exp_f32_e32 v38, v38
	v_exp_f32_e32 v39, v39
	v_exp_f32_e32 v40, v40
	v_exp_f32_e32 v41, v41
	v_exp_f32_e32 v42, v42
	v_exp_f32_e32 v43, v43
	v_exp_f32_e32 v44, v44
	v_exp_f32_e32 v45, v45
	v_exp_f32_e32 v46, v46
	v_exp_f32_e32 v47, v47
	v_cvt_pk_bf16_f32 v64, v32, v33
	v_cvt_pk_bf16_f32 v65, v34, v35
	v_cvt_pk_bf16_f32 v66, v36, v37
	v_cvt_pk_bf16_f32 v67, v38, v39
	v_cvt_pk_bf16_f32 v68, v40, v41
	v_cvt_pk_bf16_f32 v69, v42, v43
	v_cvt_pk_bf16_f32 v70, v44, v45
	v_cvt_pk_bf16_f32 v71, v46, v47
	v_pk_add_f32 v[232:233], v[232:233], v[32:33]
	v_pk_add_f32 v[232:233], v[232:233], v[34:35]
	v_pk_add_f32 v[232:233], v[232:233], v[36:37]
	v_pk_add_f32 v[232:233], v[232:233], v[38:39]
	v_pk_add_f32 v[232:233], v[232:233], v[40:41]
	v_pk_add_f32 v[232:233], v[232:233], v[42:43]
	v_pk_add_f32 v[232:233], v[232:233], v[44:45]
	v_pk_add_f32 v[232:233], v[232:233], v[46:47]
	s_waitcnt lgkmcnt(0)
	v_mfma_f32_32x32x16_bf16 v[0:15], v[64:67], v[72:75], v[0:15]
	v_mfma_f32_32x32x16_bf16 v[16:31], v[64:67], v[76:79], v[16:31]
	v_mfma_f32_32x32x16_bf16 v[0:15], v[68:71], v[220:223], v[0:15]
	v_mfma_f32_32x32x16_bf16 v[16:31], v[68:71], v[224:227], v[16:31]
	s_waitcnt vmcnt(0)
	ds_write_b128 v112, v[204:207]
	ds_write_b128 v112, v[208:211] offset:1024
	ds_write_b128 v112, v[212:215] offset:2048
	ds_write_b128 v112, v[216:219] offset:3072
	ds_read2_b32 v[32:33], v115 offset0:128 offset1:129
	ds_read2_b32 v[34:35], v115 offset0:130 offset1:131
	ds_read2_b32 v[36:37], v115 offset0:136 offset1:137
	ds_read2_b32 v[38:39], v115 offset0:138 offset1:139
	ds_read2_b32 v[40:41], v115 offset0:144 offset1:145
	ds_read2_b32 v[42:43], v115 offset0:146 offset1:147
	ds_read2_b32 v[44:45], v115 offset0:152 offset1:153
	ds_read2_b32 v[46:47], v115 offset0:154 offset1:155
	s_waitcnt lgkmcnt(0)
	v_mfma_f32_32x32x16_bf16 v[32:47], v[188:191], v[48:51], v[32:47]
	ds_read_b64_tr_b16 v[72:73], v231
	ds_read_b64_tr_b16 v[74:75], v231 offset:512
	ds_read_b64_tr_b16 v[76:77], v231 offset:2048
	ds_read_b64_tr_b16 v[78:79], v231 offset:2560
	ds_read_b64_tr_b16 v[220:221], v231 offset:1024
	ds_read_b64_tr_b16 v[222:223], v231 offset:1536
	ds_read_b64_tr_b16 v[224:225], v231 offset:3072
	ds_read_b64_tr_b16 v[226:227], v231 offset:3584
	v_mfma_f32_32x32x16_bf16 v[32:47], v[192:195], v[52:55], v[32:47]
	v_mfma_f32_32x32x16_bf16 v[32:47], v[196:199], v[56:59], v[32:47]
	v_mfma_f32_32x32x16_bf16 v[32:47], v[200:203], v[60:63], v[32:47]
	s_nop 11
	v_exp_f32_e32 v32, v32
	v_exp_f32_e32 v33, v33
	v_exp_f32_e32 v34, v34
	v_exp_f32_e32 v35, v35
	v_exp_f32_e32 v36, v36
	v_exp_f32_e32 v37, v37
	v_exp_f32_e32 v38, v38
	v_exp_f32_e32 v39, v39
	v_exp_f32_e32 v40, v40
	v_exp_f32_e32 v41, v41
	v_exp_f32_e32 v42, v42
	v_exp_f32_e32 v43, v43
	v_exp_f32_e32 v44, v44
	v_exp_f32_e32 v45, v45
	v_exp_f32_e32 v46, v46
	v_exp_f32_e32 v47, v47
	v_cvt_pk_bf16_f32 v64, v32, v33
	v_cvt_pk_bf16_f32 v65, v34, v35
	v_cvt_pk_bf16_f32 v66, v36, v37
	v_cvt_pk_bf16_f32 v67, v38, v39
	v_cvt_pk_bf16_f32 v68, v40, v41
	v_cvt_pk_bf16_f32 v69, v42, v43
	v_cvt_pk_bf16_f32 v70, v44, v45
	v_cvt_pk_bf16_f32 v71, v46, v47
	v_pk_add_f32 v[232:233], v[232:233], v[32:33]
	v_pk_add_f32 v[232:233], v[232:233], v[34:35]
	v_pk_add_f32 v[232:233], v[232:233], v[36:37]
	v_pk_add_f32 v[232:233], v[232:233], v[38:39]
	v_pk_add_f32 v[232:233], v[232:233], v[40:41]
	v_pk_add_f32 v[232:233], v[232:233], v[42:43]
	v_pk_add_f32 v[232:233], v[232:233], v[44:45]
	v_pk_add_f32 v[232:233], v[232:233], v[46:47]
	s_waitcnt lgkmcnt(0)
	v_mfma_f32_32x32x16_bf16 v[0:15], v[64:67], v[72:75], v[0:15]
	v_mfma_f32_32x32x16_bf16 v[16:31], v[64:67], v[76:79], v[16:31]
	v_mfma_f32_32x32x16_bf16 v[0:15], v[68:71], v[220:223], v[0:15]
	v_mfma_f32_32x32x16_bf16 v[16:31], v[68:71], v[224:227], v[16:31]
	v_add_f32_e32 v113, v232, v233
	v_or_b32_e32 v114, 1, v107
	v_or_b32_e32 v97, 2, v107
	v_or_b32_e32 v96, 3, v107
	v_or_b32_e32 v95, 8, v107
	v_or_b32_e32 v94, 9, v107
	v_or_b32_e32 v93, 10, v107
	v_or_b32_e32 v92, 11, v107
	v_or_b32_e32 v91, 16, v107
	v_or_b32_e32 v90, 17, v107
	v_or_b32_e32 v89, 18, v107
	v_or_b32_e32 v88, 19, v107
	v_or_b32_e32 v87, 24, v107
	v_or_b32_e32 v86, 25, v107
	v_or_b32_e32 v85, 26, v107
	v_or_b32_e32 v84, 27, v107
	s_nop 11
	s_branch .LBB0_553

; #define LAS __attribute__((address_space(3)))
; #define GAS __attribute__((address_space(1)))
; __device__ __forceinline__ void dil_unit(LAS unsigned char* lds, bf16_t* proj, int seq, int hd, int T0, int rho) {
;     int tid_ = threadIdx.x; asm volatile("" : "+v"(tid_));
;     const int tid = tid_, lane = tid & 63, r32 = lane & 31, hi = lane >> 5, wid = __builtin_amdgcn_readfirstlane(tid >> 6);
;     bf16_t* base = proj + (size_t)seq * SEQ * NIN;
;     LAS unsigned char* wbuf = lds + wid * 4096;
;     const LAS unsigned char* vp = wbuf + ((lane >> 4) & 1) * 32 + (lane & 3) * 8 + (4 * hi + ((lane & 15) >> 2)) * 64;
;     const int P0 = T0 + rho;
;     bf16x8 qr[4];
; #pragma unroll
;     for (int ks = 0; ks < 4; ++ks) qr[ks] = *(const GAS bf16x8*)(base + (size_t)(P0 + 16 * r32) * NIN + PC_LQ + hd * 64 + 16 * ks + 8 * hi);
;     f32x16 o0 = {}, o1 = {}; float l = 0.f;
;     const bool bound = (T0 < 1024) || (T0 >= 15360);
; __device__ __forceinline__ void attn_phase(unsigned char* ws, int l, LAS unsigned char* lds, int G) {
;     ...
;     for (int bu = vb; bu < 1152; bu += G) {
;         const int sh = bu >> 6, rem = bu & 63, T0 = (rem >> 1) * 512, rho = (rem & 1) * 8 + wid;
;         dil_unit(lds, proj, sh / 6, sh % 6, T0, rho);
.LBB0_1266:
	s_lshr_b32 s82, s60, 8
	s_mul_i32 s82, s82, 13
	s_add_i32 s82, s82, s60
	s_ashr_i32 s4, s60, 6
	s_mul_hi_i32 s9, s4, 0x2aaaaaab
	s_lshl_b32 s5, s82, 8
	s_lshr_b32 s10, s9, 31
	s_and_b32 s8, s5, 0x3e00
	s_lshl_b32 s5, s82, 3
	s_add_i32 s9, s9, s10
	s_and_b32 s5, s5, 8
	s_mul_i32 s10, s9, 6
	s_add_i32 s5, s5, s61
	s_sub_i32 s10, s4, s10
	s_mul_hi_i32 s4, s9, 0x6000000
	s_mul_i32 s9, s9, 0x6000000
	v_mov_b32_e32 v2, v154
	s_add_u32 s52, s44, s9
	s_addc_u32 s53, s45, s4
	v_and_b32_e32 v105, 31, v2
	s_add_i32 s67, s5, s8
	v_lshl_add_u32 v3, v105, 4, s67
	v_mov_b64_e32 v[0:1], s[52:53]
	s_lshl_b32 s54, s10, 6
	v_bfe_u32 v106, v2, 5, 1
	v_mad_u64_u32 v[0:1], s[4:5], v3, s62, v[0:1]
	s_ashr_i32 s55, s54, 31
	v_lshl_add_u64 v[0:1], s[54:55], 1, v[0:1]
	v_lshlrev_b32_e32 v80, 4, v106
	v_lshl_add_u64 v[0:1], v[0:1], 0, v[80:81]
	global_load_dwordx4 v[48:51], v[0:1], off offset:1280
	global_load_dwordx4 v[52:55], v[0:1], off offset:1312
	global_load_dwordx4 v[56:59], v[0:1], off offset:1344
	global_load_dwordx4 v[60:63], v[0:1], off offset:1376
	v_readfirstlane_b32 s4, v2
	s_lshl_b32 s4, s4, 6
	s_and_b32 s4, s4, 0xfffff000
	v_lshlrev_b32_e32 v0, 1, v2
	v_lshlrev_b32_e32 v104, 3, v2
	v_lshlrev_b32_e32 v107, 2, v106
	v_lshrrev_b32_e32 v1, 2, v2
	v_and_b32_e32 v103, 63, v2
	v_and_b32_e32 v0, 32, v0
	v_and_b32_e32 v98, 24, v104
	v_and_or_b32 v1, v1, 3, v107
	s_add_i32 s69, s4, 0
	v_lshlrev_b32_e32 v108, 6, v1
	v_lshlrev_b32_e32 v1, 3, v106
	v_add3_u32 v109, s69, v0, v98
	s_addk_i32 s8, 0xc400
	v_lshrrev_b32_e32 v110, 2, v103
	v_lshlrev_b32_e32 v0, 4, v103
	s_mov_b64 s[4:5], -1
	s_cmp_gt_u32 s8, 0xffffc7ff
	v_lshlrev_b32_e32 v100, 1, v98
	s_mul_i32 s8, s10, 0x1c00
	v_lshlrev_b32_e32 v82, 1, v1
	v_or_b32_e32 v111, 16, v110
	v_add_u32_e32 v112, s69, v0
	s_cbranch_scc0 .LBB0_1270
	s_movk_i32 s100, 0x1800
	s_add_i32 s101, s8, 0x15c00
	s_lshl_b32 s90, s54, 1
	s_add_u32 s82, s52, s90
	s_addc_u32 s83, s53, 0
	s_add_u32 s82, s82, 0x1200
	s_addc_u32 s83, s83, 0
	s_sub_i32 s90, s67, 64
	s_mul_i32 s90, s90, 0x1800
	s_add_u32 s84, s82, s90
	s_addc_u32 s85, s83, 0
	s_sub_i32 s90, s67, 256
	s_mul_i32 s90, s90, 0x1800
	s_add_u32 s86, s82, s90
	s_addc_u32 s87, s83, 0
	s_sub_i32 s90, s67, 1024
	s_mul_i32 s90, s90, 0x1800
	s_add_u32 s88, s82, s90
	s_addc_u32 s89, s83, 0
	v_lshlrev_b32_e32 v153, 1, v98
	v_mad_u32_u24 v80, v105, s100, v82
	v_mad_u32_u24 v100, v110, s100, v153
	v_add_u32_e32 v149, 0x18000, v100
	v_lshlrev_b32_e32 v83, 2, v105
	v_mad_u32_u24 v83, v83, s100, v82
	v_lshlrev_b32_e32 v101, 2, v110
	v_mad_u32_u24 v101, v101, s100, v153
	v_add_u32_e32 v150, 0x60000, v101
	v_lshlrev_b32_e32 v99, 4, v105
	v_mad_u32_u24 v99, v99, s100, v82
	v_lshlrev_b32_e32 v148, 4, v110
	v_mad_u32_u24 v148, v148, s100, v153
	v_add_u32_e32 v151, 0x180000, v148
	v_lshlrev_b32_e32 v228, 4, v105
	v_sub_u32_e32 v228, v107, v228
	s_add_i32 s90, s101, 1984
	v_lshl_add_u32 v228, v228, 2, s90
	v_lshlrev_b32_e32 v229, 2, v105
	v_sub_u32_e32 v229, v107, v229
	s_add_i32 s90, s101, 5104
	v_lshl_add_u32 v229, v229, 2, s90
	v_sub_u32_e32 v230, v107, v105
	s_add_i32 s90, s101, 6364
	v_lshl_add_u32 v230, v230, 2, s90
	v_add_u32_e32 v231, v109, v108
	v_mov_b64_e32 v[232:233], 0
	v_mov_b64_e32 v[0:1], 0
	v_mov_b64_e32 v[2:3], 0
	v_mov_b64_e32 v[4:5], 0
	v_mov_b64_e32 v[6:7], 0
	v_mov_b64_e32 v[8:9], 0
	v_mov_b64_e32 v[10:11], 0
	v_mov_b64_e32 v[12:13], 0
	v_mov_b64_e32 v[14:15], 0
	v_mov_b64_e32 v[16:17], 0
	v_mov_b64_e32 v[18:19], 0
	v_mov_b64_e32 v[20:21], 0
	v_mov_b64_e32 v[22:23], 0
	v_mov_b64_e32 v[24:25], 0
	v_mov_b64_e32 v[26:27], 0
	v_mov_b64_e32 v[28:29], 0
	v_mov_b64_e32 v[30:31], 0
	global_load_dwordx4 v[116:119], v80, s[84:85]
	global_load_dwordx4 v[120:123], v80, s[84:85] offset:32
	global_load_dwordx4 v[124:127], v80, s[84:85] offset:64
	global_load_dwordx4 v[128:131], v80, s[84:85] offset:96
	global_load_dwordx4 v[132:135], v100, s[84:85] offset:768
	global_load_dwordx4 v[136:139], v149, s[84:85] offset:768
	global_load_dwordx4 v[140:143], v100, s[84:85] offset:832
	global_load_dwordx4 v[144:147], v149, s[84:85] offset:832
	s_add_u32 s84, s84, 0x30000
	s_addc_u32 s85, s85, 0
	global_load_dwordx4 v[156:159], v80, s[84:85]
	global_load_dwordx4 v[160:163], v80, s[84:85] offset:32
	global_load_dwordx4 v[164:167], v80, s[84:85] offset:64
	global_load_dwordx4 v[168:171], v80, s[84:85] offset:96
	global_load_dwordx4 v[172:175], v100, s[84:85] offset:768
	global_load_dwordx4 v[176:179], v149, s[84:85] offset:768
	global_load_dwordx4 v[180:183], v100, s[84:85] offset:832
	global_load_dwordx4 v[184:187], v149, s[84:85] offset:832
	s_add_u32 s84, s84, 0x30000
	s_addc_u32 s85, s85, 0
	global_load_dwordx4 v[188:191], v80, s[84:85]
	global_load_dwordx4 v[192:195], v80, s[84:85] offset:32
	global_load_dwordx4 v[196:199], v80, s[84:85] offset:64
	global_load_dwordx4 v[200:203], v80, s[84:85] offset:96
	global_load_dwordx4 v[204:207], v100, s[84:85] offset:768
	global_load_dwordx4 v[208:211], v149, s[84:85] offset:768
	global_load_dwordx4 v[212:215], v100, s[84:85] offset:832
	global_load_dwordx4 v[216:219], v149, s[84:85] offset:832
	s_add_u32 s84, s84, 0x30000
	s_addc_u32 s85, s85, 0
	s_waitcnt vmcnt(16)
	ds_write_b128 v112, v[132:135]
	ds_write_b128 v112, v[136:139] offset:1024
	ds_write_b128 v112, v[140:143] offset:2048
	ds_write_b128 v112, v[144:147] offset:3072
	v_mov_b32_e32 v115, v228
	ds_read2_b32 v[32:33], v115 offset0:0 offset1:1
	ds_read2_b32 v[34:35], v115 offset0:2 offset1:3
	ds_read2_b32 v[36:37], v115 offset0:8 offset1:9
	ds_read2_b32 v[38:39], v115 offset0:10 offset1:11
	ds_read2_b32 v[40:41], v115 offset0:16 offset1:17
	ds_read2_b32 v[42:43], v115 offset0:18 offset1:19
	ds_read2_b32 v[44:45], v115 offset0:24 offset1:25
	ds_read2_b32 v[46:47], v115 offset0:26 offset1:27
	s_waitcnt lgkmcnt(0)
	v_mfma_f32_32x32x16_bf16 v[32:47], v[116:119], v[48:51], v[32:47]
	ds_read_b64_tr_b16 v[72:73], v231
	ds_read_b64_tr_b16 v[74:75], v231 offset:512
	ds_read_b64_tr_b16 v[76:77], v231 offset:2048
	ds_read_b64_tr_b16 v[78:79], v231 offset:2560
	ds_read_b64_tr_b16 v[220:221], v231 offset:1024
	ds_read_b64_tr_b16 v[222:223], v231 offset:1536
	ds_read_b64_tr_b16 v[224:225], v231 offset:3072
	ds_read_b64_tr_b16 v[226:227], v231 offset:3584
	v_mfma_f32_32x32x16_bf16 v[32:47], v[120:123], v[52:55], v[32:47]
	v_mfma_f32_32x32x16_bf16 v[32:47], v[124:127], v[56:59], v[32:47]
	v_mfma_f32_32x32x16_bf16 v[32:47], v[128:131], v[60:63], v[32:47]
	s_nop 11
	v_exp_f32_e32 v32, v32
	v_exp_f32_e32 v33, v33
	v_exp_f32_e32 v34, v34
	v_exp_f32_e32 v35, v35
	v_exp_f32_e32 v36, v36
	v_exp_f32_e32 v37, v37
	v_exp_f32_e32 v38, v38
	v_exp_f32_e32 v39, v39
	v_exp_f32_e32 v40, v40
	v_exp_f32_e32 v41, v41
	v_exp_f32_e32 v42, v42
	v_exp_f32_e32 v43, v43
	v_exp_f32_e32 v44, v44
	v_exp_f32_e32 v45, v45
	v_exp_f32_e32 v46, v46
	v_exp_f32_e32 v47, v47
	v_cvt_pk_bf16_f32 v64, v32, v33
	v_cvt_pk_bf16_f32 v65, v34, v35
	v_cvt_pk_bf16_f32 v66, v36, v37
	v_cvt_pk_bf16_f32 v67, v38, v39
	v_cvt_pk_bf16_f32 v68, v40, v41
	v_cvt_pk_bf16_f32 v69, v42, v43
	v_cvt_pk_bf16_f32 v70, v44, v45
	v_cvt_pk_bf16_f32 v71, v46, v47
	v_pk_add_f32 v[232:233], v[232:233], v[32:33]
	v_pk_add_f32 v[232:233], v[232:233], v[34:35]
	v_pk_add_f32 v[232:233], v[232:233], v[36:37]
	v_pk_add_f32 v[232:233], v[232:233], v[38:39]
	v_pk_add_f32 v[232:233], v[232:233], v[40:41]
	v_pk_add_f32 v[232:233], v[232:233], v[42:43]
	v_pk_add_f32 v[232:233], v[232:233], v[44:45]
	v_pk_add_f32 v[232:233], v[232:233], v[46:47]
	s_waitcnt lgkmcnt(0)
	v_mfma_f32_32x32x16_bf16 v[0:15], v[64:67], v[72:75], v[0:15]
	v_mfma_f32_32x32x16_bf16 v[16:31], v[64:67], v[76:79], v[16:31]
	v_mfma_f32_32x32x16_bf16 v[0:15], v[68:71], v[220:223], v[0:15]
	v_mfma_f32_32x32x16_bf16 v[16:31], v[68:71], v[224:227], v[16:31]
	global_load_dwordx4 v[116:119], v80, s[84:85]
	global_load_dwordx4 v[120:123], v80, s[84:85] offset:32
	global_load_dwordx4 v[124:127], v80, s[84:85] offset:64
	global_load_dwordx4 v[128:131], v80, s[84:85] offset:96
	global_load_dwordx4 v[132:135], v100, s[84:85] offset:768
	global_load_dwordx4 v[136:139], v149, s[84:85] offset:768
	global_load_dwordx4 v[140:143], v100, s[84:85] offset:832
	global_load_dwordx4 v[144:147], v149, s[84:85] offset:832
	s_add_u32 s84, s84, 0x30000
	s_addc_u32 s85, s85, 0
	s_waitcnt vmcnt(16)
	ds_write_b128 v112, v[172:175]
	ds_write_b128 v112, v[176:179] offset:1024
	ds_write_b128 v112, v[180:183] offset:2048
	ds_write_b128 v112, v[184:187] offset:3072
	ds_read2_b32 v[32:33], v115 offset0:32 offset1:33
	ds_read2_b32 v[34:35], v115 offset0:34 offset1:35
	ds_read2_b32 v[36:37], v115 offset0:40 offset1:41
	ds_read2_b32 v[38:39], v115 offset0:42 offset1:43
	ds_read2_b32 v[40:41], v115 offset0:48 offset1:49
	ds_read2_b32 v[42:43], v115 offset0:50 offset1:51
	ds_read2_b32 v[44:45], v115 offset0:56 offset1:57
	ds_read2_b32 v[46:47], v115 offset0:58 offset1:59
	s_waitcnt lgkmcnt(0)
	v_mfma_f32_32x32x16_bf16 v[32:47], v[156:159], v[48:51], v[32:47]
	ds_read_b64_tr_b16 v[72:73], v231
	ds_read_b64_tr_b16 v[74:75], v231 offset:512
	ds_read_b64_tr_b16 v[76:77], v231 offset:2048
	ds_read_b64_tr_b16 v[78:79], v231 offset:2560
	ds_read_b64_tr_b16 v[220:221], v231 offset:1024
	ds_read_b64_tr_b16 v[222:223], v231 offset:1536
	ds_read_b64_tr_b16 v[224:225], v231 offset:3072
	ds_read_b64_tr_b16 v[226:227], v231 offset:3584
	v_mfma_f32_32x32x16_bf16 v[32:47], v[160:163], v[52:55], v[32:47]
	v_mfma_f32_32x32x16_bf16 v[32:47], v[164:167], v[56:59], v[32:47]
	v_mfma_f32_32x32x16_bf16 v[32:47], v[168:171], v[60:63], v[32:47]
	s_nop 11
	v_exp_f32_e32 v32, v32
	v_exp_f32_e32 v33, v33
	v_exp_f32_e32 v34, v34
	v_exp_f32_e32 v35, v35
	v_exp_f32_e32 v36, v36
	v_exp_f32_e32 v37, v37
	v_exp_f32_e32 v38, v38
	v_exp_f32_e32 v39, v39
	v_exp_f32_e32 v40, v40
	v_exp_f32_e32 v41, v41
	v_exp_f32_e32 v42, v42
	v_exp_f32_e32 v43, v43
	v_exp_f32_e32 v44, v44
	v_exp_f32_e32 v45, v45
	v_exp_f32_e32 v46, v46
	v_exp_f32_e32 v47, v47
	v_cvt_pk_bf16_f32 v64, v32, v33
	v_cvt_pk_bf16_f32 v65, v34, v35
	v_cvt_pk_bf16_f32 v66, v36, v37
	v_cvt_pk_bf16_f32 v67, v38, v39
	v_cvt_pk_bf16_f32 v68, v40, v41
	v_cvt_pk_bf16_f32 v69, v42, v43
	v_cvt_pk_bf16_f32 v70, v44, v45
	v_cvt_pk_bf16_f32 v71, v46, v47
	v_pk_add_f32 v[232:233], v[232:233], v[32:33]
	v_pk_add_f32 v[232:233], v[232:233], v[34:35]
	v_pk_add_f32 v[232:233], v[232:233], v[36:37]
	v_pk_add_f32 v[232:233], v[232:233], v[38:39]
	v_pk_add_f32 v[232:233], v[232:233], v[40:41]
	v_pk_add_f32 v[232:233], v[232:233], v[42:43]
	v_pk_add_f32 v[232:233], v[232:233], v[44:45]
	v_pk_add_f32 v[232:233], v[232:233], v[46:47]
	s_waitcnt lgkmcnt(0)
	v_mfma_f32_32x32x16_bf16 v[0:15], v[64:67], v[72:75], v[0:15]
	v_mfma_f32_32x32x16_bf16 v[16:31], v[64:67], v[76:79], v[16:31]
	v_mfma_f32_32x32x16_bf16 v[0:15], v[68:71], v[220:223], v[0:15]
	v_mfma_f32_32x32x16_bf16 v[16:31], v[68:71], v[224:227], v[16:31]
	global_load_dwordx4 v[156:159], v80, s[84:85]
	global_load_dwordx4 v[160:163], v80, s[84:85] offset:32
	global_load_dwordx4 v[164:167], v80, s[84:85] offset:64
	global_load_dwordx4 v[168:171], v80, s[84:85] offset:96
	global_load_dwordx4 v[172:175], v100, s[84:85] offset:768
	global_load_dwordx4 v[176:179], v149, s[84:85] offset:768
	global_load_dwordx4 v[180:183], v100, s[84:85] offset:832
	global_load_dwordx4 v[184:187], v149, s[84:85] offset:832
	s_add_u32 s84, s84, 0x30000
	s_addc_u32 s85, s85, 0
	s_waitcnt vmcnt(16)
	ds_write_b128 v112, v[204:207]
	ds_write_b128 v112, v[208:211] offset:1024
	ds_write_b128 v112, v[212:215] offset:2048
	ds_write_b128 v112, v[216:219] offset:3072
	ds_read2_b32 v[32:33], v115 offset0:64 offset1:65
	ds_read2_b32 v[34:35], v115 offset0:66 offset1:67
	ds_read2_b32 v[36:37], v115 offset0:72 offset1:73
	ds_read2_b32 v[38:39], v115 offset0:74 offset1:75
	ds_read2_b32 v[40:41], v115 offset0:80 offset1:81
	ds_read2_b32 v[42:43], v115 offset0:82 offset1:83
	ds_read2_b32 v[44:45], v115 offset0:88 offset1:89
	ds_read2_b32 v[46:47], v115 offset0:90 offset1:91
	s_waitcnt lgkmcnt(0)
	v_mfma_f32_32x32x16_bf16 v[32:47], v[188:191], v[48:51], v[32:47]
	ds_read_b64_tr_b16 v[72:73], v231
	ds_read_b64_tr_b16 v[74:75], v231 offset:512
	ds_read_b64_tr_b16 v[76:77], v231 offset:2048
	ds_read_b64_tr_b16 v[78:79], v231 offset:2560
	ds_read_b64_tr_b16 v[220:221], v231 offset:1024
	ds_read_b64_tr_b16 v[222:223], v231 offset:1536
	ds_read_b64_tr_b16 v[224:225], v231 offset:3072
	ds_read_b64_tr_b16 v[226:227], v231 offset:3584
	v_mfma_f32_32x32x16_bf16 v[32:47], v[192:195], v[52:55], v[32:47]
	v_mfma_f32_32x32x16_bf16 v[32:47], v[196:199], v[56:59], v[32:47]
	v_mfma_f32_32x32x16_bf16 v[32:47], v[200:203], v[60:63], v[32:47]
	s_nop 11
	v_exp_f32_e32 v32, v32
	v_exp_f32_e32 v33, v33
	v_exp_f32_e32 v34, v34
	v_exp_f32_e32 v35, v35
	v_exp_f32_e32 v36, v36
	v_exp_f32_e32 v37, v37
	v_exp_f32_e32 v38, v38
	v_exp_f32_e32 v39, v39
	v_exp_f32_e32 v40, v40
	v_exp_f32_e32 v41, v41
	v_exp_f32_e32 v42, v42
	v_exp_f32_e32 v43, v43
	v_exp_f32_e32 v44, v44
	v_exp_f32_e32 v45, v45
	v_exp_f32_e32 v46, v46
	v_exp_f32_e32 v47, v47
	v_cvt_pk_bf16_f32 v64, v32, v33
	v_cvt_pk_bf16_f32 v65, v34, v35
	v_cvt_pk_bf16_f32 v66, v36, v37
	v_cvt_pk_bf16_f32 v67, v38, v39
	v_cvt_pk_bf16_f32 v68, v40, v41
	v_cvt_pk_bf16_f32 v69, v42, v43
	v_cvt_pk_bf16_f32 v70, v44, v45
	v_cvt_pk_bf16_f32 v71, v46, v47
	v_pk_add_f32 v[232:233], v[232:233], v[32:33]
	v_pk_add_f32 v[232:233], v[232:233], v[34:35]
	v_pk_add_f32 v[232:233], v[232:233], v[36:37]
	v_pk_add_f32 v[232:233], v[232:233], v[38:39]
	v_pk_add_f32 v[232:233], v[232:233], v[40:41]
	v_pk_add_f32 v[232:233], v[232:233], v[42:43]
	v_pk_add_f32 v[232:233], v[232:233], v[44:45]
	v_pk_add_f32 v[232:233], v[232:233], v[46:47]
	s_waitcnt lgkmcnt(0)
	v_mfma_f32_32x32x16_bf16 v[0:15], v[64:67], v[72:75], v[0:15]
	v_mfma_f32_32x32x16_bf16 v[16:31], v[64:67], v[76:79], v[16:31]
	v_mfma_f32_32x32x16_bf16 v[0:15], v[68:71], v[220:223], v[0:15]
	v_mfma_f32_32x32x16_bf16 v[16:31], v[68:71], v[224:227], v[16:31]
	global_load_dwordx4 v[188:191], v80, s[84:85]
	global_load_dwordx4 v[192:195], v80, s[84:85] offset:32
	global_load_dwordx4 v[196:199], v80, s[84:85] offset:64
	global_load_dwordx4 v[200:203], v80, s[84:85] offset:96
	global_load_dwordx4 v[204:207], v100, s[84:85] offset:768
	global_load_dwordx4 v[208:211], v149, s[84:85] offset:768
	global_load_dwordx4 v[212:215], v100, s[84:85] offset:832
	global_load_dwordx4 v[216:219], v149, s[84:85] offset:832
	s_add_u32 s84, s84, 0x30000
	s_addc_u32 s85, s85, 0
	s_waitcnt vmcnt(16)
	ds_write_b128 v112, v[132:135]
	ds_write_b128 v112, v[136:139] offset:1024
	ds_write_b128 v112, v[140:143] offset:2048
	ds_write_b128 v112, v[144:147] offset:3072
	ds_read2_b32 v[32:33], v115 offset0:96 offset1:97
	ds_read2_b32 v[34:35], v115 offset0:98 offset1:99
	ds_read2_b32 v[36:37], v115 offset0:104 offset1:105
	ds_read2_b32 v[38:39], v115 offset0:106 offset1:107
	ds_read2_b32 v[40:41], v115 offset0:112 offset1:113
	ds_read2_b32 v[42:43], v115 offset0:114 offset1:115
	ds_read2_b32 v[44:45], v115 offset0:120 offset1:121
	ds_read2_b32 v[46:47], v115 offset0:122 offset1:123
	s_waitcnt lgkmcnt(0)
	v_mfma_f32_32x32x16_bf16 v[32:47], v[116:119], v[48:51], v[32:47]
	ds_read_b64_tr_b16 v[72:73], v231
	ds_read_b64_tr_b16 v[74:75], v231 offset:512
	ds_read_b64_tr_b16 v[76:77], v231 offset:2048
	ds_read_b64_tr_b16 v[78:79], v231 offset:2560
	ds_read_b64_tr_b16 v[220:221], v231 offset:1024
	ds_read_b64_tr_b16 v[222:223], v231 offset:1536
	ds_read_b64_tr_b16 v[224:225], v231 offset:3072
	ds_read_b64_tr_b16 v[226:227], v231 offset:3584
	v_mfma_f32_32x32x16_bf16 v[32:47], v[120:123], v[52:55], v[32:47]
	v_mfma_f32_32x32x16_bf16 v[32:47], v[124:127], v[56:59], v[32:47]
	v_mfma_f32_32x32x16_bf16 v[32:47], v[128:131], v[60:63], v[32:47]
	s_nop 11
	v_exp_f32_e32 v32, v32
	v_exp_f32_e32 v33, v33
	v_exp_f32_e32 v34, v34
	v_exp_f32_e32 v35, v35
	v_exp_f32_e32 v36, v36
	v_exp_f32_e32 v37, v37
	v_exp_f32_e32 v38, v38
	v_exp_f32_e32 v39, v39
	v_exp_f32_e32 v40, v40
	v_exp_f32_e32 v41, v41
	v_exp_f32_e32 v42, v42
	v_exp_f32_e32 v43, v43
	v_exp_f32_e32 v44, v44
	v_exp_f32_e32 v45, v45
	v_exp_f32_e32 v46, v46
	v_exp_f32_e32 v47, v47
	v_cvt_pk_bf16_f32 v64, v32, v33
	v_cvt_pk_bf16_f32 v65, v34, v35
	v_cvt_pk_bf16_f32 v66, v36, v37
	v_cvt_pk_bf16_f32 v67, v38, v39
	v_cvt_pk_bf16_f32 v68, v40, v41
	v_cvt_pk_bf16_f32 v69, v42, v43
	v_cvt_pk_bf16_f32 v70, v44, v45
	v_cvt_pk_bf16_f32 v71, v46, v47
	v_pk_add_f32 v[232:233], v[232:233], v[32:33]
	v_pk_add_f32 v[232:233], v[232:233], v[34:35]
	v_pk_add_f32 v[232:233], v[232:233], v[36:37]
	v_pk_add_f32 v[232:233], v[232:233], v[38:39]
	v_pk_add_f32 v[232:233], v[232:233], v[40:41]
	v_pk_add_f32 v[232:233], v[232:233], v[42:43]
	v_pk_add_f32 v[232:233], v[232:233], v[44:45]
	v_pk_add_f32 v[232:233], v[232:233], v[46:47]
	s_waitcnt lgkmcnt(0)
	v_mfma_f32_32x32x16_bf16 v[0:15], v[64:67], v[72:75], v[0:15]
	v_mfma_f32_32x32x16_bf16 v[16:31], v[64:67], v[76:79], v[16:31]
	v_mfma_f32_32x32x16_bf16 v[0:15], v[68:71], v[220:223], v[0:15]
	v_mfma_f32_32x32x16_bf16 v[16:31], v[68:71], v[224:227], v[16:31]
	global_load_dwordx4 v[116:119], v80, s[84:85]
	global_load_dwordx4 v[120:123], v80, s[84:85] offset:32
	global_load_dwordx4 v[124:127], v80, s[84:85] offset:64
	global_load_dwordx4 v[128:131], v80, s[84:85] offset:96
	global_load_dwordx4 v[132:135], v100, s[84:85] offset:768
	global_load_dwordx4 v[136:139], v149, s[84:85] offset:768
	global_load_dwordx4 v[140:143], v100, s[84:85] offset:832
	global_load_dwordx4 v[144:147], v149, s[84:85] offset:832
	s_add_u32 s84, s84, 0x30000
	s_addc_u32 s85, s85, 0
	s_waitcnt vmcnt(16)
	ds_write_b128 v112, v[172:175]
	ds_write_b128 v112, v[176:179] offset:1024
	ds_write_b128 v112, v[180:183] offset:2048
	ds_write_b128 v112, v[184:187] offset:3072
	ds_read2_b32 v[32:33], v115 offset0:128 offset1:129
	ds_read2_b32 v[34:35], v115 offset0:130 offset1:131
	ds_read2_b32 v[36:37], v115 offset0:136 offset1:137
	ds_read2_b32 v[38:39], v115 offset0:138 offset1:139
	ds_read2_b32 v[40:41], v115 offset0:144 offset1:145
	ds_read2_b32 v[42:43], v115 offset0:146 offset1:147
	ds_read2_b32 v[44:45], v115 offset0:152 offset1:153
	ds_read2_b32 v[46:47], v115 offset0:154 offset1:155
	s_waitcnt lgkmcnt(0)
	v_mfma_f32_32x32x16_bf16 v[32:47], v[156:159], v[48:51], v[32:47]
	ds_read_b64_tr_b16 v[72:73], v231
	ds_read_b64_tr_b16 v[74:75], v231 offset:512
	ds_read_b64_tr_b16 v[76:77], v231 offset:2048
	ds_read_b64_tr_b16 v[78:79], v231 offset:2560
	ds_read_b64_tr_b16 v[220:221], v231 offset:1024
	ds_read_b64_tr_b16 v[222:223], v231 offset:1536
	ds_read_b64_tr_b16 v[224:225], v231 offset:3072
	ds_read_b64_tr_b16 v[226:227], v231 offset:3584
	v_mfma_f32_32x32x16_bf16 v[32:47], v[160:163], v[52:55], v[32:47]
	v_mfma_f32_32x32x16_bf16 v[32:47], v[164:167], v[56:59], v[32:47]
	v_mfma_f32_32x32x16_bf16 v[32:47], v[168:171], v[60:63], v[32:47]
	s_nop 11
	v_exp_f32_e32 v32, v32
	v_exp_f32_e32 v33, v33
	v_exp_f32_e32 v34, v34
	v_exp_f32_e32 v35, v35
	v_exp_f32_e32 v36, v36
	v_exp_f32_e32 v37, v37
	v_exp_f32_e32 v38, v38
	v_exp_f32_e32 v39, v39
	v_exp_f32_e32 v40, v40
	v_exp_f32_e32 v41, v41
	v_exp_f32_e32 v42, v42
	v_exp_f32_e32 v43, v43
	v_exp_f32_e32 v44, v44
	v_exp_f32_e32 v45, v45
	v_exp_f32_e32 v46, v46
	v_exp_f32_e32 v47, v47
	v_cvt_pk_bf16_f32 v64, v32, v33
	v_cvt_pk_bf16_f32 v65, v34, v35
	v_cvt_pk_bf16_f32 v66, v36, v37
	v_cvt_pk_bf16_f32 v67, v38, v39
	v_cvt_pk_bf16_f32 v68, v40, v41
	v_cvt_pk_bf16_f32 v69, v42, v43
	v_cvt_pk_bf16_f32 v70, v44, v45
	v_cvt_pk_bf16_f32 v71, v46, v47
	v_pk_add_f32 v[232:233], v[232:233], v[32:33]
	v_pk_add_f32 v[232:233], v[232:233], v[34:35]
	v_pk_add_f32 v[232:233], v[232:233], v[36:37]
	v_pk_add_f32 v[232:233], v[232:233], v[38:39]
	v_pk_add_f32 v[232:233], v[232:233], v[40:41]
	v_pk_add_f32 v[232:233], v[232:233], v[42:43]
	v_pk_add_f32 v[232:233], v[232:233], v[44:45]
	v_pk_add_f32 v[232:233], v[232:233], v[46:47]
	s_waitcnt lgkmcnt(0)
	v_mfma_f32_32x32x16_bf16 v[0:15], v[64:67], v[72:75], v[0:15]
	v_mfma_f32_32x32x16_bf16 v[16:31], v[64:67], v[76:79], v[16:31]
	v_mfma_f32_32x32x16_bf16 v[0:15], v[68:71], v[220:223], v[0:15]
	v_mfma_f32_32x32x16_bf16 v[16:31], v[68:71], v[224:227], v[16:31]
	global_load_dwordx4 v[156:159], v80, s[84:85]
	global_load_dwordx4 v[160:163], v80, s[84:85] offset:32
	global_load_dwordx4 v[164:167], v80, s[84:85] offset:64
	global_load_dwordx4 v[168:171], v80, s[84:85] offset:96
	global_load_dwordx4 v[172:175], v100, s[84:85] offset:768
	global_load_dwordx4 v[176:179], v149, s[84:85] offset:768
	global_load_dwordx4 v[180:183], v100, s[84:85] offset:832
	global_load_dwordx4 v[184:187], v149, s[84:85] offset:832
	s_add_u32 s84, s84, 0x30000
	s_addc_u32 s85, s85, 0
	s_waitcnt vmcnt(16)
	ds_write_b128 v112, v[204:207]
	ds_write_b128 v112, v[208:211] offset:1024
	ds_write_b128 v112, v[212:215] offset:2048
	ds_write_b128 v112, v[216:219] offset:3072
	ds_read2_b32 v[32:33], v115 offset0:160 offset1:161
	ds_read2_b32 v[34:35], v115 offset0:162 offset1:163
	ds_read2_b32 v[36:37], v115 offset0:168 offset1:169
	ds_read2_b32 v[38:39], v115 offset0:170 offset1:171
	ds_read2_b32 v[40:41], v115 offset0:176 offset1:177
	ds_read2_b32 v[42:43], v115 offset0:178 offset1:179
	ds_read2_b32 v[44:45], v115 offset0:184 offset1:185
	ds_read2_b32 v[46:47], v115 offset0:186 offset1:187
	s_waitcnt lgkmcnt(0)
	v_mfma_f32_32x32x16_bf16 v[32:47], v[188:191], v[48:51], v[32:47]
	ds_read_b64_tr_b16 v[72:73], v231
	ds_read_b64_tr_b16 v[74:75], v231 offset:512
	ds_read_b64_tr_b16 v[76:77], v231 offset:2048
	ds_read_b64_tr_b16 v[78:79], v231 offset:2560
	ds_read_b64_tr_b16 v[220:221], v231 offset:1024
	ds_read_b64_tr_b16 v[222:223], v231 offset:1536
	ds_read_b64_tr_b16 v[224:225], v231 offset:3072
	ds_read_b64_tr_b16 v[226:227], v231 offset:3584
	v_mfma_f32_32x32x16_bf16 v[32:47], v[192:195], v[52:55], v[32:47]
	v_mfma_f32_32x32x16_bf16 v[32:47], v[196:199], v[56:59], v[32:47]
	v_mfma_f32_32x32x16_bf16 v[32:47], v[200:203], v[60:63], v[32:47]
	s_nop 11
	v_exp_f32_e32 v32, v32
	v_exp_f32_e32 v33, v33
	v_exp_f32_e32 v34, v34
	v_exp_f32_e32 v35, v35
	v_exp_f32_e32 v36, v36
	v_exp_f32_e32 v37, v37
	v_exp_f32_e32 v38, v38
	v_exp_f32_e32 v39, v39
	v_exp_f32_e32 v40, v40
	v_exp_f32_e32 v41, v41
	v_exp_f32_e32 v42, v42
	v_exp_f32_e32 v43, v43
	v_exp_f32_e32 v44, v44
	v_exp_f32_e32 v45, v45
	v_exp_f32_e32 v46, v46
	v_exp_f32_e32 v47, v47
	v_cvt_pk_bf16_f32 v64, v32, v33
	v_cvt_pk_bf16_f32 v65, v34, v35
	v_cvt_pk_bf16_f32 v66, v36, v37
	v_cvt_pk_bf16_f32 v67, v38, v39
	v_cvt_pk_bf16_f32 v68, v40, v41
	v_cvt_pk_bf16_f32 v69, v42, v43
	v_cvt_pk_bf16_f32 v70, v44, v45
	v_cvt_pk_bf16_f32 v71, v46, v47
	v_pk_add_f32 v[232:233], v[232:233], v[32:33]
	v_pk_add_f32 v[232:233], v[232:233], v[34:35]
	v_pk_add_f32 v[232:233], v[232:233], v[36:37]
	v_pk_add_f32 v[232:233], v[232:233], v[38:39]
	v_pk_add_f32 v[232:233], v[232:233], v[40:41]
	v_pk_add_f32 v[232:233], v[232:233], v[42:43]
	v_pk_add_f32 v[232:233], v[232:233], v[44:45]
	v_pk_add_f32 v[232:233], v[232:233], v[46:47]
	s_waitcnt lgkmcnt(0)
	v_mfma_f32_32x32x16_bf16 v[0:15], v[64:67], v[72:75], v[0:15]
	v_mfma_f32_32x32x16_bf16 v[16:31], v[64:67], v[76:79], v[16:31]
	v_mfma_f32_32x32x16_bf16 v[0:15], v[68:71], v[220:223], v[0:15]
	v_mfma_f32_32x32x16_bf16 v[16:31], v[68:71], v[224:227], v[16:31]
	global_load_dwordx4 v[188:191], v80, s[84:85]
	global_load_dwordx4 v[192:195], v80, s[84:85] offset:32
	global_load_dwordx4 v[196:199], v80, s[84:85] offset:64
	global_load_dwordx4 v[200:203], v80, s[84:85] offset:96
	global_load_dwordx4 v[204:207], v100, s[84:85] offset:768
	global_load_dwordx4 v[208:211], v149, s[84:85] offset:768
	global_load_dwordx4 v[212:215], v100, s[84:85] offset:832
	global_load_dwordx4 v[216:219], v149, s[84:85] offset:832
	s_add_u32 s84, s84, 0x30000
	s_addc_u32 s85, s85, 0
	s_waitcnt vmcnt(16)
	ds_write_b128 v112, v[132:135]
	ds_write_b128 v112, v[136:139] offset:1024
	ds_write_b128 v112, v[140:143] offset:2048
	ds_write_b128 v112, v[144:147] offset:3072
	ds_read2_b32 v[32:33], v115 offset0:192 offset1:193
	ds_read2_b32 v[34:35], v115 offset0:194 offset1:195
	ds_read2_b32 v[36:37], v115 offset0:200 offset1:201
	ds_read2_b32 v[38:39], v115 offset0:202 offset1:203
	ds_read2_b32 v[40:41], v115 offset0:208 offset1:209
	ds_read2_b32 v[42:43], v115 offset0:210 offset1:211
	ds_read2_b32 v[44:45], v115 offset0:216 offset1:217
	ds_read2_b32 v[46:47], v115 offset0:218 offset1:219
	s_waitcnt lgkmcnt(0)
	v_mfma_f32_32x32x16_bf16 v[32:47], v[116:119], v[48:51], v[32:47]
	ds_read_b64_tr_b16 v[72:73], v231
	ds_read_b64_tr_b16 v[74:75], v231 offset:512
	ds_read_b64_tr_b16 v[76:77], v231 offset:2048
	ds_read_b64_tr_b16 v[78:79], v231 offset:2560
	ds_read_b64_tr_b16 v[220:221], v231 offset:1024
	ds_read_b64_tr_b16 v[222:223], v231 offset:1536
	ds_read_b64_tr_b16 v[224:225], v231 offset:3072
	ds_read_b64_tr_b16 v[226:227], v231 offset:3584
	v_mfma_f32_32x32x16_bf16 v[32:47], v[120:123], v[52:55], v[32:47]
	v_mfma_f32_32x32x16_bf16 v[32:47], v[124:127], v[56:59], v[32:47]
	v_mfma_f32_32x32x16_bf16 v[32:47], v[128:131], v[60:63], v[32:47]
	s_nop 11
	v_exp_f32_e32 v32, v32
	v_exp_f32_e32 v33, v33
	v_exp_f32_e32 v34, v34
	v_exp_f32_e32 v35, v35
	v_exp_f32_e32 v36, v36
	v_exp_f32_e32 v37, v37
	v_exp_f32_e32 v38, v38
	v_exp_f32_e32 v39, v39
	v_exp_f32_e32 v40, v40
	v_exp_f32_e32 v41, v41
	v_exp_f32_e32 v42, v42
	v_exp_f32_e32 v43, v43
	v_exp_f32_e32 v44, v44
	v_exp_f32_e32 v45, v45
	v_exp_f32_e32 v46, v46
	v_exp_f32_e32 v47, v47
	v_cvt_pk_bf16_f32 v64, v32, v33
	v_cvt_pk_bf16_f32 v65, v34, v35
	v_cvt_pk_bf16_f32 v66, v36, v37
	v_cvt_pk_bf16_f32 v67, v38, v39
	v_cvt_pk_bf16_f32 v68, v40, v41
	v_cvt_pk_bf16_f32 v69, v42, v43
	v_cvt_pk_bf16_f32 v70, v44, v45
	v_cvt_pk_bf16_f32 v71, v46, v47
	v_pk_add_f32 v[232:233], v[232:233], v[32:33]
	v_pk_add_f32 v[232:233], v[232:233], v[34:35]
	v_pk_add_f32 v[232:233], v[232:233], v[36:37]
	v_pk_add_f32 v[232:233], v[232:233], v[38:39]
	v_pk_add_f32 v[232:233], v[232:233], v[40:41]
	v_pk_add_f32 v[232:233], v[232:233], v[42:43]
	v_pk_add_f32 v[232:233], v[232:233], v[44:45]
	v_pk_add_f32 v[232:233], v[232:233], v[46:47]
	s_waitcnt lgkmcnt(0)
	v_mfma_f32_32x32x16_bf16 v[0:15], v[64:67], v[72:75], v[0:15]
	v_mfma_f32_32x32x16_bf16 v[16:31], v[64:67], v[76:79], v[16:31]
	v_mfma_f32_32x32x16_bf16 v[0:15], v[68:71], v[220:223], v[0:15]
	v_mfma_f32_32x32x16_bf16 v[16:31], v[68:71], v[224:227], v[16:31]
	global_load_dwordx4 v[116:119], v80, s[84:85]
	global_load_dwordx4 v[120:123], v80, s[84:85] offset:32
	global_load_dwordx4 v[124:127], v80, s[84:85] offset:64
	global_load_dwordx4 v[128:131], v80, s[84:85] offset:96
	global_load_dwordx4 v[132:135], v100, s[84:85] offset:768
	global_load_dwordx4 v[136:139], v149, s[84:85] offset:768
	global_load_dwordx4 v[140:143], v100, s[84:85] offset:832
	global_load_dwordx4 v[144:147], v149, s[84:85] offset:832
	s_add_u32 s84, s84, 0x30000
	s_addc_u32 s85, s85, 0
	s_waitcnt vmcnt(16)
	ds_write_b128 v112, v[172:175]
	ds_write_b128 v112, v[176:179] offset:1024
	ds_write_b128 v112, v[180:183] offset:2048
	ds_write_b128 v112, v[184:187] offset:3072
	ds_read2_b32 v[32:33], v115 offset0:224 offset1:225
	ds_read2_b32 v[34:35], v115 offset0:226 offset1:227
	ds_read2_b32 v[36:37], v115 offset0:232 offset1:233
	ds_read2_b32 v[38:39], v115 offset0:234 offset1:235
	ds_read2_b32 v[40:41], v115 offset0:240 offset1:241
	ds_read2_b32 v[42:43], v115 offset0:242 offset1:243
	ds_read2_b32 v[44:45], v115 offset0:248 offset1:249
	ds_read2_b32 v[46:47], v115 offset0:250 offset1:251
	s_waitcnt lgkmcnt(0)
	v_mfma_f32_32x32x16_bf16 v[32:47], v[156:159], v[48:51], v[32:47]
	ds_read_b64_tr_b16 v[72:73], v231
	ds_read_b64_tr_b16 v[74:75], v231 offset:512
	ds_read_b64_tr_b16 v[76:77], v231 offset:2048
	ds_read_b64_tr_b16 v[78:79], v231 offset:2560
	ds_read_b64_tr_b16 v[220:221], v231 offset:1024
	ds_read_b64_tr_b16 v[222:223], v231 offset:1536
	ds_read_b64_tr_b16 v[224:225], v231 offset:3072
	ds_read_b64_tr_b16 v[226:227], v231 offset:3584
	v_mfma_f32_32x32x16_bf16 v[32:47], v[160:163], v[52:55], v[32:47]
	v_mfma_f32_32x32x16_bf16 v[32:47], v[164:167], v[56:59], v[32:47]
	v_mfma_f32_32x32x16_bf16 v[32:47], v[168:171], v[60:63], v[32:47]
	s_nop 11
	v_exp_f32_e32 v32, v32
	v_exp_f32_e32 v33, v33
	v_exp_f32_e32 v34, v34
	v_exp_f32_e32 v35, v35
	v_exp_f32_e32 v36, v36
	v_exp_f32_e32 v37, v37
	v_exp_f32_e32 v38, v38
	v_exp_f32_e32 v39, v39
	v_exp_f32_e32 v40, v40
	v_exp_f32_e32 v41, v41
	v_exp_f32_e32 v42, v42
	v_exp_f32_e32 v43, v43
	v_exp_f32_e32 v44, v44
	v_exp_f32_e32 v45, v45
	v_exp_f32_e32 v46, v46
	v_exp_f32_e32 v47, v47
	v_cvt_pk_bf16_f32 v64, v32, v33
	v_cvt_pk_bf16_f32 v65, v34, v35
	v_cvt_pk_bf16_f32 v66, v36, v37
	v_cvt_pk_bf16_f32 v67, v38, v39
	v_cvt_pk_bf16_f32 v68, v40, v41
	v_cvt_pk_bf16_f32 v69, v42, v43
	v_cvt_pk_bf16_f32 v70, v44, v45
	v_cvt_pk_bf16_f32 v71, v46, v47
	v_pk_add_f32 v[232:233], v[232:233], v[32:33]
	v_pk_add_f32 v[232:233], v[232:233], v[34:35]
	v_pk_add_f32 v[232:233], v[232:233], v[36:37]
	v_pk_add_f32 v[232:233], v[232:233], v[38:39]
	v_pk_add_f32 v[232:233], v[232:233], v[40:41]
	v_pk_add_f32 v[232:233], v[232:233], v[42:43]
	v_pk_add_f32 v[232:233], v[232:233], v[44:45]
	v_pk_add_f32 v[232:233], v[232:233], v[46:47]
	s_waitcnt lgkmcnt(0)
	v_mfma_f32_32x32x16_bf16 v[0:15], v[64:67], v[72:75], v[0:15]
	v_mfma_f32_32x32x16_bf16 v[16:31], v[64:67], v[76:79], v[16:31]
	v_mfma_f32_32x32x16_bf16 v[0:15], v[68:71], v[220:223], v[0:15]
	v_mfma_f32_32x32x16_bf16 v[16:31], v[68:71], v[224:227], v[16:31]
	global_load_dwordx4 v[156:159], v80, s[84:85]
	global_load_dwordx4 v[160:163], v80, s[84:85] offset:32
	global_load_dwordx4 v[164:167], v80, s[84:85] offset:64
	global_load_dwordx4 v[168:171], v80, s[84:85] offset:96
	global_load_dwordx4 v[172:175], v100, s[84:85] offset:768
	global_load_dwordx4 v[176:179], v149, s[84:85] offset:768
	global_load_dwordx4 v[180:183], v100, s[84:85] offset:832
	global_load_dwordx4 v[184:187], v149, s[84:85] offset:832
	s_add_u32 s84, s84, 0x30000
	s_addc_u32 s85, s85, 0
	s_waitcnt vmcnt(16)
	ds_write_b128 v112, v[204:207]
	ds_write_b128 v112, v[208:211] offset:1024
	ds_write_b128 v112, v[212:215] offset:2048
	ds_write_b128 v112, v[216:219] offset:3072
	v_add_u32_e32 v115, 0x400, v115
	ds_read2_b32 v[32:33], v115 offset0:0 offset1:1
	ds_read2_b32 v[34:35], v115 offset0:2 offset1:3
	ds_read2_b32 v[36:37], v115 offset0:8 offset1:9
	ds_read2_b32 v[38:39], v115 offset0:10 offset1:11
	ds_read2_b32 v[40:41], v115 offset0:16 offset1:17
	ds_read2_b32 v[42:43], v115 offset0:18 offset1:19
	ds_read2_b32 v[44:45], v115 offset0:24 offset1:25
	ds_read2_b32 v[46:47], v115 offset0:26 offset1:27
	s_waitcnt lgkmcnt(0)
	v_mfma_f32_32x32x16_bf16 v[32:47], v[188:191], v[48:51], v[32:47]
	ds_read_b64_tr_b16 v[72:73], v231
	ds_read_b64_tr_b16 v[74:75], v231 offset:512
	ds_read_b64_tr_b16 v[76:77], v231 offset:2048
	ds_read_b64_tr_b16 v[78:79], v231 offset:2560
	ds_read_b64_tr_b16 v[220:221], v231 offset:1024
	ds_read_b64_tr_b16 v[222:223], v231 offset:1536
	ds_read_b64_tr_b16 v[224:225], v231 offset:3072
	ds_read_b64_tr_b16 v[226:227], v231 offset:3584
	v_mfma_f32_32x32x16_bf16 v[32:47], v[192:195], v[52:55], v[32:47]
	v_mfma_f32_32x32x16_bf16 v[32:47], v[196:199], v[56:59], v[32:47]
	v_mfma_f32_32x32x16_bf16 v[32:47], v[200:203], v[60:63], v[32:47]
	s_nop 11
	v_exp_f32_e32 v32, v32
	v_exp_f32_e32 v33, v33
	v_exp_f32_e32 v34, v34
	v_exp_f32_e32 v35, v35
	v_exp_f32_e32 v36, v36
	v_exp_f32_e32 v37, v37
	v_exp_f32_e32 v38, v38
	v_exp_f32_e32 v39, v39
	v_exp_f32_e32 v40, v40
	v_exp_f32_e32 v41, v41
	v_exp_f32_e32 v42, v42
	v_exp_f32_e32 v43, v43
	v_exp_f32_e32 v44, v44
	v_exp_f32_e32 v45, v45
	v_exp_f32_e32 v46, v46
	v_exp_f32_e32 v47, v47
	v_cvt_pk_bf16_f32 v64, v32, v33
	v_cvt_pk_bf16_f32 v65, v34, v35
	v_cvt_pk_bf16_f32 v66, v36, v37
	v_cvt_pk_bf16_f32 v67, v38, v39
	v_cvt_pk_bf16_f32 v68, v40, v41
	v_cvt_pk_bf16_f32 v69, v42, v43
	v_cvt_pk_bf16_f32 v70, v44, v45
	v_cvt_pk_bf16_f32 v71, v46, v47
	v_pk_add_f32 v[232:233], v[232:233], v[32:33]
	v_pk_add_f32 v[232:233], v[232:233], v[34:35]
	v_pk_add_f32 v[232:233], v[232:233], v[36:37]
	v_pk_add_f32 v[232:233], v[232:233], v[38:39]
	v_pk_add_f32 v[232:233], v[232:233], v[40:41]
	v_pk_add_f32 v[232:233], v[232:233], v[42:43]
	v_pk_add_f32 v[232:233], v[232:233], v[44:45]
	v_pk_add_f32 v[232:233], v[232:233], v[46:47]
	s_waitcnt lgkmcnt(0)
	v_mfma_f32_32x32x16_bf16 v[0:15], v[64:67], v[72:75], v[0:15]
	v_mfma_f32_32x32x16_bf16 v[16:31], v[64:67], v[76:79], v[16:31]
	v_mfma_f32_32x32x16_bf16 v[0:15], v[68:71], v[220:223], v[0:15]
	v_mfma_f32_32x32x16_bf16 v[16:31], v[68:71], v[224:227], v[16:31]
	global_load_dwordx4 v[188:191], v80, s[84:85]
	global_load_dwordx4 v[192:195], v80, s[84:85] offset:32
	global_load_dwordx4 v[196:199], v80, s[84:85] offset:64
	global_load_dwordx4 v[200:203], v80, s[84:85] offset:96
	global_load_dwordx4 v[204:207], v100, s[84:85] offset:768
	global_load_dwordx4 v[208:211], v149, s[84:85] offset:768
	global_load_dwordx4 v[212:215], v100, s[84:85] offset:832
	global_load_dwordx4 v[216:219], v149, s[84:85] offset:832
	s_add_u32 s84, s84, 0x30000
	s_addc_u32 s85, s85, 0
	s_waitcnt vmcnt(16)
	ds_write_b128 v112, v[132:135]
	ds_write_b128 v112, v[136:139] offset:1024
	ds_write_b128 v112, v[140:143] offset:2048
	ds_write_b128 v112, v[144:147] offset:3072
	ds_read2_b32 v[32:33], v115 offset0:32 offset1:33
	ds_read2_b32 v[34:35], v115 offset0:34 offset1:35
	ds_read2_b32 v[36:37], v115 offset0:40 offset1:41
	ds_read2_b32 v[38:39], v115 offset0:42 offset1:43
	ds_read2_b32 v[40:41], v115 offset0:48 offset1:49
	ds_read2_b32 v[42:43], v115 offset0:50 offset1:51
	ds_read2_b32 v[44:45], v115 offset0:56 offset1:57
	ds_read2_b32 v[46:47], v115 offset0:58 offset1:59
	s_waitcnt lgkmcnt(0)
	v_mfma_f32_32x32x16_bf16 v[32:47], v[116:119], v[48:51], v[32:47]
	ds_read_b64_tr_b16 v[72:73], v231
	ds_read_b64_tr_b16 v[74:75], v231 offset:512
	ds_read_b64_tr_b16 v[76:77], v231 offset:2048
	ds_read_b64_tr_b16 v[78:79], v231 offset:2560
	ds_read_b64_tr_b16 v[220:221], v231 offset:1024
	ds_read_b64_tr_b16 v[222:223], v231 offset:1536
	ds_read_b64_tr_b16 v[224:225], v231 offset:3072
	ds_read_b64_tr_b16 v[226:227], v231 offset:3584
	v_mfma_f32_32x32x16_bf16 v[32:47], v[120:123], v[52:55], v[32:47]
	v_mfma_f32_32x32x16_bf16 v[32:47], v[124:127], v[56:59], v[32:47]
	v_mfma_f32_32x32x16_bf16 v[32:47], v[128:131], v[60:63], v[32:47]
	s_nop 11
	v_exp_f32_e32 v32, v32
	v_exp_f32_e32 v33, v33
	v_exp_f32_e32 v34, v34
	v_exp_f32_e32 v35, v35
	v_exp_f32_e32 v36, v36
	v_exp_f32_e32 v37, v37
	v_exp_f32_e32 v38, v38
	v_exp_f32_e32 v39, v39
	v_exp_f32_e32 v40, v40
	v_exp_f32_e32 v41, v41
	v_exp_f32_e32 v42, v42
	v_exp_f32_e32 v43, v43
	v_exp_f32_e32 v44, v44
	v_exp_f32_e32 v45, v45
	v_exp_f32_e32 v46, v46
	v_exp_f32_e32 v47, v47
	v_cvt_pk_bf16_f32 v64, v32, v33
	v_cvt_pk_bf16_f32 v65, v34, v35
	v_cvt_pk_bf16_f32 v66, v36, v37
	v_cvt_pk_bf16_f32 v67, v38, v39
	v_cvt_pk_bf16_f32 v68, v40, v41
	v_cvt_pk_bf16_f32 v69, v42, v43
	v_cvt_pk_bf16_f32 v70, v44, v45
	v_cvt_pk_bf16_f32 v71, v46, v47
	v_pk_add_f32 v[232:233], v[232:233], v[32:33]
	v_pk_add_f32 v[232:233], v[232:233], v[34:35]
	v_pk_add_f32 v[232:233], v[232:233], v[36:37]
	v_pk_add_f32 v[232:233], v[232:233], v[38:39]
	v_pk_add_f32 v[232:233], v[232:233], v[40:41]
	v_pk_add_f32 v[232:233], v[232:233], v[42:43]
	v_pk_add_f32 v[232:233], v[232:233], v[44:45]
	v_pk_add_f32 v[232:233], v[232:233], v[46:47]
	s_waitcnt lgkmcnt(0)
	v_mfma_f32_32x32x16_bf16 v[0:15], v[64:67], v[72:75], v[0:15]
	v_mfma_f32_32x32x16_bf16 v[16:31], v[64:67], v[76:79], v[16:31]
	v_mfma_f32_32x32x16_bf16 v[0:15], v[68:71], v[220:223], v[0:15]
	v_mfma_f32_32x32x16_bf16 v[16:31], v[68:71], v[224:227], v[16:31]
	global_load_dwordx4 v[116:119], v80, s[84:85]
	global_load_dwordx4 v[120:123], v80, s[84:85] offset:32
	global_load_dwordx4 v[124:127], v80, s[84:85] offset:64
	global_load_dwordx4 v[128:131], v80, s[84:85] offset:96
	global_load_dwordx4 v[132:135], v100, s[84:85] offset:768
	global_load_dwordx4 v[136:139], v149, s[84:85] offset:768
	global_load_dwordx4 v[140:143], v100, s[84:85] offset:832
	global_load_dwordx4 v[144:147], v149, s[84:85] offset:832
	s_add_u32 s84, s84, 0x30000
	s_addc_u32 s85, s85, 0
	s_waitcnt vmcnt(16)
	ds_write_b128 v112, v[172:175]
	ds_write_b128 v112, v[176:179] offset:1024
	ds_write_b128 v112, v[180:183] offset:2048
	ds_write_b128 v112, v[184:187] offset:3072
	ds_read2_b32 v[32:33], v115 offset0:64 offset1:65
	ds_read2_b32 v[34:35], v115 offset0:66 offset1:67
	ds_read2_b32 v[36:37], v115 offset0:72 offset1:73
	ds_read2_b32 v[38:39], v115 offset0:74 offset1:75
	ds_read2_b32 v[40:41], v115 offset0:80 offset1:81
	ds_read2_b32 v[42:43], v115 offset0:82 offset1:83
	ds_read2_b32 v[44:45], v115 offset0:88 offset1:89
	ds_read2_b32 v[46:47], v115 offset0:90 offset1:91
	s_waitcnt lgkmcnt(0)
	v_mfma_f32_32x32x16_bf16 v[32:47], v[156:159], v[48:51], v[32:47]
	ds_read_b64_tr_b16 v[72:73], v231
	ds_read_b64_tr_b16 v[74:75], v231 offset:512
	ds_read_b64_tr_b16 v[76:77], v231 offset:2048
	ds_read_b64_tr_b16 v[78:79], v231 offset:2560
	ds_read_b64_tr_b16 v[220:221], v231 offset:1024
	ds_read_b64_tr_b16 v[222:223], v231 offset:1536
	ds_read_b64_tr_b16 v[224:225], v231 offset:3072
	ds_read_b64_tr_b16 v[226:227], v231 offset:3584
	v_mfma_f32_32x32x16_bf16 v[32:47], v[160:163], v[52:55], v[32:47]
	v_mfma_f32_32x32x16_bf16 v[32:47], v[164:167], v[56:59], v[32:47]
	v_mfma_f32_32x32x16_bf16 v[32:47], v[168:171], v[60:63], v[32:47]
	s_nop 11
	v_exp_f32_e32 v32, v32
	v_exp_f32_e32 v33, v33
	v_exp_f32_e32 v34, v34
	v_exp_f32_e32 v35, v35
	v_exp_f32_e32 v36, v36
	v_exp_f32_e32 v37, v37
	v_exp_f32_e32 v38, v38
	v_exp_f32_e32 v39, v39
	v_exp_f32_e32 v40, v40
	v_exp_f32_e32 v41, v41
	v_exp_f32_e32 v42, v42
	v_exp_f32_e32 v43, v43
	v_exp_f32_e32 v44, v44
	v_exp_f32_e32 v45, v45
	v_exp_f32_e32 v46, v46
	v_exp_f32_e32 v47, v47
	v_cvt_pk_bf16_f32 v64, v32, v33
	v_cvt_pk_bf16_f32 v65, v34, v35
	v_cvt_pk_bf16_f32 v66, v36, v37
	v_cvt_pk_bf16_f32 v67, v38, v39
	v_cvt_pk_bf16_f32 v68, v40, v41
	v_cvt_pk_bf16_f32 v69, v42, v43
	v_cvt_pk_bf16_f32 v70, v44, v45
	v_cvt_pk_bf16_f32 v71, v46, v47
	v_pk_add_f32 v[232:233], v[232:233], v[32:33]
	v_pk_add_f32 v[232:233], v[232:233], v[34:35]
	v_pk_add_f32 v[232:233], v[232:233], v[36:37]
	v_pk_add_f32 v[232:233], v[232:233], v[38:39]
	v_pk_add_f32 v[232:233], v[232:233], v[40:41]
	v_pk_add_f32 v[232:233], v[232:233], v[42:43]
	v_pk_add_f32 v[232:233], v[232:233], v[44:45]
	v_pk_add_f32 v[232:233], v[232:233], v[46:47]
	s_waitcnt lgkmcnt(0)
	v_mfma_f32_32x32x16_bf16 v[0:15], v[64:67], v[72:75], v[0:15]
	v_mfma_f32_32x32x16_bf16 v[16:31], v[64:67], v[76:79], v[16:31]
	v_mfma_f32_32x32x16_bf16 v[0:15], v[68:71], v[220:223], v[0:15]
	v_mfma_f32_32x32x16_bf16 v[16:31], v[68:71], v[224:227], v[16:31]
	global_load_dwordx4 v[156:159], v80, s[84:85]
	global_load_dwordx4 v[160:163], v80, s[84:85] offset:32
	global_load_dwordx4 v[164:167], v80, s[84:85] offset:64
	global_load_dwordx4 v[168:171], v80, s[84:85] offset:96
	global_load_dwordx4 v[172:175], v100, s[84:85] offset:768
	global_load_dwordx4 v[176:179], v149, s[84:85] offset:768
	global_load_dwordx4 v[180:183], v100, s[84:85] offset:832
	global_load_dwordx4 v[184:187], v149, s[84:85] offset:832
	s_add_u32 s84, s84, 0x30000
	s_addc_u32 s85, s85, 0
	s_waitcnt vmcnt(16)
	ds_write_b128 v112, v[204:207]
	ds_write_b128 v112, v[208:211] offset:1024
	ds_write_b128 v112, v[212:215] offset:2048
	ds_write_b128 v112, v[216:219] offset:3072
	ds_read2_b32 v[32:33], v115 offset0:96 offset1:97
	ds_read2_b32 v[34:35], v115 offset0:98 offset1:99
	ds_read2_b32 v[36:37], v115 offset0:104 offset1:105
	ds_read2_b32 v[38:39], v115 offset0:106 offset1:107
	ds_read2_b32 v[40:41], v115 offset0:112 offset1:113
	ds_read2_b32 v[42:43], v115 offset0:114 offset1:115
	ds_read2_b32 v[44:45], v115 offset0:120 offset1:121
	ds_read2_b32 v[46:47], v115 offset0:122 offset1:123
	s_waitcnt lgkmcnt(0)
	v_mfma_f32_32x32x16_bf16 v[32:47], v[188:191], v[48:51], v[32:47]
	ds_read_b64_tr_b16 v[72:73], v231
	ds_read_b64_tr_b16 v[74:75], v231 offset:512
	ds_read_b64_tr_b16 v[76:77], v231 offset:2048
	ds_read_b64_tr_b16 v[78:79], v231 offset:2560
	ds_read_b64_tr_b16 v[220:221], v231 offset:1024
	ds_read_b64_tr_b16 v[222:223], v231 offset:1536
	ds_read_b64_tr_b16 v[224:225], v231 offset:3072
	ds_read_b64_tr_b16 v[226:227], v231 offset:3584
	v_mfma_f32_32x32x16_bf16 v[32:47], v[192:195], v[52:55], v[32:47]
	v_mfma_f32_32x32x16_bf16 v[32:47], v[196:199], v[56:59], v[32:47]
	v_mfma_f32_32x32x16_bf16 v[32:47], v[200:203], v[60:63], v[32:47]
	s_nop 11
	v_exp_f32_e32 v32, v32
	v_exp_f32_e32 v33, v33
	v_exp_f32_e32 v34, v34
	v_exp_f32_e32 v35, v35
	v_exp_f32_e32 v36, v36
	v_exp_f32_e32 v37, v37
	v_exp_f32_e32 v38, v38
	v_exp_f32_e32 v39, v39
	v_exp_f32_e32 v40, v40
	v_exp_f32_e32 v41, v41
	v_exp_f32_e32 v42, v42
	v_exp_f32_e32 v43, v43
	v_exp_f32_e32 v44, v44
	v_exp_f32_e32 v45, v45
	v_exp_f32_e32 v46, v46
	v_exp_f32_e32 v47, v47
	v_cvt_pk_bf16_f32 v64, v32, v33
	v_cvt_pk_bf16_f32 v65, v34, v35
	v_cvt_pk_bf16_f32 v66, v36, v37
	v_cvt_pk_bf16_f32 v67, v38, v39
	v_cvt_pk_bf16_f32 v68, v40, v41
	v_cvt_pk_bf16_f32 v69, v42, v43
	v_cvt_pk_bf16_f32 v70, v44, v45
	v_cvt_pk_bf16_f32 v71, v46, v47
	v_pk_add_f32 v[232:233], v[232:233], v[32:33]
	v_pk_add_f32 v[232:233], v[232:233], v[34:35]
	v_pk_add_f32 v[232:233], v[232:233], v[36:37]
	v_pk_add_f32 v[232:233], v[232:233], v[38:39]
	v_pk_add_f32 v[232:233], v[232:233], v[40:41]
	v_pk_add_f32 v[232:233], v[232:233], v[42:43]
	v_pk_add_f32 v[232:233], v[232:233], v[44:45]
	v_pk_add_f32 v[232:233], v[232:233], v[46:47]
	s_waitcnt lgkmcnt(0)
	v_mfma_f32_32x32x16_bf16 v[0:15], v[64:67], v[72:75], v[0:15]
	v_mfma_f32_32x32x16_bf16 v[16:31], v[64:67], v[76:79], v[16:31]
	v_mfma_f32_32x32x16_bf16 v[0:15], v[68:71], v[220:223], v[0:15]
	v_mfma_f32_32x32x16_bf16 v[16:31], v[68:71], v[224:227], v[16:31]
	global_load_dwordx4 v[188:191], v80, s[84:85]
	global_load_dwordx4 v[192:195], v80, s[84:85] offset:32
	global_load_dwordx4 v[196:199], v80, s[84:85] offset:64
	global_load_dwordx4 v[200:203], v80, s[84:85] offset:96
	global_load_dwordx4 v[204:207], v100, s[84:85] offset:768
	global_load_dwordx4 v[208:211], v149, s[84:85] offset:768
	global_load_dwordx4 v[212:215], v100, s[84:85] offset:832
	global_load_dwordx4 v[216:219], v149, s[84:85] offset:832
	s_add_u32 s84, s84, 0x30000
	s_addc_u32 s85, s85, 0
	s_waitcnt vmcnt(16)
	ds_write_b128 v112, v[132:135]
	ds_write_b128 v112, v[136:139] offset:1024
	ds_write_b128 v112, v[140:143] offset:2048
	ds_write_b128 v112, v[144:147] offset:3072
	ds_read2_b32 v[32:33], v115 offset0:128 offset1:129
	ds_read2_b32 v[34:35], v115 offset0:130 offset1:131
	ds_read2_b32 v[36:37], v115 offset0:136 offset1:137
	ds_read2_b32 v[38:39], v115 offset0:138 offset1:139
	ds_read2_b32 v[40:41], v115 offset0:144 offset1:145
	ds_read2_b32 v[42:43], v115 offset0:146 offset1:147
	ds_read2_b32 v[44:45], v115 offset0:152 offset1:153
	ds_read2_b32 v[46:47], v115 offset0:154 offset1:155
	s_waitcnt lgkmcnt(0)
	v_mfma_f32_32x32x16_bf16 v[32:47], v[116:119], v[48:51], v[32:47]
	ds_read_b64_tr_b16 v[72:73], v231
	ds_read_b64_tr_b16 v[74:75], v231 offset:512
	ds_read_b64_tr_b16 v[76:77], v231 offset:2048
	ds_read_b64_tr_b16 v[78:79], v231 offset:2560
	ds_read_b64_tr_b16 v[220:221], v231 offset:1024
	ds_read_b64_tr_b16 v[222:223], v231 offset:1536
	ds_read_b64_tr_b16 v[224:225], v231 offset:3072
	ds_read_b64_tr_b16 v[226:227], v231 offset:3584
	v_mfma_f32_32x32x16_bf16 v[32:47], v[120:123], v[52:55], v[32:47]
	v_mfma_f32_32x32x16_bf16 v[32:47], v[124:127], v[56:59], v[32:47]
	v_mfma_f32_32x32x16_bf16 v[32:47], v[128:131], v[60:63], v[32:47]
	s_nop 11
	v_exp_f32_e32 v32, v32
	v_exp_f32_e32 v33, v33
	v_exp_f32_e32 v34, v34
	v_exp_f32_e32 v35, v35
	v_exp_f32_e32 v36, v36
	v_exp_f32_e32 v37, v37
	v_exp_f32_e32 v38, v38
	v_exp_f32_e32 v39, v39
	v_exp_f32_e32 v40, v40
	v_exp_f32_e32 v41, v41
	v_exp_f32_e32 v42, v42
	v_exp_f32_e32 v43, v43
	v_exp_f32_e32 v44, v44
	v_exp_f32_e32 v45, v45
	v_exp_f32_e32 v46, v46
	v_exp_f32_e32 v47, v47
	v_cvt_pk_bf16_f32 v64, v32, v33
	v_cvt_pk_bf16_f32 v65, v34, v35
	v_cvt_pk_bf16_f32 v66, v36, v37
	v_cvt_pk_bf16_f32 v67, v38, v39
	v_cvt_pk_bf16_f32 v68, v40, v41
	v_cvt_pk_bf16_f32 v69, v42, v43
	v_cvt_pk_bf16_f32 v70, v44, v45
	v_cvt_pk_bf16_f32 v71, v46, v47
	v_pk_add_f32 v[232:233], v[232:233], v[32:33]
	v_pk_add_f32 v[232:233], v[232:233], v[34:35]
	v_pk_add_f32 v[232:233], v[232:233], v[36:37]
	v_pk_add_f32 v[232:233], v[232:233], v[38:39]
	v_pk_add_f32 v[232:233], v[232:233], v[40:41]
	v_pk_add_f32 v[232:233], v[232:233], v[42:43]
	v_pk_add_f32 v[232:233], v[232:233], v[44:45]
	v_pk_add_f32 v[232:233], v[232:233], v[46:47]
	s_waitcnt lgkmcnt(0)
	v_mfma_f32_32x32x16_bf16 v[0:15], v[64:67], v[72:75], v[0:15]
	v_mfma_f32_32x32x16_bf16 v[16:31], v[64:67], v[76:79], v[16:31]
	v_mfma_f32_32x32x16_bf16 v[0:15], v[68:71], v[220:223], v[0:15]
	v_mfma_f32_32x32x16_bf16 v[16:31], v[68:71], v[224:227], v[16:31]
	global_load_dwordx4 v[116:119], v80, s[84:85]
	global_load_dwordx4 v[120:123], v80, s[84:85] offset:32
	global_load_dwordx4 v[124:127], v80, s[84:85] offset:64
	global_load_dwordx4 v[128:131], v80, s[84:85] offset:96
	global_load_dwordx4 v[132:135], v100, s[84:85] offset:768
	global_load_dwordx4 v[136:139], v149, s[84:85] offset:768
	global_load_dwordx4 v[140:143], v100, s[84:85] offset:832
	global_load_dwordx4 v[144:147], v149, s[84:85] offset:832
	s_add_u32 s84, s84, 0x30000
	s_addc_u32 s85, s85, 0
	s_waitcnt vmcnt(16)
	ds_write_b128 v112, v[172:175]
	ds_write_b128 v112, v[176:179] offset:1024
	ds_write_b128 v112, v[180:183] offset:2048
	ds_write_b128 v112, v[184:187] offset:3072
	ds_read2_b32 v[32:33], v115 offset0:160 offset1:161
	ds_read2_b32 v[34:35], v115 offset0:162 offset1:163
	ds_read2_b32 v[36:37], v115 offset0:168 offset1:169
	ds_read2_b32 v[38:39], v115 offset0:170 offset1:171
	ds_read2_b32 v[40:41], v115 offset0:176 offset1:177
	ds_read2_b32 v[42:43], v115 offset0:178 offset1:179
	ds_read2_b32 v[44:45], v115 offset0:184 offset1:185
	ds_read2_b32 v[46:47], v115 offset0:186 offset1:187
	s_waitcnt lgkmcnt(0)
	v_mfma_f32_32x32x16_bf16 v[32:47], v[156:159], v[48:51], v[32:47]
	ds_read_b64_tr_b16 v[72:73], v231
	ds_read_b64_tr_b16 v[74:75], v231 offset:512
	ds_read_b64_tr_b16 v[76:77], v231 offset:2048
	ds_read_b64_tr_b16 v[78:79], v231 offset:2560
	ds_read_b64_tr_b16 v[220:221], v231 offset:1024
	ds_read_b64_tr_b16 v[222:223], v231 offset:1536
	ds_read_b64_tr_b16 v[224:225], v231 offset:3072
	ds_read_b64_tr_b16 v[226:227], v231 offset:3584
	v_mfma_f32_32x32x16_bf16 v[32:47], v[160:163], v[52:55], v[32:47]
	v_mfma_f32_32x32x16_bf16 v[32:47], v[164:167], v[56:59], v[32:47]
	v_mfma_f32_32x32x16_bf16 v[32:47], v[168:171], v[60:63], v[32:47]
	s_nop 11
	v_exp_f32_e32 v32, v32
	v_exp_f32_e32 v33, v33
	v_exp_f32_e32 v34, v34
	v_exp_f32_e32 v35, v35
	v_exp_f32_e32 v36, v36
	v_exp_f32_e32 v37, v37
	v_exp_f32_e32 v38, v38
	v_exp_f32_e32 v39, v39
	v_exp_f32_e32 v40, v40
	v_exp_f32_e32 v41, v41
	v_exp_f32_e32 v42, v42
	v_exp_f32_e32 v43, v43
	v_exp_f32_e32 v44, v44
	v_exp_f32_e32 v45, v45
	v_exp_f32_e32 v46, v46
	v_exp_f32_e32 v47, v47
	v_cvt_pk_bf16_f32 v64, v32, v33
	v_cvt_pk_bf16_f32 v65, v34, v35
	v_cvt_pk_bf16_f32 v66, v36, v37
	v_cvt_pk_bf16_f32 v67, v38, v39
	v_cvt_pk_bf16_f32 v68, v40, v41
	v_cvt_pk_bf16_f32 v69, v42, v43
	v_cvt_pk_bf16_f32 v70, v44, v45
	v_cvt_pk_bf16_f32 v71, v46, v47
	v_pk_add_f32 v[232:233], v[232:233], v[32:33]
	v_pk_add_f32 v[232:233], v[232:233], v[34:35]
	v_pk_add_f32 v[232:233], v[232:233], v[36:37]
	v_pk_add_f32 v[232:233], v[232:233], v[38:39]
	v_pk_add_f32 v[232:233], v[232:233], v[40:41]
	v_pk_add_f32 v[232:233], v[232:233], v[42:43]
	v_pk_add_f32 v[232:233], v[232:233], v[44:45]
	v_pk_add_f32 v[232:233], v[232:233], v[46:47]
	s_waitcnt lgkmcnt(0)
	v_mfma_f32_32x32x16_bf16 v[0:15], v[64:67], v[72:75], v[0:15]
	v_mfma_f32_32x32x16_bf16 v[16:31], v[64:67], v[76:79], v[16:31]
	v_mfma_f32_32x32x16_bf16 v[0:15], v[68:71], v[220:223], v[0:15]
	v_mfma_f32_32x32x16_bf16 v[16:31], v[68:71], v[224:227], v[16:31]
	global_load_dwordx4 v[156:159], v80, s[84:85]
	global_load_dwordx4 v[160:163], v80, s[84:85] offset:32
	global_load_dwordx4 v[164:167], v80, s[84:85] offset:64
	global_load_dwordx4 v[168:171], v80, s[84:85] offset:96
	global_load_dwordx4 v[172:175], v100, s[84:85] offset:768
	global_load_dwordx4 v[176:179], v149, s[84:85] offset:768
	global_load_dwordx4 v[180:183], v100, s[84:85] offset:832
	global_load_dwordx4 v[184:187], v149, s[84:85] offset:832
	s_add_u32 s84, s84, 0x30000
	s_addc_u32 s85, s85, 0
	s_waitcnt vmcnt(16)
	ds_write_b128 v112, v[204:207]
	ds_write_b128 v112, v[208:211] offset:1024
	ds_write_b128 v112, v[212:215] offset:2048
	ds_write_b128 v112, v[216:219] offset:3072
	ds_read2_b32 v[32:33], v115 offset0:192 offset1:193
	ds_read2_b32 v[34:35], v115 offset0:194 offset1:195
	ds_read2_b32 v[36:37], v115 offset0:200 offset1:201
	ds_read2_b32 v[38:39], v115 offset0:202 offset1:203
	ds_read2_b32 v[40:41], v115 offset0:208 offset1:209
	ds_read2_b32 v[42:43], v115 offset0:210 offset1:211
	ds_read2_b32 v[44:45], v115 offset0:216 offset1:217
	ds_read2_b32 v[46:47], v115 offset0:218 offset1:219
	s_waitcnt lgkmcnt(0)
	v_mfma_f32_32x32x16_bf16 v[32:47], v[188:191], v[48:51], v[32:47]
	ds_read_b64_tr_b16 v[72:73], v231
	ds_read_b64_tr_b16 v[74:75], v231 offset:512
	ds_read_b64_tr_b16 v[76:77], v231 offset:2048
	ds_read_b64_tr_b16 v[78:79], v231 offset:2560
	ds_read_b64_tr_b16 v[220:221], v231 offset:1024
	ds_read_b64_tr_b16 v[222:223], v231 offset:1536
	ds_read_b64_tr_b16 v[224:225], v231 offset:3072
	ds_read_b64_tr_b16 v[226:227], v231 offset:3584
	v_mfma_f32_32x32x16_bf16 v[32:47], v[192:195], v[52:55], v[32:47]
	v_mfma_f32_32x32x16_bf16 v[32:47], v[196:199], v[56:59], v[32:47]
	v_mfma_f32_32x32x16_bf16 v[32:47], v[200:203], v[60:63], v[32:47]
	s_nop 11
	v_exp_f32_e32 v32, v32
	v_exp_f32_e32 v33, v33
	v_exp_f32_e32 v34, v34
	v_exp_f32_e32 v35, v35
	v_exp_f32_e32 v36, v36
	v_exp_f32_e32 v37, v37
	v_exp_f32_e32 v38, v38
	v_exp_f32_e32 v39, v39
	v_exp_f32_e32 v40, v40
	v_exp_f32_e32 v41, v41
	v_exp_f32_e32 v42, v42
	v_exp_f32_e32 v43, v43
	v_exp_f32_e32 v44, v44
	v_exp_f32_e32 v45, v45
	v_exp_f32_e32 v46, v46
	v_exp_f32_e32 v47, v47
	v_cvt_pk_bf16_f32 v64, v32, v33
	v_cvt_pk_bf16_f32 v65, v34, v35
	v_cvt_pk_bf16_f32 v66, v36, v37
	v_cvt_pk_bf16_f32 v67, v38, v39
	v_cvt_pk_bf16_f32 v68, v40, v41
	v_cvt_pk_bf16_f32 v69, v42, v43
	v_cvt_pk_bf16_f32 v70, v44, v45
	v_cvt_pk_bf16_f32 v71, v46, v47
	v_pk_add_f32 v[232:233], v[232:233], v[32:33]
	v_pk_add_f32 v[232:233], v[232:233], v[34:35]
	v_pk_add_f32 v[232:233], v[232:233], v[36:37]
	v_pk_add_f32 v[232:233], v[232:233], v[38:39]
	v_pk_add_f32 v[232:233], v[232:233], v[40:41]
	v_pk_add_f32 v[232:233], v[232:233], v[42:43]
	v_pk_add_f32 v[232:233], v[232:233], v[44:45]
	v_pk_add_f32 v[232:233], v[232:233], v[46:47]
	s_waitcnt lgkmcnt(0)
	v_mfma_f32_32x32x16_bf16 v[0:15], v[64:67], v[72:75], v[0:15]
	v_mfma_f32_32x32x16_bf16 v[16:31], v[64:67], v[76:79], v[16:31]
	v_mfma_f32_32x32x16_bf16 v[0:15], v[68:71], v[220:223], v[0:15]
	v_mfma_f32_32x32x16_bf16 v[16:31], v[68:71], v[224:227], v[16:31]
	global_load_dwordx4 v[188:191], v80, s[84:85]
	global_load_dwordx4 v[192:195], v80, s[84:85] offset:32
	global_load_dwordx4 v[196:199], v80, s[84:85] offset:64
	global_load_dwordx4 v[200:203], v80, s[84:85] offset:96
	global_load_dwordx4 v[204:207], v100, s[84:85] offset:768
	global_load_dwordx4 v[208:211], v149, s[84:85] offset:768
	global_load_dwordx4 v[212:215], v100, s[84:85] offset:832
	global_load_dwordx4 v[216:219], v149, s[84:85] offset:832
	s_add_u32 s84, s84, 0x30000
	s_addc_u32 s85, s85, 0
	s_waitcnt vmcnt(16)
	ds_write_b128 v112, v[132:135]
	ds_write_b128 v112, v[136:139] offset:1024
	ds_write_b128 v112, v[140:143] offset:2048
	ds_write_b128 v112, v[144:147] offset:3072
	ds_read2_b32 v[32:33], v115 offset0:224 offset1:225
	ds_read2_b32 v[34:35], v115 offset0:226 offset1:227
	ds_read2_b32 v[36:37], v115 offset0:232 offset1:233
	ds_read2_b32 v[38:39], v115 offset0:234 offset1:235
	ds_read2_b32 v[40:41], v115 offset0:240 offset1:241
	ds_read2_b32 v[42:43], v115 offset0:242 offset1:243
	ds_read2_b32 v[44:45], v115 offset0:248 offset1:249
	ds_read2_b32 v[46:47], v115 offset0:250 offset1:251
	s_waitcnt lgkmcnt(0)
	v_mfma_f32_32x32x16_bf16 v[32:47], v[116:119], v[48:51], v[32:47]
	ds_read_b64_tr_b16 v[72:73], v231
	ds_read_b64_tr_b16 v[74:75], v231 offset:512
	ds_read_b64_tr_b16 v[76:77], v231 offset:2048
	ds_read_b64_tr_b16 v[78:79], v231 offset:2560
	ds_read_b64_tr_b16 v[220:221], v231 offset:1024
	ds_read_b64_tr_b16 v[222:223], v231 offset:1536
	ds_read_b64_tr_b16 v[224:225], v231 offset:3072
	ds_read_b64_tr_b16 v[226:227], v231 offset:3584
	v_mfma_f32_32x32x16_bf16 v[32:47], v[120:123], v[52:55], v[32:47]
	v_mfma_f32_32x32x16_bf16 v[32:47], v[124:127], v[56:59], v[32:47]
	v_mfma_f32_32x32x16_bf16 v[32:47], v[128:131], v[60:63], v[32:47]
	s_nop 11
	v_exp_f32_e32 v32, v32
	v_exp_f32_e32 v33, v33
	v_exp_f32_e32 v34, v34
	v_exp_f32_e32 v35, v35
	v_exp_f32_e32 v36, v36
	v_exp_f32_e32 v37, v37
	v_exp_f32_e32 v38, v38
	v_exp_f32_e32 v39, v39
	v_exp_f32_e32 v40, v40
	v_exp_f32_e32 v41, v41
	v_exp_f32_e32 v42, v42
	v_exp_f32_e32 v43, v43
	v_exp_f32_e32 v44, v44
	v_exp_f32_e32 v45, v45
	v_exp_f32_e32 v46, v46
	v_exp_f32_e32 v47, v47
	v_cvt_pk_bf16_f32 v64, v32, v33
	v_cvt_pk_bf16_f32 v65, v34, v35
	v_cvt_pk_bf16_f32 v66, v36, v37
	v_cvt_pk_bf16_f32 v67, v38, v39
	v_cvt_pk_bf16_f32 v68, v40, v41
	v_cvt_pk_bf16_f32 v69, v42, v43
	v_cvt_pk_bf16_f32 v70, v44, v45
	v_cvt_pk_bf16_f32 v71, v46, v47
	v_pk_add_f32 v[232:233], v[232:233], v[32:33]
	v_pk_add_f32 v[232:233], v[232:233], v[34:35]
	v_pk_add_f32 v[232:233], v[232:233], v[36:37]
	v_pk_add_f32 v[232:233], v[232:233], v[38:39]
	v_pk_add_f32 v[232:233], v[232:233], v[40:41]
	v_pk_add_f32 v[232:233], v[232:233], v[42:43]
	v_pk_add_f32 v[232:233], v[232:233], v[44:45]
	v_pk_add_f32 v[232:233], v[232:233], v[46:47]
	s_waitcnt lgkmcnt(0)
	v_mfma_f32_32x32x16_bf16 v[0:15], v[64:67], v[72:75], v[0:15]
	v_mfma_f32_32x32x16_bf16 v[16:31], v[64:67], v[76:79], v[16:31]
	v_mfma_f32_32x32x16_bf16 v[0:15], v[68:71], v[220:223], v[0:15]
	v_mfma_f32_32x32x16_bf16 v[16:31], v[68:71], v[224:227], v[16:31]
	global_load_dwordx4 v[116:119], v80, s[84:85]
	global_load_dwordx4 v[120:123], v80, s[84:85] offset:32
	global_load_dwordx4 v[124:127], v80, s[84:85] offset:64
	global_load_dwordx4 v[128:131], v80, s[84:85] offset:96
	global_load_dwordx4 v[132:135], v100, s[84:85] offset:768
	global_load_dwordx4 v[136:139], v149, s[84:85] offset:768
	global_load_dwordx4 v[140:143], v100, s[84:85] offset:832
	global_load_dwordx4 v[144:147], v149, s[84:85] offset:832
	s_add_u32 s84, s84, 0x30000
	s_addc_u32 s85, s85, 0
	s_waitcnt vmcnt(16)
	ds_write_b128 v112, v[172:175]
	ds_write_b128 v112, v[176:179] offset:1024
	ds_write_b128 v112, v[180:183] offset:2048
	ds_write_b128 v112, v[184:187] offset:3072
	v_add_u32_e32 v115, 0x400, v115
	ds_read2_b32 v[32:33], v115 offset0:0 offset1:1
	ds_read2_b32 v[34:35], v115 offset0:2 offset1:3
	ds_read2_b32 v[36:37], v115 offset0:8 offset1:9
	ds_read2_b32 v[38:39], v115 offset0:10 offset1:11
	ds_read2_b32 v[40:41], v115 offset0:16 offset1:17
	ds_read2_b32 v[42:43], v115 offset0:18 offset1:19
	ds_read2_b32 v[44:45], v115 offset0:24 offset1:25
	ds_read2_b32 v[46:47], v115 offset0:26 offset1:27
	s_waitcnt lgkmcnt(0)
	v_mfma_f32_32x32x16_bf16 v[32:47], v[156:159], v[48:51], v[32:47]
	ds_read_b64_tr_b16 v[72:73], v231
	ds_read_b64_tr_b16 v[74:75], v231 offset:512
	ds_read_b64_tr_b16 v[76:77], v231 offset:2048
	ds_read_b64_tr_b16 v[78:79], v231 offset:2560
	ds_read_b64_tr_b16 v[220:221], v231 offset:1024
	ds_read_b64_tr_b16 v[222:223], v231 offset:1536
	ds_read_b64_tr_b16 v[224:225], v231 offset:3072
	ds_read_b64_tr_b16 v[226:227], v231 offset:3584
	v_mfma_f32_32x32x16_bf16 v[32:47], v[160:163], v[52:55], v[32:47]
	v_mfma_f32_32x32x16_bf16 v[32:47], v[164:167], v[56:59], v[32:47]
	v_mfma_f32_32x32x16_bf16 v[32:47], v[168:171], v[60:63], v[32:47]
	s_nop 11
	v_exp_f32_e32 v32, v32
	v_exp_f32_e32 v33, v33
	v_exp_f32_e32 v34, v34
	v_exp_f32_e32 v35, v35
	v_exp_f32_e32 v36, v36
	v_exp_f32_e32 v37, v37
	v_exp_f32_e32 v38, v38
	v_exp_f32_e32 v39, v39
	v_exp_f32_e32 v40, v40
	v_exp_f32_e32 v41, v41
	v_exp_f32_e32 v42, v42
	v_exp_f32_e32 v43, v43
	v_exp_f32_e32 v44, v44
	v_exp_f32_e32 v45, v45
	v_exp_f32_e32 v46, v46
	v_exp_f32_e32 v47, v47
	v_cvt_pk_bf16_f32 v64, v32, v33
	v_cvt_pk_bf16_f32 v65, v34, v35
	v_cvt_pk_bf16_f32 v66, v36, v37
	v_cvt_pk_bf16_f32 v67, v38, v39
	v_cvt_pk_bf16_f32 v68, v40, v41
	v_cvt_pk_bf16_f32 v69, v42, v43
	v_cvt_pk_bf16_f32 v70, v44, v45
	v_cvt_pk_bf16_f32 v71, v46, v47
	v_pk_add_f32 v[232:233], v[232:233], v[32:33]
	v_pk_add_f32 v[232:233], v[232:233], v[34:35]
	v_pk_add_f32 v[232:233], v[232:233], v[36:37]
	v_pk_add_f32 v[232:233], v[232:233], v[38:39]
	v_pk_add_f32 v[232:233], v[232:233], v[40:41]
	v_pk_add_f32 v[232:233], v[232:233], v[42:43]
	v_pk_add_f32 v[232:233], v[232:233], v[44:45]
	v_pk_add_f32 v[232:233], v[232:233], v[46:47]
	s_waitcnt lgkmcnt(0)
	v_mfma_f32_32x32x16_bf16 v[0:15], v[64:67], v[72:75], v[0:15]
	v_mfma_f32_32x32x16_bf16 v[16:31], v[64:67], v[76:79], v[16:31]
	v_mfma_f32_32x32x16_bf16 v[0:15], v[68:71], v[220:223], v[0:15]
	v_mfma_f32_32x32x16_bf16 v[16:31], v[68:71], v[224:227], v[16:31]
	global_load_dwordx4 v[156:159], v80, s[84:85]
	global_load_dwordx4 v[160:163], v80, s[84:85] offset:32
	global_load_dwordx4 v[164:167], v80, s[84:85] offset:64
	global_load_dwordx4 v[168:171], v80, s[84:85] offset:96
	global_load_dwordx4 v[172:175], v100, s[84:85] offset:768
	global_load_dwordx4 v[176:179], v149, s[84:85] offset:768
	global_load_dwordx4 v[180:183], v100, s[84:85] offset:832
	global_load_dwordx4 v[184:187], v149, s[84:85] offset:832
	s_waitcnt vmcnt(16)
	ds_write_b128 v112, v[204:207]
	ds_write_b128 v112, v[208:211] offset:1024
	ds_write_b128 v112, v[212:215] offset:2048
	ds_write_b128 v112, v[216:219] offset:3072
	ds_read2_b32 v[32:33], v115 offset0:32 offset1:33
	ds_read2_b32 v[34:35], v115 offset0:34 offset1:35
	ds_read2_b32 v[36:37], v115 offset0:40 offset1:41
	ds_read2_b32 v[38:39], v115 offset0:42 offset1:43
	ds_read2_b32 v[40:41], v115 offset0:48 offset1:49
	ds_read2_b32 v[42:43], v115 offset0:50 offset1:51
	ds_read2_b32 v[44:45], v115 offset0:56 offset1:57
	ds_read2_b32 v[46:47], v115 offset0:58 offset1:59
	s_waitcnt lgkmcnt(0)
	v_mfma_f32_32x32x16_bf16 v[32:47], v[188:191], v[48:51], v[32:47]
	ds_read_b64_tr_b16 v[72:73], v231
	ds_read_b64_tr_b16 v[74:75], v231 offset:512
	ds_read_b64_tr_b16 v[76:77], v231 offset:2048
	ds_read_b64_tr_b16 v[78:79], v231 offset:2560
	ds_read_b64_tr_b16 v[220:221], v231 offset:1024
	ds_read_b64_tr_b16 v[222:223], v231 offset:1536
	ds_read_b64_tr_b16 v[224:225], v231 offset:3072
	ds_read_b64_tr_b16 v[226:227], v231 offset:3584
	v_mfma_f32_32x32x16_bf16 v[32:47], v[192:195], v[52:55], v[32:47]
	v_mfma_f32_32x32x16_bf16 v[32:47], v[196:199], v[56:59], v[32:47]
	v_mfma_f32_32x32x16_bf16 v[32:47], v[200:203], v[60:63], v[32:47]
	s_nop 11
	v_exp_f32_e32 v32, v32
	v_exp_f32_e32 v33, v33
	v_exp_f32_e32 v34, v34
	v_exp_f32_e32 v35, v35
	v_exp_f32_e32 v36, v36
	v_exp_f32_e32 v37, v37
	v_exp_f32_e32 v38, v38
	v_exp_f32_e32 v39, v39
	v_exp_f32_e32 v40, v40
	v_exp_f32_e32 v41, v41
	v_exp_f32_e32 v42, v42
	v_exp_f32_e32 v43, v43
	v_exp_f32_e32 v44, v44
	v_exp_f32_e32 v45, v45
	v_exp_f32_e32 v46, v46
	v_exp_f32_e32 v47, v47
	v_cvt_pk_bf16_f32 v64, v32, v33
	v_cvt_pk_bf16_f32 v65, v34, v35
	v_cvt_pk_bf16_f32 v66, v36, v37
	v_cvt_pk_bf16_f32 v67, v38, v39
	v_cvt_pk_bf16_f32 v68, v40, v41
	v_cvt_pk_bf16_f32 v69, v42, v43
	v_cvt_pk_bf16_f32 v70, v44, v45
	v_cvt_pk_bf16_f32 v71, v46, v47
	v_pk_add_f32 v[232:233], v[232:233], v[32:33]
	v_pk_add_f32 v[232:233], v[232:233], v[34:35]
	v_pk_add_f32 v[232:233], v[232:233], v[36:37]
	v_pk_add_f32 v[232:233], v[232:233], v[38:39]
	v_pk_add_f32 v[232:233], v[232:233], v[40:41]
	v_pk_add_f32 v[232:233], v[232:233], v[42:43]
	v_pk_add_f32 v[232:233], v[232:233], v[44:45]
	v_pk_add_f32 v[232:233], v[232:233], v[46:47]
	s_waitcnt lgkmcnt(0)
	v_mfma_f32_32x32x16_bf16 v[0:15], v[64:67], v[72:75], v[0:15]
	v_mfma_f32_32x32x16_bf16 v[16:31], v[64:67], v[76:79], v[16:31]
	v_mfma_f32_32x32x16_bf16 v[0:15], v[68:71], v[220:223], v[0:15]
	v_mfma_f32_32x32x16_bf16 v[16:31], v[68:71], v[224:227], v[16:31]
	global_load_dwordx4 v[188:191], v83, s[86:87]
	global_load_dwordx4 v[192:195], v83, s[86:87] offset:32
	global_load_dwordx4 v[196:199], v83, s[86:87] offset:64
	global_load_dwordx4 v[200:203], v83, s[86:87] offset:96
	global_load_dwordx4 v[204:207], v101, s[86:87] offset:768
	global_load_dwordx4 v[208:211], v150, s[86:87] offset:768
	global_load_dwordx4 v[212:215], v101, s[86:87] offset:832
	global_load_dwordx4 v[216:219], v150, s[86:87] offset:832
	s_add_u32 s86, s86, 0xc0000
	s_addc_u32 s87, s87, 0
	s_waitcnt vmcnt(16)
	ds_write_b128 v112, v[132:135]
	ds_write_b128 v112, v[136:139] offset:1024
	ds_write_b128 v112, v[140:143] offset:2048
	ds_write_b128 v112, v[144:147] offset:3072
	ds_read2_b32 v[32:33], v115 offset0:64 offset1:65
	ds_read2_b32 v[34:35], v115 offset0:66 offset1:67
	ds_read2_b32 v[36:37], v115 offset0:72 offset1:73
	ds_read2_b32 v[38:39], v115 offset0:74 offset1:75
	ds_read2_b32 v[40:41], v115 offset0:80 offset1:81
	ds_read2_b32 v[42:43], v115 offset0:82 offset1:83
	ds_read2_b32 v[44:45], v115 offset0:88 offset1:89
	ds_read2_b32 v[46:47], v115 offset0:90 offset1:91
	s_waitcnt lgkmcnt(0)
	v_mfma_f32_32x32x16_bf16 v[32:47], v[116:119], v[48:51], v[32:47]
	ds_read_b64_tr_b16 v[72:73], v231
	ds_read_b64_tr_b16 v[74:75], v231 offset:512
	ds_read_b64_tr_b16 v[76:77], v231 offset:2048
	ds_read_b64_tr_b16 v[78:79], v231 offset:2560
	ds_read_b64_tr_b16 v[220:221], v231 offset:1024
	ds_read_b64_tr_b16 v[222:223], v231 offset:1536
	ds_read_b64_tr_b16 v[224:225], v231 offset:3072
	ds_read_b64_tr_b16 v[226:227], v231 offset:3584
	v_mfma_f32_32x32x16_bf16 v[32:47], v[120:123], v[52:55], v[32:47]
	v_mfma_f32_32x32x16_bf16 v[32:47], v[124:127], v[56:59], v[32:47]
	v_mfma_f32_32x32x16_bf16 v[32:47], v[128:131], v[60:63], v[32:47]
	s_nop 11
	v_exp_f32_e32 v32, v32
	v_exp_f32_e32 v33, v33
	v_exp_f32_e32 v34, v34
	v_exp_f32_e32 v35, v35
	v_exp_f32_e32 v36, v36
	v_exp_f32_e32 v37, v37
	v_exp_f32_e32 v38, v38
	v_exp_f32_e32 v39, v39
	v_exp_f32_e32 v40, v40
	v_exp_f32_e32 v41, v41
	v_exp_f32_e32 v42, v42
	v_exp_f32_e32 v43, v43
	v_exp_f32_e32 v44, v44
	v_exp_f32_e32 v45, v45
	v_exp_f32_e32 v46, v46
	v_exp_f32_e32 v47, v47
	v_cvt_pk_bf16_f32 v64, v32, v33
	v_cvt_pk_bf16_f32 v65, v34, v35
	v_cvt_pk_bf16_f32 v66, v36, v37
	v_cvt_pk_bf16_f32 v67, v38, v39
	v_cvt_pk_bf16_f32 v68, v40, v41
	v_cvt_pk_bf16_f32 v69, v42, v43
	v_cvt_pk_bf16_f32 v70, v44, v45
	v_cvt_pk_bf16_f32 v71, v46, v47
	v_pk_add_f32 v[232:233], v[232:233], v[32:33]
	v_pk_add_f32 v[232:233], v[232:233], v[34:35]
	v_pk_add_f32 v[232:233], v[232:233], v[36:37]
	v_pk_add_f32 v[232:233], v[232:233], v[38:39]
	v_pk_add_f32 v[232:233], v[232:233], v[40:41]
	v_pk_add_f32 v[232:233], v[232:233], v[42:43]
	v_pk_add_f32 v[232:233], v[232:233], v[44:45]
	v_pk_add_f32 v[232:233], v[232:233], v[46:47]
	s_waitcnt lgkmcnt(0)
	v_mfma_f32_32x32x16_bf16 v[0:15], v[64:67], v[72:75], v[0:15]
	v_mfma_f32_32x32x16_bf16 v[16:31], v[64:67], v[76:79], v[16:31]
	v_mfma_f32_32x32x16_bf16 v[0:15], v[68:71], v[220:223], v[0:15]
	v_mfma_f32_32x32x16_bf16 v[16:31], v[68:71], v[224:227], v[16:31]
	global_load_dwordx4 v[116:119], v83, s[86:87]
	global_load_dwordx4 v[120:123], v83, s[86:87] offset:32
	global_load_dwordx4 v[124:127], v83, s[86:87] offset:64
	global_load_dwordx4 v[128:131], v83, s[86:87] offset:96
	global_load_dwordx4 v[132:135], v101, s[86:87] offset:768
	global_load_dwordx4 v[136:139], v150, s[86:87] offset:768
	global_load_dwordx4 v[140:143], v101, s[86:87] offset:832
	global_load_dwordx4 v[144:147], v150, s[86:87] offset:832
	s_add_u32 s86, s86, 0xc0000
	s_addc_u32 s87, s87, 0
	s_waitcnt vmcnt(16)
	ds_write_b128 v112, v[172:175]
	ds_write_b128 v112, v[176:179] offset:1024
	ds_write_b128 v112, v[180:183] offset:2048
	ds_write_b128 v112, v[184:187] offset:3072
	ds_read2_b32 v[32:33], v115 offset0:96 offset1:97
	ds_read2_b32 v[34:35], v115 offset0:98 offset1:99
	ds_read2_b32 v[36:37], v115 offset0:104 offset1:105
	ds_read2_b32 v[38:39], v115 offset0:106 offset1:107
	ds_read2_b32 v[40:41], v115 offset0:112 offset1:113
	ds_read2_b32 v[42:43], v115 offset0:114 offset1:115
	ds_read2_b32 v[44:45], v115 offset0:120 offset1:121
	ds_read2_b32 v[46:47], v115 offset0:122 offset1:123
	s_waitcnt lgkmcnt(0)
	v_mfma_f32_32x32x16_bf16 v[32:47], v[156:159], v[48:51], v[32:47]
	ds_read_b64_tr_b16 v[72:73], v231
	ds_read_b64_tr_b16 v[74:75], v231 offset:512
	ds_read_b64_tr_b16 v[76:77], v231 offset:2048
	ds_read_b64_tr_b16 v[78:79], v231 offset:2560
	ds_read_b64_tr_b16 v[220:221], v231 offset:1024
	ds_read_b64_tr_b16 v[222:223], v231 offset:1536
	ds_read_b64_tr_b16 v[224:225], v231 offset:3072
	ds_read_b64_tr_b16 v[226:227], v231 offset:3584
	v_mfma_f32_32x32x16_bf16 v[32:47], v[160:163], v[52:55], v[32:47]
	v_mfma_f32_32x32x16_bf16 v[32:47], v[164:167], v[56:59], v[32:47]
	v_mfma_f32_32x32x16_bf16 v[32:47], v[168:171], v[60:63], v[32:47]
	s_nop 11
	v_exp_f32_e32 v32, v32
	v_exp_f32_e32 v33, v33
	v_exp_f32_e32 v34, v34
	v_exp_f32_e32 v35, v35
	v_exp_f32_e32 v36, v36
	v_exp_f32_e32 v37, v37
	v_exp_f32_e32 v38, v38
	v_exp_f32_e32 v39, v39
	v_exp_f32_e32 v40, v40
	v_exp_f32_e32 v41, v41
	v_exp_f32_e32 v42, v42
	v_exp_f32_e32 v43, v43
	v_exp_f32_e32 v44, v44
	v_exp_f32_e32 v45, v45
	v_exp_f32_e32 v46, v46
	v_exp_f32_e32 v47, v47
	v_cvt_pk_bf16_f32 v64, v32, v33
	v_cvt_pk_bf16_f32 v65, v34, v35
	v_cvt_pk_bf16_f32 v66, v36, v37
	v_cvt_pk_bf16_f32 v67, v38, v39
	v_cvt_pk_bf16_f32 v68, v40, v41
	v_cvt_pk_bf16_f32 v69, v42, v43
	v_cvt_pk_bf16_f32 v70, v44, v45
	v_cvt_pk_bf16_f32 v71, v46, v47
	v_pk_add_f32 v[232:233], v[232:233], v[32:33]
	v_pk_add_f32 v[232:233], v[232:233], v[34:35]
	v_pk_add_f32 v[232:233], v[232:233], v[36:37]
	v_pk_add_f32 v[232:233], v[232:233], v[38:39]
	v_pk_add_f32 v[232:233], v[232:233], v[40:41]
	v_pk_add_f32 v[232:233], v[232:233], v[42:43]
	v_pk_add_f32 v[232:233], v[232:233], v[44:45]
	v_pk_add_f32 v[232:233], v[232:233], v[46:47]
	s_waitcnt lgkmcnt(0)
	v_mfma_f32_32x32x16_bf16 v[0:15], v[64:67], v[72:75], v[0:15]
	v_mfma_f32_32x32x16_bf16 v[16:31], v[64:67], v[76:79], v[16:31]
	v_mfma_f32_32x32x16_bf16 v[0:15], v[68:71], v[220:223], v[0:15]
	v_mfma_f32_32x32x16_bf16 v[16:31], v[68:71], v[224:227], v[16:31]
	global_load_dwordx4 v[156:159], v83, s[86:87]
	global_load_dwordx4 v[160:163], v83, s[86:87] offset:32
	global_load_dwordx4 v[164:167], v83, s[86:87] offset:64
	global_load_dwordx4 v[168:171], v83, s[86:87] offset:96
	global_load_dwordx4 v[172:175], v101, s[86:87] offset:768
	global_load_dwordx4 v[176:179], v150, s[86:87] offset:768
	global_load_dwordx4 v[180:183], v101, s[86:87] offset:832
	global_load_dwordx4 v[184:187], v150, s[86:87] offset:832
	s_add_u32 s86, s86, 0xc0000
	s_addc_u32 s87, s87, 0
	s_waitcnt vmcnt(16)
	ds_write_b128 v112, v[204:207]
	ds_write_b128 v112, v[208:211] offset:1024
	ds_write_b128 v112, v[212:215] offset:2048
	ds_write_b128 v112, v[216:219] offset:3072
	v_mov_b32_e32 v115, v229
	ds_read2_b32 v[32:33], v115 offset0:0 offset1:1
	ds_read2_b32 v[34:35], v115 offset0:2 offset1:3
	ds_read2_b32 v[36:37], v115 offset0:8 offset1:9
	ds_read2_b32 v[38:39], v115 offset0:10 offset1:11
	ds_read2_b32 v[40:41], v115 offset0:16 offset1:17
	ds_read2_b32 v[42:43], v115 offset0:18 offset1:19
	ds_read2_b32 v[44:45], v115 offset0:24 offset1:25
	ds_read2_b32 v[46:47], v115 offset0:26 offset1:27
	s_waitcnt lgkmcnt(0)
	v_mfma_f32_32x32x16_bf16 v[32:47], v[188:191], v[48:51], v[32:47]
	ds_read_b64_tr_b16 v[72:73], v231
	ds_read_b64_tr_b16 v[74:75], v231 offset:512
	ds_read_b64_tr_b16 v[76:77], v231 offset:2048
	ds_read_b64_tr_b16 v[78:79], v231 offset:2560
	ds_read_b64_tr_b16 v[220:221], v231 offset:1024
	ds_read_b64_tr_b16 v[222:223], v231 offset:1536
	ds_read_b64_tr_b16 v[224:225], v231 offset:3072
	ds_read_b64_tr_b16 v[226:227], v231 offset:3584
	v_mfma_f32_32x32x16_bf16 v[32:47], v[192:195], v[52:55], v[32:47]
	v_mfma_f32_32x32x16_bf16 v[32:47], v[196:199], v[56:59], v[32:47]
	v_mfma_f32_32x32x16_bf16 v[32:47], v[200:203], v[60:63], v[32:47]
	s_nop 11
	v_exp_f32_e32 v32, v32
	v_exp_f32_e32 v33, v33
	v_exp_f32_e32 v34, v34
	v_exp_f32_e32 v35, v35
	v_exp_f32_e32 v36, v36
	v_exp_f32_e32 v37, v37
	v_exp_f32_e32 v38, v38
	v_exp_f32_e32 v39, v39
	v_exp_f32_e32 v40, v40
	v_exp_f32_e32 v41, v41
	v_exp_f32_e32 v42, v42
	v_exp_f32_e32 v43, v43
	v_exp_f32_e32 v44, v44
	v_exp_f32_e32 v45, v45
	v_exp_f32_e32 v46, v46
	v_exp_f32_e32 v47, v47
	v_cvt_pk_bf16_f32 v64, v32, v33
	v_cvt_pk_bf16_f32 v65, v34, v35
	v_cvt_pk_bf16_f32 v66, v36, v37
	v_cvt_pk_bf16_f32 v67, v38, v39
	v_cvt_pk_bf16_f32 v68, v40, v41
	v_cvt_pk_bf16_f32 v69, v42, v43
	v_cvt_pk_bf16_f32 v70, v44, v45
	v_cvt_pk_bf16_f32 v71, v46, v47
	v_pk_add_f32 v[232:233], v[232:233], v[32:33]
	v_pk_add_f32 v[232:233], v[232:233], v[34:35]
	v_pk_add_f32 v[232:233], v[232:233], v[36:37]
	v_pk_add_f32 v[232:233], v[232:233], v[38:39]
	v_pk_add_f32 v[232:233], v[232:233], v[40:41]
	v_pk_add_f32 v[232:233], v[232:233], v[42:43]
	v_pk_add_f32 v[232:233], v[232:233], v[44:45]
	v_pk_add_f32 v[232:233], v[232:233], v[46:47]
	s_waitcnt lgkmcnt(0)
	v_mfma_f32_32x32x16_bf16 v[0:15], v[64:67], v[72:75], v[0:15]
	v_mfma_f32_32x32x16_bf16 v[16:31], v[64:67], v[76:79], v[16:31]
	v_mfma_f32_32x32x16_bf16 v[0:15], v[68:71], v[220:223], v[0:15]
	v_mfma_f32_32x32x16_bf16 v[16:31], v[68:71], v[224:227], v[16:31]
	global_load_dwordx4 v[188:191], v83, s[86:87]
	global_load_dwordx4 v[192:195], v83, s[86:87] offset:32
	global_load_dwordx4 v[196:199], v83, s[86:87] offset:64
	global_load_dwordx4 v[200:203], v83, s[86:87] offset:96
	global_load_dwordx4 v[204:207], v101, s[86:87] offset:768
	global_load_dwordx4 v[208:211], v150, s[86:87] offset:768
	global_load_dwordx4 v[212:215], v101, s[86:87] offset:832
	global_load_dwordx4 v[216:219], v150, s[86:87] offset:832
	s_add_u32 s86, s86, 0xc0000
	s_addc_u32 s87, s87, 0
	s_waitcnt vmcnt(16)
	ds_write_b128 v112, v[132:135]
	ds_write_b128 v112, v[136:139] offset:1024
	ds_write_b128 v112, v[140:143] offset:2048
	ds_write_b128 v112, v[144:147] offset:3072
	ds_read2_b32 v[32:33], v115 offset0:32 offset1:33
	ds_read2_b32 v[34:35], v115 offset0:34 offset1:35
	ds_read2_b32 v[36:37], v115 offset0:40 offset1:41
	ds_read2_b32 v[38:39], v115 offset0:42 offset1:43
	ds_read2_b32 v[40:41], v115 offset0:48 offset1:49
	ds_read2_b32 v[42:43], v115 offset0:50 offset1:51
	ds_read2_b32 v[44:45], v115 offset0:56 offset1:57
	ds_read2_b32 v[46:47], v115 offset0:58 offset1:59
	s_waitcnt lgkmcnt(0)
	v_mfma_f32_32x32x16_bf16 v[32:47], v[116:119], v[48:51], v[32:47]
	ds_read_b64_tr_b16 v[72:73], v231
	ds_read_b64_tr_b16 v[74:75], v231 offset:512
	ds_read_b64_tr_b16 v[76:77], v231 offset:2048
	ds_read_b64_tr_b16 v[78:79], v231 offset:2560
	ds_read_b64_tr_b16 v[220:221], v231 offset:1024
	ds_read_b64_tr_b16 v[222:223], v231 offset:1536
	ds_read_b64_tr_b16 v[224:225], v231 offset:3072
	ds_read_b64_tr_b16 v[226:227], v231 offset:3584
	v_mfma_f32_32x32x16_bf16 v[32:47], v[120:123], v[52:55], v[32:47]
	v_mfma_f32_32x32x16_bf16 v[32:47], v[124:127], v[56:59], v[32:47]
	v_mfma_f32_32x32x16_bf16 v[32:47], v[128:131], v[60:63], v[32:47]
	s_nop 11
	v_exp_f32_e32 v32, v32
	v_exp_f32_e32 v33, v33
	v_exp_f32_e32 v34, v34
	v_exp_f32_e32 v35, v35
	v_exp_f32_e32 v36, v36
	v_exp_f32_e32 v37, v37
	v_exp_f32_e32 v38, v38
	v_exp_f32_e32 v39, v39
	v_exp_f32_e32 v40, v40
	v_exp_f32_e32 v41, v41
	v_exp_f32_e32 v42, v42
	v_exp_f32_e32 v43, v43
	v_exp_f32_e32 v44, v44
	v_exp_f32_e32 v45, v45
	v_exp_f32_e32 v46, v46
	v_exp_f32_e32 v47, v47
	v_cvt_pk_bf16_f32 v64, v32, v33
	v_cvt_pk_bf16_f32 v65, v34, v35
	v_cvt_pk_bf16_f32 v66, v36, v37
	v_cvt_pk_bf16_f32 v67, v38, v39
	v_cvt_pk_bf16_f32 v68, v40, v41
	v_cvt_pk_bf16_f32 v69, v42, v43
	v_cvt_pk_bf16_f32 v70, v44, v45
	v_cvt_pk_bf16_f32 v71, v46, v47
	v_pk_add_f32 v[232:233], v[232:233], v[32:33]
	v_pk_add_f32 v[232:233], v[232:233], v[34:35]
	v_pk_add_f32 v[232:233], v[232:233], v[36:37]
	v_pk_add_f32 v[232:233], v[232:233], v[38:39]
	v_pk_add_f32 v[232:233], v[232:233], v[40:41]
	v_pk_add_f32 v[232:233], v[232:233], v[42:43]
	v_pk_add_f32 v[232:233], v[232:233], v[44:45]
	v_pk_add_f32 v[232:233], v[232:233], v[46:47]
	s_waitcnt lgkmcnt(0)
	v_mfma_f32_32x32x16_bf16 v[0:15], v[64:67], v[72:75], v[0:15]
	v_mfma_f32_32x32x16_bf16 v[16:31], v[64:67], v[76:79], v[16:31]
	v_mfma_f32_32x32x16_bf16 v[0:15], v[68:71], v[220:223], v[0:15]
	v_mfma_f32_32x32x16_bf16 v[16:31], v[68:71], v[224:227], v[16:31]
	global_load_dwordx4 v[116:119], v83, s[86:87]
	global_load_dwordx4 v[120:123], v83, s[86:87] offset:32
	global_load_dwordx4 v[124:127], v83, s[86:87] offset:64
	global_load_dwordx4 v[128:131], v83, s[86:87] offset:96
	global_load_dwordx4 v[132:135], v101, s[86:87] offset:768
	global_load_dwordx4 v[136:139], v150, s[86:87] offset:768
	global_load_dwordx4 v[140:143], v101, s[86:87] offset:832
	global_load_dwordx4 v[144:147], v150, s[86:87] offset:832
	s_add_u32 s86, s86, 0xc0000
	s_addc_u32 s87, s87, 0
	s_waitcnt vmcnt(16)
	ds_write_b128 v112, v[172:175]
	ds_write_b128 v112, v[176:179] offset:1024
	ds_write_b128 v112, v[180:183] offset:2048
	ds_write_b128 v112, v[184:187] offset:3072
	ds_read2_b32 v[32:33], v115 offset0:64 offset1:65
	ds_read2_b32 v[34:35], v115 offset0:66 offset1:67
	ds_read2_b32 v[36:37], v115 offset0:72 offset1:73
	ds_read2_b32 v[38:39], v115 offset0:74 offset1:75
	ds_read2_b32 v[40:41], v115 offset0:80 offset1:81
	ds_read2_b32 v[42:43], v115 offset0:82 offset1:83
	ds_read2_b32 v[44:45], v115 offset0:88 offset1:89
	ds_read2_b32 v[46:47], v115 offset0:90 offset1:91
	s_waitcnt lgkmcnt(0)
	v_mfma_f32_32x32x16_bf16 v[32:47], v[156:159], v[48:51], v[32:47]
	ds_read_b64_tr_b16 v[72:73], v231
	ds_read_b64_tr_b16 v[74:75], v231 offset:512
	ds_read_b64_tr_b16 v[76:77], v231 offset:2048
	ds_read_b64_tr_b16 v[78:79], v231 offset:2560
	ds_read_b64_tr_b16 v[220:221], v231 offset:1024
	ds_read_b64_tr_b16 v[222:223], v231 offset:1536
	ds_read_b64_tr_b16 v[224:225], v231 offset:3072
	ds_read_b64_tr_b16 v[226:227], v231 offset:3584
	v_mfma_f32_32x32x16_bf16 v[32:47], v[160:163], v[52:55], v[32:47]
	v_mfma_f32_32x32x16_bf16 v[32:47], v[164:167], v[56:59], v[32:47]
	v_mfma_f32_32x32x16_bf16 v[32:47], v[168:171], v[60:63], v[32:47]
	s_nop 11
	v_exp_f32_e32 v32, v32
	v_exp_f32_e32 v33, v33
	v_exp_f32_e32 v34, v34
	v_exp_f32_e32 v35, v35
	v_exp_f32_e32 v36, v36
	v_exp_f32_e32 v37, v37
	v_exp_f32_e32 v38, v38
	v_exp_f32_e32 v39, v39
	v_exp_f32_e32 v40, v40
	v_exp_f32_e32 v41, v41
	v_exp_f32_e32 v42, v42
	v_exp_f32_e32 v43, v43
	v_exp_f32_e32 v44, v44
	v_exp_f32_e32 v45, v45
	v_exp_f32_e32 v46, v46
	v_exp_f32_e32 v47, v47
	v_cvt_pk_bf16_f32 v64, v32, v33
	v_cvt_pk_bf16_f32 v65, v34, v35
	v_cvt_pk_bf16_f32 v66, v36, v37
	v_cvt_pk_bf16_f32 v67, v38, v39
	v_cvt_pk_bf16_f32 v68, v40, v41
	v_cvt_pk_bf16_f32 v69, v42, v43
	v_cvt_pk_bf16_f32 v70, v44, v45
	v_cvt_pk_bf16_f32 v71, v46, v47
	v_pk_add_f32 v[232:233], v[232:233], v[32:33]
	v_pk_add_f32 v[232:233], v[232:233], v[34:35]
	v_pk_add_f32 v[232:233], v[232:233], v[36:37]
	v_pk_add_f32 v[232:233], v[232:233], v[38:39]
	v_pk_add_f32 v[232:233], v[232:233], v[40:41]
	v_pk_add_f32 v[232:233], v[232:233], v[42:43]
	v_pk_add_f32 v[232:233], v[232:233], v[44:45]
	v_pk_add_f32 v[232:233], v[232:233], v[46:47]
	s_waitcnt lgkmcnt(0)
	v_mfma_f32_32x32x16_bf16 v[0:15], v[64:67], v[72:75], v[0:15]
	v_mfma_f32_32x32x16_bf16 v[16:31], v[64:67], v[76:79], v[16:31]
	v_mfma_f32_32x32x16_bf16 v[0:15], v[68:71], v[220:223], v[0:15]
	v_mfma_f32_32x32x16_bf16 v[16:31], v[68:71], v[224:227], v[16:31]
	global_load_dwordx4 v[156:159], v83, s[86:87]
	global_load_dwordx4 v[160:163], v83, s[86:87] offset:32
	global_load_dwordx4 v[164:167], v83, s[86:87] offset:64
	global_load_dwordx4 v[168:171], v83, s[86:87] offset:96
	global_load_dwordx4 v[172:175], v101, s[86:87] offset:768
	global_load_dwordx4 v[176:179], v150, s[86:87] offset:768
	global_load_dwordx4 v[180:183], v101, s[86:87] offset:832
	global_load_dwordx4 v[184:187], v150, s[86:87] offset:832
	s_add_u32 s86, s86, 0xc0000
	s_addc_u32 s87, s87, 0
	s_waitcnt vmcnt(16)
	ds_write_b128 v112, v[204:207]
	ds_write_b128 v112, v[208:211] offset:1024
	ds_write_b128 v112, v[212:215] offset:2048
	ds_write_b128 v112, v[216:219] offset:3072
	ds_read2_b32 v[32:33], v115 offset0:96 offset1:97
	ds_read2_b32 v[34:35], v115 offset0:98 offset1:99
	ds_read2_b32 v[36:37], v115 offset0:104 offset1:105
	ds_read2_b32 v[38:39], v115 offset0:106 offset1:107
	ds_read2_b32 v[40:41], v115 offset0:112 offset1:113
	ds_read2_b32 v[42:43], v115 offset0:114 offset1:115
	ds_read2_b32 v[44:45], v115 offset0:120 offset1:121
	ds_read2_b32 v[46:47], v115 offset0:122 offset1:123
	s_waitcnt lgkmcnt(0)
	v_mfma_f32_32x32x16_bf16 v[32:47], v[188:191], v[48:51], v[32:47]
	ds_read_b64_tr_b16 v[72:73], v231
	ds_read_b64_tr_b16 v[74:75], v231 offset:512
	ds_read_b64_tr_b16 v[76:77], v231 offset:2048
	ds_read_b64_tr_b16 v[78:79], v231 offset:2560
	ds_read_b64_tr_b16 v[220:221], v231 offset:1024
	ds_read_b64_tr_b16 v[222:223], v231 offset:1536
	ds_read_b64_tr_b16 v[224:225], v231 offset:3072
	ds_read_b64_tr_b16 v[226:227], v231 offset:3584
	v_mfma_f32_32x32x16_bf16 v[32:47], v[192:195], v[52:55], v[32:47]
	v_mfma_f32_32x32x16_bf16 v[32:47], v[196:199], v[56:59], v[32:47]
	v_mfma_f32_32x32x16_bf16 v[32:47], v[200:203], v[60:63], v[32:47]
	s_nop 11
	v_exp_f32_e32 v32, v32
	v_exp_f32_e32 v33, v33
	v_exp_f32_e32 v34, v34
	v_exp_f32_e32 v35, v35
	v_exp_f32_e32 v36, v36
	v_exp_f32_e32 v37, v37
	v_exp_f32_e32 v38, v38
	v_exp_f32_e32 v39, v39
	v_exp_f32_e32 v40, v40
	v_exp_f32_e32 v41, v41
	v_exp_f32_e32 v42, v42
	v_exp_f32_e32 v43, v43
	v_exp_f32_e32 v44, v44
	v_exp_f32_e32 v45, v45
	v_exp_f32_e32 v46, v46
	v_exp_f32_e32 v47, v47
	v_cvt_pk_bf16_f32 v64, v32, v33
	v_cvt_pk_bf16_f32 v65, v34, v35
	v_cvt_pk_bf16_f32 v66, v36, v37
	v_cvt_pk_bf16_f32 v67, v38, v39
	v_cvt_pk_bf16_f32 v68, v40, v41
	v_cvt_pk_bf16_f32 v69, v42, v43
	v_cvt_pk_bf16_f32 v70, v44, v45
	v_cvt_pk_bf16_f32 v71, v46, v47
	v_pk_add_f32 v[232:233], v[232:233], v[32:33]
	v_pk_add_f32 v[232:233], v[232:233], v[34:35]
	v_pk_add_f32 v[232:233], v[232:233], v[36:37]
	v_pk_add_f32 v[232:233], v[232:233], v[38:39]
	v_pk_add_f32 v[232:233], v[232:233], v[40:41]
	v_pk_add_f32 v[232:233], v[232:233], v[42:43]
	v_pk_add_f32 v[232:233], v[232:233], v[44:45]
	v_pk_add_f32 v[232:233], v[232:233], v[46:47]
	s_waitcnt lgkmcnt(0)
	v_mfma_f32_32x32x16_bf16 v[0:15], v[64:67], v[72:75], v[0:15]
	v_mfma_f32_32x32x16_bf16 v[16:31], v[64:67], v[76:79], v[16:31]
	v_mfma_f32_32x32x16_bf16 v[0:15], v[68:71], v[220:223], v[0:15]
	v_mfma_f32_32x32x16_bf16 v[16:31], v[68:71], v[224:227], v[16:31]
	global_load_dwordx4 v[188:191], v83, s[86:87]
	global_load_dwordx4 v[192:195], v83, s[86:87] offset:32
	global_load_dwordx4 v[196:199], v83, s[86:87] offset:64
	global_load_dwordx4 v[200:203], v83, s[86:87] offset:96
	global_load_dwordx4 v[204:207], v101, s[86:87] offset:768
	global_load_dwordx4 v[208:211], v150, s[86:87] offset:768
	global_load_dwordx4 v[212:215], v101, s[86:87] offset:832
	global_load_dwordx4 v[216:219], v150, s[86:87] offset:832
	s_add_u32 s86, s86, 0xc0000
	s_addc_u32 s87, s87, 0
	s_waitcnt vmcnt(16)
	ds_write_b128 v112, v[132:135]
	ds_write_b128 v112, v[136:139] offset:1024
	ds_write_b128 v112, v[140:143] offset:2048
	ds_write_b128 v112, v[144:147] offset:3072
	ds_read2_b32 v[32:33], v115 offset0:128 offset1:129
	ds_read2_b32 v[34:35], v115 offset0:130 offset1:131
	ds_read2_b32 v[36:37], v115 offset0:136 offset1:137
	ds_read2_b32 v[38:39], v115 offset0:138 offset1:139
	ds_read2_b32 v[40:41], v115 offset0:144 offset1:145
	ds_read2_b32 v[42:43], v115 offset0:146 offset1:147
	ds_read2_b32 v[44:45], v115 offset0:152 offset1:153
	ds_read2_b32 v[46:47], v115 offset0:154 offset1:155
	s_waitcnt lgkmcnt(0)
	v_mfma_f32_32x32x16_bf16 v[32:47], v[116:119], v[48:51], v[32:47]
	ds_read_b64_tr_b16 v[72:73], v231
	ds_read_b64_tr_b16 v[74:75], v231 offset:512
	ds_read_b64_tr_b16 v[76:77], v231 offset:2048
	ds_read_b64_tr_b16 v[78:79], v231 offset:2560
	ds_read_b64_tr_b16 v[220:221], v231 offset:1024
	ds_read_b64_tr_b16 v[222:223], v231 offset:1536
	ds_read_b64_tr_b16 v[224:225], v231 offset:3072
	ds_read_b64_tr_b16 v[226:227], v231 offset:3584
	v_mfma_f32_32x32x16_bf16 v[32:47], v[120:123], v[52:55], v[32:47]
	v_mfma_f32_32x32x16_bf16 v[32:47], v[124:127], v[56:59], v[32:47]
	v_mfma_f32_32x32x16_bf16 v[32:47], v[128:131], v[60:63], v[32:47]
	s_nop 11
	v_exp_f32_e32 v32, v32
	v_exp_f32_e32 v33, v33
	v_exp_f32_e32 v34, v34
	v_exp_f32_e32 v35, v35
	v_exp_f32_e32 v36, v36
	v_exp_f32_e32 v37, v37
	v_exp_f32_e32 v38, v38
	v_exp_f32_e32 v39, v39
	v_exp_f32_e32 v40, v40
	v_exp_f32_e32 v41, v41
	v_exp_f32_e32 v42, v42
	v_exp_f32_e32 v43, v43
	v_exp_f32_e32 v44, v44
	v_exp_f32_e32 v45, v45
	v_exp_f32_e32 v46, v46
	v_exp_f32_e32 v47, v47
	v_cvt_pk_bf16_f32 v64, v32, v33
	v_cvt_pk_bf16_f32 v65, v34, v35
	v_cvt_pk_bf16_f32 v66, v36, v37
	v_cvt_pk_bf16_f32 v67, v38, v39
	v_cvt_pk_bf16_f32 v68, v40, v41
	v_cvt_pk_bf16_f32 v69, v42, v43
	v_cvt_pk_bf16_f32 v70, v44, v45
	v_cvt_pk_bf16_f32 v71, v46, v47
	v_pk_add_f32 v[232:233], v[232:233], v[32:33]
	v_pk_add_f32 v[232:233], v[232:233], v[34:35]
	v_pk_add_f32 v[232:233], v[232:233], v[36:37]
	v_pk_add_f32 v[232:233], v[232:233], v[38:39]
	v_pk_add_f32 v[232:233], v[232:233], v[40:41]
	v_pk_add_f32 v[232:233], v[232:233], v[42:43]
	v_pk_add_f32 v[232:233], v[232:233], v[44:45]
	v_pk_add_f32 v[232:233], v[232:233], v[46:47]
	s_waitcnt lgkmcnt(0)
	v_mfma_f32_32x32x16_bf16 v[0:15], v[64:67], v[72:75], v[0:15]
	v_mfma_f32_32x32x16_bf16 v[16:31], v[64:67], v[76:79], v[16:31]
	v_mfma_f32_32x32x16_bf16 v[0:15], v[68:71], v[220:223], v[0:15]
	v_mfma_f32_32x32x16_bf16 v[16:31], v[68:71], v[224:227], v[16:31]
	global_load_dwordx4 v[116:119], v83, s[86:87]
	global_load_dwordx4 v[120:123], v83, s[86:87] offset:32
	global_load_dwordx4 v[124:127], v83, s[86:87] offset:64
	global_load_dwordx4 v[128:131], v83, s[86:87] offset:96
	global_load_dwordx4 v[132:135], v101, s[86:87] offset:768
	global_load_dwordx4 v[136:139], v150, s[86:87] offset:768
	global_load_dwordx4 v[140:143], v101, s[86:87] offset:832
	global_load_dwordx4 v[144:147], v150, s[86:87] offset:832
	s_waitcnt vmcnt(16)
	ds_write_b128 v112, v[172:175]
	ds_write_b128 v112, v[176:179] offset:1024
	ds_write_b128 v112, v[180:183] offset:2048
	ds_write_b128 v112, v[184:187] offset:3072
	ds_read2_b32 v[32:33], v115 offset0:160 offset1:161
	ds_read2_b32 v[34:35], v115 offset0:162 offset1:163
	ds_read2_b32 v[36:37], v115 offset0:168 offset1:169
	ds_read2_b32 v[38:39], v115 offset0:170 offset1:171
	ds_read2_b32 v[40:41], v115 offset0:176 offset1:177
	ds_read2_b32 v[42:43], v115 offset0:178 offset1:179
	ds_read2_b32 v[44:45], v115 offset0:184 offset1:185
	ds_read2_b32 v[46:47], v115 offset0:186 offset1:187
	s_waitcnt lgkmcnt(0)
	v_mfma_f32_32x32x16_bf16 v[32:47], v[156:159], v[48:51], v[32:47]
	ds_read_b64_tr_b16 v[72:73], v231
	ds_read_b64_tr_b16 v[74:75], v231 offset:512
	ds_read_b64_tr_b16 v[76:77], v231 offset:2048
	ds_read_b64_tr_b16 v[78:79], v231 offset:2560
	ds_read_b64_tr_b16 v[220:221], v231 offset:1024
	ds_read_b64_tr_b16 v[222:223], v231 offset:1536
	ds_read_b64_tr_b16 v[224:225], v231 offset:3072
	ds_read_b64_tr_b16 v[226:227], v231 offset:3584
	v_mfma_f32_32x32x16_bf16 v[32:47], v[160:163], v[52:55], v[32:47]
	v_mfma_f32_32x32x16_bf16 v[32:47], v[164:167], v[56:59], v[32:47]
	v_mfma_f32_32x32x16_bf16 v[32:47], v[168:171], v[60:63], v[32:47]
	s_nop 11
	v_exp_f32_e32 v32, v32
	v_exp_f32_e32 v33, v33
	v_exp_f32_e32 v34, v34
	v_exp_f32_e32 v35, v35
	v_exp_f32_e32 v36, v36
	v_exp_f32_e32 v37, v37
	v_exp_f32_e32 v38, v38
	v_exp_f32_e32 v39, v39
	v_exp_f32_e32 v40, v40
	v_exp_f32_e32 v41, v41
	v_exp_f32_e32 v42, v42
	v_exp_f32_e32 v43, v43
	v_exp_f32_e32 v44, v44
	v_exp_f32_e32 v45, v45
	v_exp_f32_e32 v46, v46
	v_exp_f32_e32 v47, v47
	v_cvt_pk_bf16_f32 v64, v32, v33
	v_cvt_pk_bf16_f32 v65, v34, v35
	v_cvt_pk_bf16_f32 v66, v36, v37
	v_cvt_pk_bf16_f32 v67, v38, v39
	v_cvt_pk_bf16_f32 v68, v40, v41
	v_cvt_pk_bf16_f32 v69, v42, v43
	v_cvt_pk_bf16_f32 v70, v44, v45
	v_cvt_pk_bf16_f32 v71, v46, v47
	v_pk_add_f32 v[232:233], v[232:233], v[32:33]
	v_pk_add_f32 v[232:233], v[232:233], v[34:35]
	v_pk_add_f32 v[232:233], v[232:233], v[36:37]
	v_pk_add_f32 v[232:233], v[232:233], v[38:39]
	v_pk_add_f32 v[232:233], v[232:233], v[40:41]
	v_pk_add_f32 v[232:233], v[232:233], v[42:43]
	v_pk_add_f32 v[232:233], v[232:233], v[44:45]
	v_pk_add_f32 v[232:233], v[232:233], v[46:47]
	s_waitcnt lgkmcnt(0)
	v_mfma_f32_32x32x16_bf16 v[0:15], v[64:67], v[72:75], v[0:15]
	v_mfma_f32_32x32x16_bf16 v[16:31], v[64:67], v[76:79], v[16:31]
	v_mfma_f32_32x32x16_bf16 v[0:15], v[68:71], v[220:223], v[0:15]
	v_mfma_f32_32x32x16_bf16 v[16:31], v[68:71], v[224:227], v[16:31]
	global_load_dwordx4 v[156:159], v99, s[88:89]
	global_load_dwordx4 v[160:163], v99, s[88:89] offset:32
	global_load_dwordx4 v[164:167], v99, s[88:89] offset:64
	global_load_dwordx4 v[168:171], v99, s[88:89] offset:96
	global_load_dwordx4 v[172:175], v148, s[88:89] offset:768
	global_load_dwordx4 v[176:179], v151, s[88:89] offset:768
	global_load_dwordx4 v[180:183], v148, s[88:89] offset:832
	global_load_dwordx4 v[184:187], v151, s[88:89] offset:832
	s_add_u32 s88, s88, 0x300000
	s_addc_u32 s89, s89, 0
	s_waitcnt vmcnt(16)
	ds_write_b128 v112, v[204:207]
	ds_write_b128 v112, v[208:211] offset:1024
	ds_write_b128 v112, v[212:215] offset:2048
	ds_write_b128 v112, v[216:219] offset:3072
	ds_read2_b32 v[32:33], v115 offset0:192 offset1:193
	ds_read2_b32 v[34:35], v115 offset0:194 offset1:195
	ds_read2_b32 v[36:37], v115 offset0:200 offset1:201
	ds_read2_b32 v[38:39], v115 offset0:202 offset1:203
	ds_read2_b32 v[40:41], v115 offset0:208 offset1:209
	ds_read2_b32 v[42:43], v115 offset0:210 offset1:211
	ds_read2_b32 v[44:45], v115 offset0:216 offset1:217
	ds_read2_b32 v[46:47], v115 offset0:218 offset1:219
	s_waitcnt lgkmcnt(0)
	v_mfma_f32_32x32x16_bf16 v[32:47], v[188:191], v[48:51], v[32:47]
	ds_read_b64_tr_b16 v[72:73], v231
	ds_read_b64_tr_b16 v[74:75], v231 offset:512
	ds_read_b64_tr_b16 v[76:77], v231 offset:2048
	ds_read_b64_tr_b16 v[78:79], v231 offset:2560
	ds_read_b64_tr_b16 v[220:221], v231 offset:1024
	ds_read_b64_tr_b16 v[222:223], v231 offset:1536
	ds_read_b64_tr_b16 v[224:225], v231 offset:3072
	ds_read_b64_tr_b16 v[226:227], v231 offset:3584
	v_mfma_f32_32x32x16_bf16 v[32:47], v[192:195], v[52:55], v[32:47]
	v_mfma_f32_32x32x16_bf16 v[32:47], v[196:199], v[56:59], v[32:47]
	v_mfma_f32_32x32x16_bf16 v[32:47], v[200:203], v[60:63], v[32:47]
	s_nop 11
	v_exp_f32_e32 v32, v32
	v_exp_f32_e32 v33, v33
	v_exp_f32_e32 v34, v34
	v_exp_f32_e32 v35, v35
	v_exp_f32_e32 v36, v36
	v_exp_f32_e32 v37, v37
	v_exp_f32_e32 v38, v38
	v_exp_f32_e32 v39, v39
	v_exp_f32_e32 v40, v40
	v_exp_f32_e32 v41, v41
	v_exp_f32_e32 v42, v42
	v_exp_f32_e32 v43, v43
	v_exp_f32_e32 v44, v44
	v_exp_f32_e32 v45, v45
	v_exp_f32_e32 v46, v46
	v_exp_f32_e32 v47, v47
	v_cvt_pk_bf16_f32 v64, v32, v33
	v_cvt_pk_bf16_f32 v65, v34, v35
	v_cvt_pk_bf16_f32 v66, v36, v37
	v_cvt_pk_bf16_f32 v67, v38, v39
	v_cvt_pk_bf16_f32 v68, v40, v41
	v_cvt_pk_bf16_f32 v69, v42, v43
	v_cvt_pk_bf16_f32 v70, v44, v45
	v_cvt_pk_bf16_f32 v71, v46, v47
	v_pk_add_f32 v[232:233], v[232:233], v[32:33]
	v_pk_add_f32 v[232:233], v[232:233], v[34:35]
	v_pk_add_f32 v[232:233], v[232:233], v[36:37]
	v_pk_add_f32 v[232:233], v[232:233], v[38:39]
	v_pk_add_f32 v[232:233], v[232:233], v[40:41]
	v_pk_add_f32 v[232:233], v[232:233], v[42:43]
	v_pk_add_f32 v[232:233], v[232:233], v[44:45]
	v_pk_add_f32 v[232:233], v[232:233], v[46:47]
	s_waitcnt lgkmcnt(0)
	v_mfma_f32_32x32x16_bf16 v[0:15], v[64:67], v[72:75], v[0:15]
	v_mfma_f32_32x32x16_bf16 v[16:31], v[64:67], v[76:79], v[16:31]
	v_mfma_f32_32x32x16_bf16 v[0:15], v[68:71], v[220:223], v[0:15]
	v_mfma_f32_32x32x16_bf16 v[16:31], v[68:71], v[224:227], v[16:31]
	global_load_dwordx4 v[188:191], v99, s[88:89]
	global_load_dwordx4 v[192:195], v99, s[88:89] offset:32
	global_load_dwordx4 v[196:199], v99, s[88:89] offset:64
	global_load_dwordx4 v[200:203], v99, s[88:89] offset:96
	global_load_dwordx4 v[204:207], v148, s[88:89] offset:768
	global_load_dwordx4 v[208:211], v151, s[88:89] offset:768
	global_load_dwordx4 v[212:215], v148, s[88:89] offset:832
	global_load_dwordx4 v[216:219], v151, s[88:89] offset:832
	s_add_u32 s88, s88, 0x300000
	s_addc_u32 s89, s89, 0
	s_waitcnt vmcnt(16)
	ds_write_b128 v112, v[132:135]
	ds_write_b128 v112, v[136:139] offset:1024
	ds_write_b128 v112, v[140:143] offset:2048
	ds_write_b128 v112, v[144:147] offset:3072
	ds_read2_b32 v[32:33], v115 offset0:224 offset1:225
	ds_read2_b32 v[34:35], v115 offset0:226 offset1:227
	ds_read2_b32 v[36:37], v115 offset0:232 offset1:233
	ds_read2_b32 v[38:39], v115 offset0:234 offset1:235
	ds_read2_b32 v[40:41], v115 offset0:240 offset1:241
	ds_read2_b32 v[42:43], v115 offset0:242 offset1:243
	ds_read2_b32 v[44:45], v115 offset0:248 offset1:249
	ds_read2_b32 v[46:47], v115 offset0:250 offset1:251
	s_waitcnt lgkmcnt(0)
	v_mfma_f32_32x32x16_bf16 v[32:47], v[116:119], v[48:51], v[32:47]
	ds_read_b64_tr_b16 v[72:73], v231
	ds_read_b64_tr_b16 v[74:75], v231 offset:512
	ds_read_b64_tr_b16 v[76:77], v231 offset:2048
	ds_read_b64_tr_b16 v[78:79], v231 offset:2560
	ds_read_b64_tr_b16 v[220:221], v231 offset:1024
	ds_read_b64_tr_b16 v[222:223], v231 offset:1536
	ds_read_b64_tr_b16 v[224:225], v231 offset:3072
	ds_read_b64_tr_b16 v[226:227], v231 offset:3584
	v_mfma_f32_32x32x16_bf16 v[32:47], v[120:123], v[52:55], v[32:47]
	v_mfma_f32_32x32x16_bf16 v[32:47], v[124:127], v[56:59], v[32:47]
	v_mfma_f32_32x32x16_bf16 v[32:47], v[128:131], v[60:63], v[32:47]
	s_nop 11
	v_exp_f32_e32 v32, v32
	v_exp_f32_e32 v33, v33
	v_exp_f32_e32 v34, v34
	v_exp_f32_e32 v35, v35
	v_exp_f32_e32 v36, v36
	v_exp_f32_e32 v37, v37
	v_exp_f32_e32 v38, v38
	v_exp_f32_e32 v39, v39
	v_exp_f32_e32 v40, v40
	v_exp_f32_e32 v41, v41
	v_exp_f32_e32 v42, v42
	v_exp_f32_e32 v43, v43
	v_exp_f32_e32 v44, v44
	v_exp_f32_e32 v45, v45
	v_exp_f32_e32 v46, v46
	v_exp_f32_e32 v47, v47
	v_cvt_pk_bf16_f32 v64, v32, v33
	v_cvt_pk_bf16_f32 v65, v34, v35
	v_cvt_pk_bf16_f32 v66, v36, v37
	v_cvt_pk_bf16_f32 v67, v38, v39
	v_cvt_pk_bf16_f32 v68, v40, v41
	v_cvt_pk_bf16_f32 v69, v42, v43
	v_cvt_pk_bf16_f32 v70, v44, v45
	v_cvt_pk_bf16_f32 v71, v46, v47
	v_pk_add_f32 v[232:233], v[232:233], v[32:33]
	v_pk_add_f32 v[232:233], v[232:233], v[34:35]
	v_pk_add_f32 v[232:233], v[232:233], v[36:37]
	v_pk_add_f32 v[232:233], v[232:233], v[38:39]
	v_pk_add_f32 v[232:233], v[232:233], v[40:41]
	v_pk_add_f32 v[232:233], v[232:233], v[42:43]
	v_pk_add_f32 v[232:233], v[232:233], v[44:45]
	v_pk_add_f32 v[232:233], v[232:233], v[46:47]
	s_waitcnt lgkmcnt(0)
	v_mfma_f32_32x32x16_bf16 v[0:15], v[64:67], v[72:75], v[0:15]
	v_mfma_f32_32x32x16_bf16 v[16:31], v[64:67], v[76:79], v[16:31]
	v_mfma_f32_32x32x16_bf16 v[0:15], v[68:71], v[220:223], v[0:15]
	v_mfma_f32_32x32x16_bf16 v[16:31], v[68:71], v[224:227], v[16:31]
	global_load_dwordx4 v[116:119], v99, s[88:89]
	global_load_dwordx4 v[120:123], v99, s[88:89] offset:32
	global_load_dwordx4 v[124:127], v99, s[88:89] offset:64
	global_load_dwordx4 v[128:131], v99, s[88:89] offset:96
	global_load_dwordx4 v[132:135], v148, s[88:89] offset:768
	global_load_dwordx4 v[136:139], v151, s[88:89] offset:768
	global_load_dwordx4 v[140:143], v148, s[88:89] offset:832
	global_load_dwordx4 v[144:147], v151, s[88:89] offset:832
	s_add_u32 s88, s88, 0x300000
	s_addc_u32 s89, s89, 0
	s_waitcnt vmcnt(16)
	ds_write_b128 v112, v[172:175]
	ds_write_b128 v112, v[176:179] offset:1024
	ds_write_b128 v112, v[180:183] offset:2048
	ds_write_b128 v112, v[184:187] offset:3072
	v_mov_b32_e32 v115, v230
	ds_read2_b32 v[32:33], v115 offset0:0 offset1:1
	ds_read2_b32 v[34:35], v115 offset0:2 offset1:3
	ds_read2_b32 v[36:37], v115 offset0:8 offset1:9
	ds_read2_b32 v[38:39], v115 offset0:10 offset1:11
	ds_read2_b32 v[40:41], v115 offset0:16 offset1:17
	ds_read2_b32 v[42:43], v115 offset0:18 offset1:19
	ds_read2_b32 v[44:45], v115 offset0:24 offset1:25
	ds_read2_b32 v[46:47], v115 offset0:26 offset1:27
	s_waitcnt lgkmcnt(0)
	v_mfma_f32_32x32x16_bf16 v[32:47], v[156:159], v[48:51], v[32:47]
	ds_read_b64_tr_b16 v[72:73], v231
	ds_read_b64_tr_b16 v[74:75], v231 offset:512
	ds_read_b64_tr_b16 v[76:77], v231 offset:2048
	ds_read_b64_tr_b16 v[78:79], v231 offset:2560
	ds_read_b64_tr_b16 v[220:221], v231 offset:1024
	ds_read_b64_tr_b16 v[222:223], v231 offset:1536
	ds_read_b64_tr_b16 v[224:225], v231 offset:3072
	ds_read_b64_tr_b16 v[226:227], v231 offset:3584
	v_mfma_f32_32x32x16_bf16 v[32:47], v[160:163], v[52:55], v[32:47]
	v_mfma_f32_32x32x16_bf16 v[32:47], v[164:167], v[56:59], v[32:47]
	v_mfma_f32_32x32x16_bf16 v[32:47], v[168:171], v[60:63], v[32:47]
	s_nop 11
	v_exp_f32_e32 v32, v32
	v_exp_f32_e32 v33, v33
	v_exp_f32_e32 v34, v34
	v_exp_f32_e32 v35, v35
	v_exp_f32_e32 v36, v36
	v_exp_f32_e32 v37, v37
	v_exp_f32_e32 v38, v38
	v_exp_f32_e32 v39, v39
	v_exp_f32_e32 v40, v40
	v_exp_f32_e32 v41, v41
	v_exp_f32_e32 v42, v42
	v_exp_f32_e32 v43, v43
	v_exp_f32_e32 v44, v44
	v_exp_f32_e32 v45, v45
	v_exp_f32_e32 v46, v46
	v_exp_f32_e32 v47, v47
	v_cvt_pk_bf16_f32 v64, v32, v33
	v_cvt_pk_bf16_f32 v65, v34, v35
	v_cvt_pk_bf16_f32 v66, v36, v37
	v_cvt_pk_bf16_f32 v67, v38, v39
	v_cvt_pk_bf16_f32 v68, v40, v41
	v_cvt_pk_bf16_f32 v69, v42, v43
	v_cvt_pk_bf16_f32 v70, v44, v45
	v_cvt_pk_bf16_f32 v71, v46, v47
	v_pk_add_f32 v[232:233], v[232:233], v[32:33]
	v_pk_add_f32 v[232:233], v[232:233], v[34:35]
	v_pk_add_f32 v[232:233], v[232:233], v[36:37]
	v_pk_add_f32 v[232:233], v[232:233], v[38:39]
	v_pk_add_f32 v[232:233], v[232:233], v[40:41]
	v_pk_add_f32 v[232:233], v[232:233], v[42:43]
	v_pk_add_f32 v[232:233], v[232:233], v[44:45]
	v_pk_add_f32 v[232:233], v[232:233], v[46:47]
	s_waitcnt lgkmcnt(0)
	v_mfma_f32_32x32x16_bf16 v[0:15], v[64:67], v[72:75], v[0:15]
	v_mfma_f32_32x32x16_bf16 v[16:31], v[64:67], v[76:79], v[16:31]
	v_mfma_f32_32x32x16_bf16 v[0:15], v[68:71], v[220:223], v[0:15]
	v_mfma_f32_32x32x16_bf16 v[16:31], v[68:71], v[224:227], v[16:31]
	global_load_dwordx4 v[156:159], v99, s[88:89]
	global_load_dwordx4 v[160:163], v99, s[88:89] offset:32
	global_load_dwordx4 v[164:167], v99, s[88:89] offset:64
	global_load_dwordx4 v[168:171], v99, s[88:89] offset:96
	global_load_dwordx4 v[172:175], v148, s[88:89] offset:768
	global_load_dwordx4 v[176:179], v151, s[88:89] offset:768
	global_load_dwordx4 v[180:183], v148, s[88:89] offset:832
	global_load_dwordx4 v[184:187], v151, s[88:89] offset:832
	s_add_u32 s88, s88, 0x300000
	s_addc_u32 s89, s89, 0
	s_waitcnt vmcnt(16)
	ds_write_b128 v112, v[204:207]
	ds_write_b128 v112, v[208:211] offset:1024
	ds_write_b128 v112, v[212:215] offset:2048
	ds_write_b128 v112, v[216:219] offset:3072
	ds_read2_b32 v[32:33], v115 offset0:32 offset1:33
	ds_read2_b32 v[34:35], v115 offset0:34 offset1:35
	ds_read2_b32 v[36:37], v115 offset0:40 offset1:41
	ds_read2_b32 v[38:39], v115 offset0:42 offset1:43
	ds_read2_b32 v[40:41], v115 offset0:48 offset1:49
	ds_read2_b32 v[42:43], v115 offset0:50 offset1:51
	ds_read2_b32 v[44:45], v115 offset0:56 offset1:57
	ds_read2_b32 v[46:47], v115 offset0:58 offset1:59
	s_waitcnt lgkmcnt(0)
	v_mfma_f32_32x32x16_bf16 v[32:47], v[188:191], v[48:51], v[32:47]
	ds_read_b64_tr_b16 v[72:73], v231
	ds_read_b64_tr_b16 v[74:75], v231 offset:512
	ds_read_b64_tr_b16 v[76:77], v231 offset:2048
	ds_read_b64_tr_b16 v[78:79], v231 offset:2560
	ds_read_b64_tr_b16 v[220:221], v231 offset:1024
	ds_read_b64_tr_b16 v[222:223], v231 offset:1536
	ds_read_b64_tr_b16 v[224:225], v231 offset:3072
	ds_read_b64_tr_b16 v[226:227], v231 offset:3584
	v_mfma_f32_32x32x16_bf16 v[32:47], v[192:195], v[52:55], v[32:47]
	v_mfma_f32_32x32x16_bf16 v[32:47], v[196:199], v[56:59], v[32:47]
	v_mfma_f32_32x32x16_bf16 v[32:47], v[200:203], v[60:63], v[32:47]
	s_nop 11
	v_exp_f32_e32 v32, v32
	v_exp_f32_e32 v33, v33
	v_exp_f32_e32 v34, v34
	v_exp_f32_e32 v35, v35
	v_exp_f32_e32 v36, v36
	v_exp_f32_e32 v37, v37
	v_exp_f32_e32 v38, v38
	v_exp_f32_e32 v39, v39
	v_exp_f32_e32 v40, v40
	v_exp_f32_e32 v41, v41
	v_exp_f32_e32 v42, v42
	v_exp_f32_e32 v43, v43
	v_exp_f32_e32 v44, v44
	v_exp_f32_e32 v45, v45
	v_exp_f32_e32 v46, v46
	v_exp_f32_e32 v47, v47
	v_cvt_pk_bf16_f32 v64, v32, v33
	v_cvt_pk_bf16_f32 v65, v34, v35
	v_cvt_pk_bf16_f32 v66, v36, v37
	v_cvt_pk_bf16_f32 v67, v38, v39
	v_cvt_pk_bf16_f32 v68, v40, v41
	v_cvt_pk_bf16_f32 v69, v42, v43
	v_cvt_pk_bf16_f32 v70, v44, v45
	v_cvt_pk_bf16_f32 v71, v46, v47
	v_pk_add_f32 v[232:233], v[232:233], v[32:33]
	v_pk_add_f32 v[232:233], v[232:233], v[34:35]
	v_pk_add_f32 v[232:233], v[232:233], v[36:37]
	v_pk_add_f32 v[232:233], v[232:233], v[38:39]
	v_pk_add_f32 v[232:233], v[232:233], v[40:41]
	v_pk_add_f32 v[232:233], v[232:233], v[42:43]
	v_pk_add_f32 v[232:233], v[232:233], v[44:45]
	v_pk_add_f32 v[232:233], v[232:233], v[46:47]
	s_waitcnt lgkmcnt(0)
	v_mfma_f32_32x32x16_bf16 v[0:15], v[64:67], v[72:75], v[0:15]
	v_mfma_f32_32x32x16_bf16 v[16:31], v[64:67], v[76:79], v[16:31]
	v_mfma_f32_32x32x16_bf16 v[0:15], v[68:71], v[220:223], v[0:15]
	v_mfma_f32_32x32x16_bf16 v[16:31], v[68:71], v[224:227], v[16:31]
	global_load_dwordx4 v[188:191], v99, s[88:89]
	global_load_dwordx4 v[192:195], v99, s[88:89] offset:32
	global_load_dwordx4 v[196:199], v99, s[88:89] offset:64
	global_load_dwordx4 v[200:203], v99, s[88:89] offset:96
	global_load_dwordx4 v[204:207], v148, s[88:89] offset:768
	global_load_dwordx4 v[208:211], v151, s[88:89] offset:768
	global_load_dwordx4 v[212:215], v148, s[88:89] offset:832
	global_load_dwordx4 v[216:219], v151, s[88:89] offset:832
	s_waitcnt vmcnt(16)
	ds_write_b128 v112, v[132:135]
	ds_write_b128 v112, v[136:139] offset:1024
	ds_write_b128 v112, v[140:143] offset:2048
	ds_write_b128 v112, v[144:147] offset:3072
	ds_read2_b32 v[32:33], v115 offset0:64 offset1:65
	ds_read2_b32 v[34:35], v115 offset0:66 offset1:67
	ds_read2_b32 v[36:37], v115 offset0:72 offset1:73
	ds_read2_b32 v[38:39], v115 offset0:74 offset1:75
	ds_read2_b32 v[40:41], v115 offset0:80 offset1:81
	ds_read2_b32 v[42:43], v115 offset0:82 offset1:83
	ds_read2_b32 v[44:45], v115 offset0:88 offset1:89
	ds_read2_b32 v[46:47], v115 offset0:90 offset1:91
	s_waitcnt lgkmcnt(0)
	v_mfma_f32_32x32x16_bf16 v[32:47], v[116:119], v[48:51], v[32:47]
	ds_read_b64_tr_b16 v[72:73], v231
	ds_read_b64_tr_b16 v[74:75], v231 offset:512
	ds_read_b64_tr_b16 v[76:77], v231 offset:2048
	ds_read_b64_tr_b16 v[78:79], v231 offset:2560
	ds_read_b64_tr_b16 v[220:221], v231 offset:1024
	ds_read_b64_tr_b16 v[222:223], v231 offset:1536
	ds_read_b64_tr_b16 v[224:225], v231 offset:3072
	ds_read_b64_tr_b16 v[226:227], v231 offset:3584
	v_mfma_f32_32x32x16_bf16 v[32:47], v[120:123], v[52:55], v[32:47]
	v_mfma_f32_32x32x16_bf16 v[32:47], v[124:127], v[56:59], v[32:47]
	v_mfma_f32_32x32x16_bf16 v[32:47], v[128:131], v[60:63], v[32:47]
	s_nop 11
	v_exp_f32_e32 v32, v32
	v_exp_f32_e32 v33, v33
	v_exp_f32_e32 v34, v34
	v_exp_f32_e32 v35, v35
	v_exp_f32_e32 v36, v36
	v_exp_f32_e32 v37, v37
	v_exp_f32_e32 v38, v38
	v_exp_f32_e32 v39, v39
	v_exp_f32_e32 v40, v40
	v_exp_f32_e32 v41, v41
	v_exp_f32_e32 v42, v42
	v_exp_f32_e32 v43, v43
	v_exp_f32_e32 v44, v44
	v_exp_f32_e32 v45, v45
	v_exp_f32_e32 v46, v46
	v_exp_f32_e32 v47, v47
	v_cvt_pk_bf16_f32 v64, v32, v33
	v_cvt_pk_bf16_f32 v65, v34, v35
	v_cvt_pk_bf16_f32 v66, v36, v37
	v_cvt_pk_bf16_f32 v67, v38, v39
	v_cvt_pk_bf16_f32 v68, v40, v41
	v_cvt_pk_bf16_f32 v69, v42, v43
	v_cvt_pk_bf16_f32 v70, v44, v45
	v_cvt_pk_bf16_f32 v71, v46, v47
	v_pk_add_f32 v[232:233], v[232:233], v[32:33]
	v_pk_add_f32 v[232:233], v[232:233], v[34:35]
	v_pk_add_f32 v[232:233], v[232:233], v[36:37]
	v_pk_add_f32 v[232:233], v[232:233], v[38:39]
	v_pk_add_f32 v[232:233], v[232:233], v[40:41]
	v_pk_add_f32 v[232:233], v[232:233], v[42:43]
	v_pk_add_f32 v[232:233], v[232:233], v[44:45]
	v_pk_add_f32 v[232:233], v[232:233], v[46:47]
	s_waitcnt lgkmcnt(0)
	v_mfma_f32_32x32x16_bf16 v[0:15], v[64:67], v[72:75], v[0:15]
	v_mfma_f32_32x32x16_bf16 v[16:31], v[64:67], v[76:79], v[16:31]
	v_mfma_f32_32x32x16_bf16 v[0:15], v[68:71], v[220:223], v[0:15]
	v_mfma_f32_32x32x16_bf16 v[16:31], v[68:71], v[224:227], v[16:31]
	s_waitcnt vmcnt(8)
	ds_write_b128 v112, v[172:175]
	ds_write_b128 v112, v[176:179] offset:1024
	ds_write_b128 v112, v[180:183] offset:2048
	ds_write_b128 v112, v[184:187] offset:3072
	ds_read2_b32 v[32:33], v115 offset0:96 offset1:97
	ds_read2_b32 v[34:35], v115 offset0:98 offset1:99
	ds_read2_b32 v[36:37], v115 offset0:104 offset1:105
	ds_read2_b32 v[38:39], v115 offset0:106 offset1:107
	ds_read2_b32 v[40:41], v115 offset0:112 offset1:113
	ds_read2_b32 v[42:43], v115 offset0:114 offset1:115
	ds_read2_b32 v[44:45], v115 offset0:120 offset1:121
	ds_read2_b32 v[46:47], v115 offset0:122 offset1:123
	s_waitcnt lgkmcnt(0)
; #define LAS __attribute__((address_space(3)))
; __device__ __forceinline__ int crow(int r, int hi) { return (r & 3) + 8 * (r >> 2) + 4 * hi; }
; __device__ __forceinline__ void dil_unit(LAS unsigned char* lds, bf16_t* proj, int seq, int hd, int T0, int rho) {
;     ...
;     if (bound) DIL_LOOP(true); else DIL_LOOP(false);
;     ...
;     LAS bf16_t* stg = (LAS bf16_t*)wbuf;
;     l += __shfl_xor(l, 32);
; #pragma unroll
;     for (int rr = 0; rr < 16; ++rr) {
;         const int j = crow(rr, hi);
	v_mfma_f32_32x32x16_bf16 v[32:47], v[156:159], v[48:51], v[32:47]
	ds_read_b64_tr_b16 v[72:73], v231
	ds_read_b64_tr_b16 v[74:75], v231 offset:512
	ds_read_b64_tr_b16 v[76:77], v231 offset:2048
	ds_read_b64_tr_b16 v[78:79], v231 offset:2560
	ds_read_b64_tr_b16 v[220:221], v231 offset:1024
	ds_read_b64_tr_b16 v[222:223], v231 offset:1536
	ds_read_b64_tr_b16 v[224:225], v231 offset:3072
	ds_read_b64_tr_b16 v[226:227], v231 offset:3584
	v_mfma_f32_32x32x16_bf16 v[32:47], v[160:163], v[52:55], v[32:47]
	v_mfma_f32_32x32x16_bf16 v[32:47], v[164:167], v[56:59], v[32:47]
	v_mfma_f32_32x32x16_bf16 v[32:47], v[168:171], v[60:63], v[32:47]
	s_nop 11
	v_exp_f32_e32 v32, v32
	v_exp_f32_e32 v33, v33
	v_exp_f32_e32 v34, v34
	v_exp_f32_e32 v35, v35
	v_exp_f32_e32 v36, v36
	v_exp_f32_e32 v37, v37
	v_exp_f32_e32 v38, v38
	v_exp_f32_e32 v39, v39
	v_exp_f32_e32 v40, v40
	v_exp_f32_e32 v41, v41
	v_exp_f32_e32 v42, v42
	v_exp_f32_e32 v43, v43
	v_exp_f32_e32 v44, v44
	v_exp_f32_e32 v45, v45
	v_exp_f32_e32 v46, v46
	v_exp_f32_e32 v47, v47
	v_cvt_pk_bf16_f32 v64, v32, v33
	v_cvt_pk_bf16_f32 v65, v34, v35
	v_cvt_pk_bf16_f32 v66, v36, v37
	v_cvt_pk_bf16_f32 v67, v38, v39
	v_cvt_pk_bf16_f32 v68, v40, v41
	v_cvt_pk_bf16_f32 v69, v42, v43
	v_cvt_pk_bf16_f32 v70, v44, v45
	v_cvt_pk_bf16_f32 v71, v46, v47
	v_pk_add_f32 v[232:233], v[232:233], v[32:33]
	v_pk_add_f32 v[232:233], v[232:233], v[34:35]
	v_pk_add_f32 v[232:233], v[232:233], v[36:37]
	v_pk_add_f32 v[232:233], v[232:233], v[38:39]
	v_pk_add_f32 v[232:233], v[232:233], v[40:41]
	v_pk_add_f32 v[232:233], v[232:233], v[42:43]
	v_pk_add_f32 v[232:233], v[232:233], v[44:45]
	v_pk_add_f32 v[232:233], v[232:233], v[46:47]
	s_waitcnt lgkmcnt(0)
	v_mfma_f32_32x32x16_bf16 v[0:15], v[64:67], v[72:75], v[0:15]
	v_mfma_f32_32x32x16_bf16 v[16:31], v[64:67], v[76:79], v[16:31]
	v_mfma_f32_32x32x16_bf16 v[0:15], v[68:71], v[220:223], v[0:15]
	v_mfma_f32_32x32x16_bf16 v[16:31], v[68:71], v[224:227], v[16:31]
	s_waitcnt vmcnt(0)
	ds_write_b128 v112, v[204:207]
	ds_write_b128 v112, v[208:211] offset:1024
	ds_write_b128 v112, v[212:215] offset:2048
	ds_write_b128 v112, v[216:219] offset:3072
	ds_read2_b32 v[32:33], v115 offset0:128 offset1:129
	ds_read2_b32 v[34:35], v115 offset0:130 offset1:131
	ds_read2_b32 v[36:37], v115 offset0:136 offset1:137
	ds_read2_b32 v[38:39], v115 offset0:138 offset1:139
	ds_read2_b32 v[40:41], v115 offset0:144 offset1:145
	ds_read2_b32 v[42:43], v115 offset0:146 offset1:147
	ds_read2_b32 v[44:45], v115 offset0:152 offset1:153
	ds_read2_b32 v[46:47], v115 offset0:154 offset1:155
	s_waitcnt lgkmcnt(0)
	v_mfma_f32_32x32x16_bf16 v[32:47], v[188:191], v[48:51], v[32:47]
	ds_read_b64_tr_b16 v[72:73], v231
	ds_read_b64_tr_b16 v[74:75], v231 offset:512
	ds_read_b64_tr_b16 v[76:77], v231 offset:2048
	ds_read_b64_tr_b16 v[78:79], v231 offset:2560
	ds_read_b64_tr_b16 v[220:221], v231 offset:1024
	ds_read_b64_tr_b16 v[222:223], v231 offset:1536
	ds_read_b64_tr_b16 v[224:225], v231 offset:3072
	ds_read_b64_tr_b16 v[226:227], v231 offset:3584
	v_mfma_f32_32x32x16_bf16 v[32:47], v[192:195], v[52:55], v[32:47]
	v_mfma_f32_32x32x16_bf16 v[32:47], v[196:199], v[56:59], v[32:47]
	v_mfma_f32_32x32x16_bf16 v[32:47], v[200:203], v[60:63], v[32:47]
	s_nop 11
	v_exp_f32_e32 v32, v32
	v_exp_f32_e32 v33, v33
	v_exp_f32_e32 v34, v34
	v_exp_f32_e32 v35, v35
	v_exp_f32_e32 v36, v36
	v_exp_f32_e32 v37, v37
	v_exp_f32_e32 v38, v38
	v_exp_f32_e32 v39, v39
	v_exp_f32_e32 v40, v40
	v_exp_f32_e32 v41, v41
	v_exp_f32_e32 v42, v42
	v_exp_f32_e32 v43, v43
	v_exp_f32_e32 v44, v44
	v_exp_f32_e32 v45, v45
	v_exp_f32_e32 v46, v46
	v_exp_f32_e32 v47, v47
	v_cvt_pk_bf16_f32 v64, v32, v33
	v_cvt_pk_bf16_f32 v65, v34, v35
	v_cvt_pk_bf16_f32 v66, v36, v37
	v_cvt_pk_bf16_f32 v67, v38, v39
	v_cvt_pk_bf16_f32 v68, v40, v41
	v_cvt_pk_bf16_f32 v69, v42, v43
	v_cvt_pk_bf16_f32 v70, v44, v45
	v_cvt_pk_bf16_f32 v71, v46, v47
	v_pk_add_f32 v[232:233], v[232:233], v[32:33]
	v_pk_add_f32 v[232:233], v[232:233], v[34:35]
	v_pk_add_f32 v[232:233], v[232:233], v[36:37]
	v_pk_add_f32 v[232:233], v[232:233], v[38:39]
	v_pk_add_f32 v[232:233], v[232:233], v[40:41]
	v_pk_add_f32 v[232:233], v[232:233], v[42:43]
	v_pk_add_f32 v[232:233], v[232:233], v[44:45]
	v_pk_add_f32 v[232:233], v[232:233], v[46:47]
	s_waitcnt lgkmcnt(0)
	v_mfma_f32_32x32x16_bf16 v[0:15], v[64:67], v[72:75], v[0:15]
	v_mfma_f32_32x32x16_bf16 v[16:31], v[64:67], v[76:79], v[16:31]
	v_mfma_f32_32x32x16_bf16 v[0:15], v[68:71], v[220:223], v[0:15]
	v_mfma_f32_32x32x16_bf16 v[16:31], v[68:71], v[224:227], v[16:31]
	v_add_f32_e32 v113, v232, v233
	v_or_b32_e32 v114, 1, v107
	v_or_b32_e32 v97, 2, v107
	v_or_b32_e32 v96, 3, v107
	v_or_b32_e32 v95, 8, v107
	v_or_b32_e32 v94, 9, v107
	v_or_b32_e32 v93, 10, v107
	v_or_b32_e32 v92, 11, v107
	v_or_b32_e32 v91, 16, v107
	v_or_b32_e32 v90, 17, v107
	v_or_b32_e32 v89, 18, v107
	v_or_b32_e32 v88, 19, v107
	v_or_b32_e32 v87, 24, v107
	v_or_b32_e32 v86, 25, v107
	v_or_b32_e32 v85, 26, v107
	v_or_b32_e32 v84, 27, v107
	s_nop 11
	s_branch .LBB0_1265

; __global__ void __launch_bounds__(512) mk_fwd(Args a) {
;     extern __shared__ __attribute__((aligned(16))) unsigned char lds_raw[];
	.amdhsa_kernel _Z6mk_fwd4Args
		.amdhsa_group_segment_fixed_size 0
		.amdhsa_private_segment_fixed_size 0
		.amdhsa_kernarg_size 456
		.amdhsa_user_sgpr_count 2
		.amdhsa_user_sgpr_dispatch_ptr 0
		.amdhsa_user_sgpr_queue_ptr 0
		.amdhsa_user_sgpr_kernarg_segment_ptr 1
		.amdhsa_user_sgpr_dispatch_id 0
		.amdhsa_user_sgpr_kernarg_preload_length 0
		.amdhsa_user_sgpr_kernarg_preload_offset 0
		.amdhsa_user_sgpr_private_segment_size 0
		.amdhsa_uses_dynamic_stack 0
		.amdhsa_enable_private_segment 0
		.amdhsa_system_sgpr_workgroup_id_x 1
		.amdhsa_system_sgpr_workgroup_id_y 0
		.amdhsa_system_sgpr_workgroup_id_z 0
		.amdhsa_system_sgpr_workgroup_info 0
		.amdhsa_system_vgpr_workitem_id 2
		.amdhsa_next_free_vgpr 235
		.amdhsa_next_free_sgpr 102
		.amdhsa_accum_offset 236
		.amdhsa_reserve_vcc 1
		.amdhsa_float_round_mode_32 0
		.amdhsa_float_round_mode_16_64 0
		.amdhsa_float_denorm_mode_32 3
		.amdhsa_float_denorm_mode_16_64 3
		.amdhsa_dx10_clamp 1
		.amdhsa_ieee_mode 1
		.amdhsa_fp16_overflow 0
		.amdhsa_tg_split 0
		.amdhsa_exception_fp_ieee_invalid_op 0
		.amdhsa_exception_fp_denorm_src 0
		.amdhsa_exception_fp_ieee_div_zero 0
		.amdhsa_exception_fp_ieee_overflow 0
		.amdhsa_exception_fp_ieee_underflow 0
		.amdhsa_exception_fp_ieee_inexact 0
		.amdhsa_exception_int_div_zero 0
	.end_amdhsa_kernel

; __global__ void __launch_bounds__(512) mk_fwd(Args a) {
;     extern __shared__ __attribute__((aligned(16))) unsigned char lds_raw[];
amdhsa.kernels:
  - .agpr_count:     0
    .args:
      - .offset:         0
        .size:           200
        .value_kind:     by_value
      - .offset:         200
        .size:           4
        .value_kind:     hidden_block_count_x
      - .offset:         204
        .size:           4
        .value_kind:     hidden_block_count_y
      - .offset:         208
        .size:           4
        .value_kind:     hidden_block_count_z
      - .offset:         212
        .size:           2
        .value_kind:     hidden_group_size_x
      - .offset:         214
        .size:           2
        .value_kind:     hidden_group_size_y
      - .offset:         216
        .size:           2
        .value_kind:     hidden_group_size_z
      - .offset:         218
        .size:           2
        .value_kind:     hidden_remainder_x
      - .offset:         220
        .size:           2
        .value_kind:     hidden_remainder_y
      - .offset:         222
        .size:           2
        .value_kind:     hidden_remainder_z
      - .offset:         240
        .size:           8
        .value_kind:     hidden_global_offset_x
      - .offset:         248
        .size:           8
        .value_kind:     hidden_global_offset_y
      - .offset:         256
        .size:           8
        .value_kind:     hidden_global_offset_z
      - .offset:         264
        .size:           2
        .value_kind:     hidden_grid_dims
      - .offset:         288
        .size:           8
        .value_kind:     hidden_multigrid_sync_arg
      - .offset:         320
        .size:           4
        .value_kind:     hidden_dynamic_lds_size
    .group_segment_fixed_size: 0
    .kernarg_segment_align: 8
    .kernarg_segment_size: 456
    .language:       OpenCL C
    .language_version:
      - 2
      - 0
    .max_flat_workgroup_size: 512
    .name:           _Z6mk_fwd4Args
    .private_segment_fixed_size: 0
    .sgpr_count:     108
    .sgpr_spill_count: 48
    .symbol:         _Z6mk_fwd4Args.kd
    .uniform_work_group_size: 1
    .uses_dynamic_stack: false
    .vgpr_count:     235
    .vgpr_spill_count: 0
    .wavefront_size: 64
